# main loops: removed back-to-back s_setprio 0/1 flip in the middle of each MMA section and the redundant lgkmcnt(0) after the barrier
# baseline (speedup 1.0000x reference)
; #define LAS __attribute__((address_space(3)))
; #define PG8_STAGE(bufoff, gbase, voff) do { _Pragma("unroll") for (int _i = 0; _i < 2; ++_i) \
;         __builtin_amdgcn_global_load_lds((const unsigned*)((const char*)(gbase) + (voff)[_i]), (LAS unsigned*)(lds + (bufoff) + ldsw + _i * 8192), 16, 0, 0); } while (0)
; #define PG8_LDA(dst, b, h) do { _Pragma("unroll") for (int m = 0; m < 4; ++m) _Pragma("unroll") for (int k = 0; k < 2; ++k) dst[m][k] = *(const LAS bf16x8*)(lds + PG8_SA(b, h) + aoff + m * 2048 + k * 1024); } while (0)
; #define PG8_LDB(dst, b, h) do { _Pragma("unroll") for (int n = 0; n < 2; ++n) _Pragma("unroll") for (int k = 0; k < 2; ++k) dst[n][k] = *(const LAS bf16x8*)(lds + PG8_SB(b, h) + boff + n * 2048 + k * 1024); } while (0)
; #define PG8_WAIT_V(n) asm volatile("s_waitcnt vmcnt(" #n ")" ::: "memory")
; #define PG8_WAIT_L(n) asm volatile("s_waitcnt lgkmcnt(" #n ")" ::: "memory")
; #define PG8_BAR __builtin_amdgcn_s_barrier()
; template <class Epi>
; __device__ __forceinline__ void gemm_phase(LAS unsigned char* lds, const int tid, const Gemm g, const StaticOrder& S, const Epi& E) {
;     ...
;             const bool last = (t == nt - 2);
;             const char* a1 = cA + (size_t)(t + 1) * kstep;
;             const char* a2 = last ? nA : cA + (size_t)(t + 2) * kstep; const char* b2 = last ? nB : cB + (size_t)(t + 2) * kstep;
;             const char* a3 = a2 + kstep; const char* b3 = b2 + kstep;
;             if constexpr (Epi::SS_LDS) { if (last) {
;                 const char* sp = (const char*)E.ss + (size_t)cur.pm * (256 * 64) + (size_t)tid * 16;
;                 __builtin_amdgcn_global_load_lds((const unsigned*)sp, (LAS unsigned*)(lds + RS_OFF + ldsw), 16, 0, 0);
;                 __builtin_amdgcn_global_load_lds((const unsigned*)(sp + 8192), (LAS unsigned*)(lds + RS_OFF + 8192 + ldsw), 16, 0, 0); } }
;     ...
;             PG8_LDB(B0, 0, 0); PG8_LDB(B1, 0, 1); PG8_SCHED; PG8_LDA(At, 0, 0); PG8_STAGE(PG8_SA(1, 1), a1 + hstepA, voffA);
;             PG8_WAIT_V(8); PG8_WAIT_L(0); PG8_BAR; PG8_MMA(0, 0, At, B0); PG8_MMA(0, 1, At, B1); PG8_BAR; PG8_SCHED;
;             PG8_LDA(At, 0, 1); PG8_STAGE(PG8_SB(0, 0), b2, voffB); PG8_STAGE(PG8_SB(0, 1), b2 + hstepB, voffB); PG8_STAGE(PG8_SA(0, 0), a2, voffA);
;             PG8_WAIT_V(8); PG8_WAIT_L(0); PG8_BAR; PG8_MMA(1, 0, At, B0); PG8_MMA(1, 1, At, B1); PG8_BAR; PG8_SCHED;
.LBB0_263:
	v_add_u32_e32 v168, s51, v151
	v_add_u32_e32 v184, s52, v151
	ds_read_b128 v[156:159], v168
	ds_read_b128 v[160:163], v168 offset:1024
	ds_read_b128 v[164:167], v168 offset:2048
	ds_read_b128 v[168:171], v168 offset:3072
	ds_read_b128 v[172:175], v184
	ds_read_b128 v[176:179], v184 offset:1024
	ds_read_b128 v[180:183], v184 offset:2048
	ds_read_b128 v[184:187], v184 offset:3072
	s_add_i32 s58, s58, 2
	s_add_u32 s30, s26, 0xfffc0080
	s_addc_u32 s31, s27, -1
	s_and_b64 s[28:29], s[28:29], exec
	s_cselect_b32 s31, s17, s31
	s_cselect_b32 s30, s19, s30
	s_cselect_b32 s29, s55, s57
	s_cselect_b32 s28, s56, s25
	v_lshl_add_u64 v[220:221], s[26:27], 0, v[140:141]
	s_add_i32 m0, s41, 0xc000
	ds_read_b128 v[188:191], v153
	ds_read_b128 v[192:195], v153 offset:1024
	ds_read_b128 v[196:199], v153 offset:2048
	ds_read_b128 v[200:203], v153 offset:3072
	ds_read_b128 v[204:207], v153 offset:4096
	ds_read_b128 v[208:211], v153 offset:5120
	ds_read_b128 v[212:215], v153 offset:6144
	ds_read_b128 v[216:219], v153 offset:7168
	global_load_lds_dwordx4 v[220:221], off
	v_lshl_add_u64 v[220:221], s[26:27], 0, v[138:139]
	s_add_i32 m0, s41, 0xe000
	s_nop 0
	global_load_lds_dwordx4 v[220:221], off
	s_waitcnt vmcnt(8)
	s_waitcnt lgkmcnt(0)
	s_barrier
	s_setprio 1
	v_mfma_f32_16x16x32_bf16 v[120:123], v[156:159], v[188:191], v[120:123]
	v_mfma_f32_16x16x32_bf16 v[116:119], v[164:167], v[188:191], v[116:119]
	v_mfma_f32_16x16x32_bf16 v[108:111], v[156:159], v[196:199], v[108:111]
	v_mfma_f32_16x16x32_bf16 v[100:103], v[164:167], v[196:199], v[100:103]
	v_mfma_f32_16x16x32_bf16 v[92:95], v[156:159], v[204:207], v[92:95]
	v_mfma_f32_16x16x32_bf16 v[84:87], v[164:167], v[204:207], v[84:87]
	v_mfma_f32_16x16x32_bf16 v[76:79], v[156:159], v[212:215], v[76:79]
	v_mfma_f32_16x16x32_bf16 v[68:71], v[164:167], v[212:215], v[68:71]
	v_mfma_f32_16x16x32_bf16 v[120:123], v[160:163], v[192:195], v[120:123]
	v_mfma_f32_16x16x32_bf16 v[116:119], v[168:171], v[192:195], v[116:119]
	v_mfma_f32_16x16x32_bf16 v[108:111], v[160:163], v[200:203], v[108:111]
	v_mfma_f32_16x16x32_bf16 v[100:103], v[168:171], v[200:203], v[100:103]
	v_mfma_f32_16x16x32_bf16 v[92:95], v[160:163], v[208:211], v[92:95]
	v_mfma_f32_16x16x32_bf16 v[84:87], v[168:171], v[208:211], v[84:87]
	v_mfma_f32_16x16x32_bf16 v[76:79], v[160:163], v[216:219], v[76:79]
	v_mfma_f32_16x16x32_bf16 v[68:71], v[168:171], v[216:219], v[68:71]
	v_mfma_f32_16x16x32_bf16 v[124:127], v[172:175], v[188:191], v[124:127]
	v_mfma_f32_16x16x32_bf16 v[112:115], v[180:183], v[188:191], v[112:115]
	v_mfma_f32_16x16x32_bf16 v[104:107], v[172:175], v[196:199], v[104:107]
	v_mfma_f32_16x16x32_bf16 v[96:99], v[180:183], v[196:199], v[96:99]
	v_mfma_f32_16x16x32_bf16 v[88:91], v[172:175], v[204:207], v[88:91]
	v_mfma_f32_16x16x32_bf16 v[80:83], v[180:183], v[204:207], v[80:83]
	v_mfma_f32_16x16x32_bf16 v[72:75], v[172:175], v[212:215], v[72:75]
	v_mfma_f32_16x16x32_bf16 v[64:67], v[180:183], v[212:215], v[64:67]
	v_mfma_f32_16x16x32_bf16 v[124:127], v[176:179], v[192:195], v[124:127]
	v_mfma_f32_16x16x32_bf16 v[112:115], v[184:187], v[192:195], v[112:115]
	v_mfma_f32_16x16x32_bf16 v[104:107], v[176:179], v[200:203], v[104:107]
	v_mfma_f32_16x16x32_bf16 v[96:99], v[184:187], v[200:203], v[96:99]
	v_mfma_f32_16x16x32_bf16 v[88:91], v[176:179], v[208:211], v[88:91]
	v_mfma_f32_16x16x32_bf16 v[80:83], v[184:187], v[208:211], v[80:83]
	v_mfma_f32_16x16x32_bf16 v[72:75], v[176:179], v[216:219], v[72:75]
	v_mfma_f32_16x16x32_bf16 v[64:67], v[184:187], v[216:219], v[64:67]
	s_setprio 0
	s_barrier
	s_add_i32 s59, s51, s38
	v_lshl_add_u64 v[220:221], s[28:29], 0, v[132:133]
	s_mov_b32 m0, s59
	ds_read_b128 v[188:191], v153 offset:16384
	ds_read_b128 v[192:195], v153 offset:17408
	ds_read_b128 v[196:199], v153 offset:18432
	ds_read_b128 v[200:203], v153 offset:19456
	ds_read_b128 v[204:207], v153 offset:20480
	ds_read_b128 v[208:211], v153 offset:21504
	ds_read_b128 v[212:215], v153 offset:22528
	ds_read_b128 v[216:219], v153 offset:23552
	global_load_lds_dwordx4 v[220:221], off
	s_add_i32 m0, s59, 0x2000
	s_add_u32 s60, s28, 0x40000
	v_lshl_add_u64 v[222:223], s[28:29], 0, v[128:129]
	s_addc_u32 s61, s29, 0
	s_add_i32 s59, s52, s38
	global_load_lds_dwordx4 v[222:223], off
	v_lshl_add_u64 v[224:225], s[60:61], 0, v[132:133]
	s_mov_b32 m0, s59
	v_lshl_add_u64 v[226:227], s[30:31], 0, v[130:131]
	global_load_lds_dwordx4 v[224:225], off
	v_lshl_add_u64 v[224:225], s[60:61], 0, v[128:129]
	s_add_i32 m0, s59, 0x2000
	s_nop 0
	global_load_lds_dwordx4 v[224:225], off
	v_lshl_add_u64 v[224:225], s[30:31], 0, v[134:135]
	s_mov_b32 m0, s41
	s_nop 0
	global_load_lds_dwordx4 v[224:225], off
	s_mov_b32 m0, s42
	s_nop 0
	global_load_lds_dwordx4 v[226:227], off
	s_waitcnt vmcnt(8)
	s_waitcnt lgkmcnt(0)
	s_barrier
; #define PG8_STAGE(bufoff, gbase, voff) do { _Pragma("unroll") for (int _i = 0; _i < 2; ++_i) \
;         __builtin_amdgcn_global_load_lds((const unsigned*)((const char*)(gbase) + (voff)[_i]), (LAS unsigned*)(lds + (bufoff) + ldsw + _i * 8192), 16, 0, 0); } while (0)
; #define PG8_LDA(dst, b, h) do { _Pragma("unroll") for (int m = 0; m < 4; ++m) _Pragma("unroll") for (int k = 0; k < 2; ++k) dst[m][k] = *(const LAS bf16x8*)(lds + PG8_SA(b, h) + aoff + m * 2048 + k * 1024); } while (0)
; #define PG8_LDB(dst, b, h) do { _Pragma("unroll") for (int n = 0; n < 2; ++n) _Pragma("unroll") for (int k = 0; k < 2; ++k) dst[n][k] = *(const LAS bf16x8*)(lds + PG8_SB(b, h) + boff + n * 2048 + k * 1024); } while (0)
; #define PG8_MMA(ai, bj, At, Bt) do { __builtin_amdgcn_s_setprio(1); _Pragma("unroll") for (int m = 0; m < 4; ++m) _Pragma("unroll") for (int n = 0; n < 2; ++n) _Pragma("unroll") for (int k = 0; k < 2; ++k) \
;         acc[ai][bj][m][n] = __builtin_amdgcn_mfma_f32_16x16x32_bf16(Bt[n][k], At[m][k], acc[ai][bj][m][n], 0, 0, 0); __builtin_amdgcn_s_setprio(0); } while (0)
; #define PG8_WAIT_V(n) asm volatile("s_waitcnt vmcnt(" #n ")" ::: "memory")
; #define PG8_WAIT_L(n) asm volatile("s_waitcnt lgkmcnt(" #n ")" ::: "memory")
; #define PG8_BAR __builtin_amdgcn_s_barrier()
; #define PG8_SCHED __builtin_amdgcn_sched_barrier(0)
; template <class Epi>
; __device__ __forceinline__ void gemm_phase(LAS unsigned char* lds, const int tid, const Gemm g, const StaticOrder& S, const Epi& E) {
;     ...
;             PG8_WAIT_V(8); PG8_WAIT_L(0); PG8_BAR; PG8_MMA(1, 0, At, B0); PG8_MMA(1, 1, At, B1); PG8_BAR; PG8_SCHED;
;             PG8_LDB(B0, 1, 0); PG8_LDB(B1, 1, 1); PG8_SCHED; PG8_LDA(At, 1, 0); PG8_STAGE(PG8_SA(0, 1), a2 + hstepA, voffA);
;             PG8_WAIT_V(8); PG8_WAIT_L(0); PG8_BAR; PG8_MMA(0, 0, At, B0); PG8_MMA(0, 1, At, B1); PG8_BAR; PG8_SCHED;
;             PG8_LDA(At, 1, 1); PG8_STAGE(PG8_SB(1, 0), b3, voffB); PG8_STAGE(PG8_SB(1, 1), b3 + hstepB, voffB); PG8_STAGE(PG8_SA(1, 0), a3, voffA);
	s_setprio 1
	v_mfma_f32_16x16x32_bf16 v[60:63], v[156:159], v[188:191], v[60:63]
	v_mfma_f32_16x16x32_bf16 v[52:55], v[164:167], v[188:191], v[52:55]
	v_mfma_f32_16x16x32_bf16 v[44:47], v[156:159], v[196:199], v[44:47]
	v_mfma_f32_16x16x32_bf16 v[36:39], v[164:167], v[196:199], v[36:39]
	v_mfma_f32_16x16x32_bf16 v[28:31], v[156:159], v[204:207], v[28:31]
	v_mfma_f32_16x16x32_bf16 v[20:23], v[164:167], v[204:207], v[20:23]
	v_mfma_f32_16x16x32_bf16 v[12:15], v[156:159], v[212:215], v[12:15]
	v_mfma_f32_16x16x32_bf16 v[4:7], v[164:167], v[212:215], v[4:7]
	v_mfma_f32_16x16x32_bf16 v[60:63], v[160:163], v[192:195], v[60:63]
	v_mfma_f32_16x16x32_bf16 v[52:55], v[168:171], v[192:195], v[52:55]
	v_mfma_f32_16x16x32_bf16 v[44:47], v[160:163], v[200:203], v[44:47]
	v_mfma_f32_16x16x32_bf16 v[36:39], v[168:171], v[200:203], v[36:39]
	v_mfma_f32_16x16x32_bf16 v[28:31], v[160:163], v[208:211], v[28:31]
	v_mfma_f32_16x16x32_bf16 v[20:23], v[168:171], v[208:211], v[20:23]
	v_mfma_f32_16x16x32_bf16 v[12:15], v[160:163], v[216:219], v[12:15]
	v_mfma_f32_16x16x32_bf16 v[4:7], v[168:171], v[216:219], v[4:7]
	v_mfma_f32_16x16x32_bf16 v[56:59], v[172:175], v[188:191], v[56:59]
	v_mfma_f32_16x16x32_bf16 v[48:51], v[180:183], v[188:191], v[48:51]
	v_mfma_f32_16x16x32_bf16 v[40:43], v[172:175], v[196:199], v[40:43]
	v_mfma_f32_16x16x32_bf16 v[32:35], v[180:183], v[196:199], v[32:35]
	v_mfma_f32_16x16x32_bf16 v[24:27], v[172:175], v[204:207], v[24:27]
	v_mfma_f32_16x16x32_bf16 v[16:19], v[180:183], v[204:207], v[16:19]
	v_mfma_f32_16x16x32_bf16 v[8:11], v[172:175], v[212:215], v[8:11]
	v_mfma_f32_16x16x32_bf16 v[0:3], v[180:183], v[212:215], v[0:3]
	v_mfma_f32_16x16x32_bf16 v[56:59], v[176:179], v[192:195], v[56:59]
	v_mfma_f32_16x16x32_bf16 v[48:51], v[184:187], v[192:195], v[48:51]
	v_mfma_f32_16x16x32_bf16 v[40:43], v[176:179], v[200:203], v[40:43]
	v_mfma_f32_16x16x32_bf16 v[32:35], v[184:187], v[200:203], v[32:35]
	v_mfma_f32_16x16x32_bf16 v[24:27], v[176:179], v[208:211], v[24:27]
	v_mfma_f32_16x16x32_bf16 v[16:19], v[184:187], v[208:211], v[16:19]
	v_mfma_f32_16x16x32_bf16 v[8:11], v[176:179], v[216:219], v[8:11]
	v_mfma_f32_16x16x32_bf16 v[0:3], v[184:187], v[216:219], v[0:3]
	s_setprio 0
	s_barrier
	s_add_i32 s59, 0, 0x18000
	s_add_i32 s60, 0, 0x1c000
	v_add_u32_e32 v168, s59, v151
	v_add_u32_e32 v184, s60, v151
	ds_read_b128 v[156:159], v168
	ds_read_b128 v[160:163], v168 offset:1024
	ds_read_b128 v[164:167], v168 offset:2048
	ds_read_b128 v[168:171], v168 offset:3072
	ds_read_b128 v[172:175], v184
	ds_read_b128 v[176:179], v184 offset:1024
	ds_read_b128 v[180:183], v184 offset:2048
	ds_read_b128 v[184:187], v184 offset:3072
	s_add_u32 s30, s30, 0x40000
	s_addc_u32 s31, s31, 0
	s_mov_b32 m0, s43
	v_lshl_add_u64 v[228:229], s[30:31], 0, v[134:135]
	ds_read_b128 v[188:191], v153 offset:32768
	ds_read_b128 v[192:195], v153 offset:33792
	ds_read_b128 v[196:199], v153 offset:34816
	ds_read_b128 v[200:203], v153 offset:35840
	ds_read_b128 v[204:207], v153 offset:36864
	ds_read_b128 v[208:211], v153 offset:37888
	ds_read_b128 v[212:215], v153 offset:38912
	ds_read_b128 v[216:219], v153 offset:39936
	global_load_lds_dwordx4 v[228:229], off
	v_lshl_add_u64 v[228:229], s[30:31], 0, v[130:131]
	s_mov_b32 m0, s44
	s_nop 0
	global_load_lds_dwordx4 v[228:229], off
	s_waitcnt vmcnt(8)
	s_waitcnt lgkmcnt(0)
	s_barrier
	s_setprio 1
	v_mfma_f32_16x16x32_bf16 v[120:123], v[156:159], v[188:191], v[120:123]
	v_mfma_f32_16x16x32_bf16 v[116:119], v[164:167], v[188:191], v[116:119]
	v_mfma_f32_16x16x32_bf16 v[108:111], v[156:159], v[196:199], v[108:111]
	v_mfma_f32_16x16x32_bf16 v[100:103], v[164:167], v[196:199], v[100:103]
	v_mfma_f32_16x16x32_bf16 v[92:95], v[156:159], v[204:207], v[92:95]
	v_mfma_f32_16x16x32_bf16 v[84:87], v[164:167], v[204:207], v[84:87]
	v_mfma_f32_16x16x32_bf16 v[76:79], v[156:159], v[212:215], v[76:79]
	v_mfma_f32_16x16x32_bf16 v[68:71], v[164:167], v[212:215], v[68:71]
	v_mfma_f32_16x16x32_bf16 v[120:123], v[160:163], v[192:195], v[120:123]
	v_mfma_f32_16x16x32_bf16 v[116:119], v[168:171], v[192:195], v[116:119]
	v_mfma_f32_16x16x32_bf16 v[108:111], v[160:163], v[200:203], v[108:111]
	v_mfma_f32_16x16x32_bf16 v[100:103], v[168:171], v[200:203], v[100:103]
	v_mfma_f32_16x16x32_bf16 v[92:95], v[160:163], v[208:211], v[92:95]
	v_mfma_f32_16x16x32_bf16 v[84:87], v[168:171], v[208:211], v[84:87]
	v_mfma_f32_16x16x32_bf16 v[76:79], v[160:163], v[216:219], v[76:79]
	v_mfma_f32_16x16x32_bf16 v[68:71], v[168:171], v[216:219], v[68:71]
	v_mfma_f32_16x16x32_bf16 v[124:127], v[172:175], v[188:191], v[124:127]
	v_mfma_f32_16x16x32_bf16 v[112:115], v[180:183], v[188:191], v[112:115]
	v_mfma_f32_16x16x32_bf16 v[104:107], v[172:175], v[196:199], v[104:107]
	v_mfma_f32_16x16x32_bf16 v[96:99], v[180:183], v[196:199], v[96:99]
	v_mfma_f32_16x16x32_bf16 v[88:91], v[172:175], v[204:207], v[88:91]
	v_mfma_f32_16x16x32_bf16 v[80:83], v[180:183], v[204:207], v[80:83]
	v_mfma_f32_16x16x32_bf16 v[72:75], v[172:175], v[212:215], v[72:75]
	v_mfma_f32_16x16x32_bf16 v[64:67], v[180:183], v[212:215], v[64:67]
	v_mfma_f32_16x16x32_bf16 v[124:127], v[176:179], v[192:195], v[124:127]
	v_mfma_f32_16x16x32_bf16 v[112:115], v[184:187], v[192:195], v[112:115]
	v_mfma_f32_16x16x32_bf16 v[104:107], v[176:179], v[200:203], v[104:107]
	v_mfma_f32_16x16x32_bf16 v[96:99], v[184:187], v[200:203], v[96:99]
	v_mfma_f32_16x16x32_bf16 v[88:91], v[176:179], v[208:211], v[88:91]
	v_mfma_f32_16x16x32_bf16 v[80:83], v[184:187], v[208:211], v[80:83]
	v_mfma_f32_16x16x32_bf16 v[72:75], v[176:179], v[216:219], v[72:75]
	v_mfma_f32_16x16x32_bf16 v[64:67], v[184:187], v[216:219], v[64:67]
	s_setprio 0
	s_barrier
; #define PG8_STAGE(bufoff, gbase, voff) do { _Pragma("unroll") for (int _i = 0; _i < 2; ++_i) \
;         __builtin_amdgcn_global_load_lds((const unsigned*)((const char*)(gbase) + (voff)[_i]), (LAS unsigned*)(lds + (bufoff) + ldsw + _i * 8192), 16, 0, 0); } while (0)
; #define PG8_LDA(dst, b, h) do { _Pragma("unroll") for (int m = 0; m < 4; ++m) _Pragma("unroll") for (int k = 0; k < 2; ++k) dst[m][k] = *(const LAS bf16x8*)(lds + PG8_SA(b, h) + aoff + m * 2048 + k * 1024); } while (0)
; #define PG8_MMA(ai, bj, At, Bt) do { __builtin_amdgcn_s_setprio(1); _Pragma("unroll") for (int m = 0; m < 4; ++m) _Pragma("unroll") for (int n = 0; n < 2; ++n) _Pragma("unroll") for (int k = 0; k < 2; ++k) \
;         acc[ai][bj][m][n] = __builtin_amdgcn_mfma_f32_16x16x32_bf16(Bt[n][k], At[m][k], acc[ai][bj][m][n], 0, 0, 0); __builtin_amdgcn_s_setprio(0); } while (0)
; #define PG8_WAIT_V(n) asm volatile("s_waitcnt vmcnt(" #n ")" ::: "memory")
; #define PG8_WAIT_L(n) asm volatile("s_waitcnt lgkmcnt(" #n ")" ::: "memory")
; #define PG8_BAR __builtin_amdgcn_s_barrier()
; #define PG8_SCHED __builtin_amdgcn_sched_barrier(0)
; template <class Epi>
; __device__ __forceinline__ void gemm_phase(LAS unsigned char* lds, const int tid, const Gemm g, const StaticOrder& S, const Epi& E) {
;     ...
;         for (int t = 0; t < nt; t += 2) {
;             const bool last = (t == nt - 2);
;             const char* a1 = cA + (size_t)(t + 1) * kstep;
;             const char* a2 = last ? nA : cA + (size_t)(t + 2) * kstep; const char* b2 = last ? nB : cB + (size_t)(t + 2) * kstep;
;             const char* a3 = a2 + kstep; const char* b3 = b2 + kstep;
;     ...
;             PG8_LDA(At, 1, 1); PG8_STAGE(PG8_SB(1, 0), b3, voffB); PG8_STAGE(PG8_SB(1, 1), b3 + hstepB, voffB); PG8_STAGE(PG8_SA(1, 0), a3, voffA);
;             PG8_WAIT_V(8); PG8_WAIT_L(0); PG8_BAR; PG8_MMA(1, 0, At, B0); PG8_MMA(1, 1, At, B1); PG8_BAR; PG8_SCHED;
	s_add_i32 s30, s59, s38
	v_lshl_add_u64 v[220:221], v[220:221], 0, s[12:13]
	s_mov_b32 m0, s30
	ds_read_b128 v[188:191], v153 offset:49152
	ds_read_b128 v[192:195], v153 offset:50176
	ds_read_b128 v[196:199], v153 offset:51200
	ds_read_b128 v[200:203], v153 offset:52224
	ds_read_b128 v[204:207], v153 offset:53248
	ds_read_b128 v[208:211], v153 offset:54272
	ds_read_b128 v[212:215], v153 offset:55296
	ds_read_b128 v[216:219], v153 offset:56320
	global_load_lds_dwordx4 v[220:221], off
	s_add_i32 m0, s30, 0x2000
	s_add_u32 s28, s28, 0x40080
	v_lshl_add_u64 v[220:221], v[222:223], 0, s[12:13]
	s_addc_u32 s29, s29, 0
	s_add_i32 s30, s60, s38
	global_load_lds_dwordx4 v[220:221], off
	v_lshl_add_u64 v[220:221], s[28:29], 0, v[132:133]
	s_mov_b32 m0, s30
	s_nop 0
	global_load_lds_dwordx4 v[220:221], off
	v_lshl_add_u64 v[220:221], s[28:29], 0, v[128:129]
	s_add_i32 m0, s30, 0x2000
	s_nop 0
	global_load_lds_dwordx4 v[220:221], off
	v_lshl_add_u64 v[220:221], v[224:225], 0, s[12:13]
	s_mov_b32 m0, s47
	s_nop 0
	global_load_lds_dwordx4 v[220:221], off
	v_lshl_add_u64 v[220:221], v[226:227], 0, s[12:13]
	s_mov_b32 m0, s48
	s_nop 0
	global_load_lds_dwordx4 v[220:221], off
	s_waitcnt vmcnt(8)
	s_waitcnt lgkmcnt(0)
	s_barrier
	s_setprio 1
	v_mfma_f32_16x16x32_bf16 v[60:63], v[156:159], v[188:191], v[60:63]
	v_mfma_f32_16x16x32_bf16 v[52:55], v[164:167], v[188:191], v[52:55]
	v_mfma_f32_16x16x32_bf16 v[44:47], v[156:159], v[196:199], v[44:47]
	v_mfma_f32_16x16x32_bf16 v[36:39], v[164:167], v[196:199], v[36:39]
	v_mfma_f32_16x16x32_bf16 v[28:31], v[156:159], v[204:207], v[28:31]
	v_mfma_f32_16x16x32_bf16 v[20:23], v[164:167], v[204:207], v[20:23]
	v_mfma_f32_16x16x32_bf16 v[12:15], v[156:159], v[212:215], v[12:15]
	v_mfma_f32_16x16x32_bf16 v[4:7], v[164:167], v[212:215], v[4:7]
	v_mfma_f32_16x16x32_bf16 v[60:63], v[160:163], v[192:195], v[60:63]
	v_mfma_f32_16x16x32_bf16 v[52:55], v[168:171], v[192:195], v[52:55]
	v_mfma_f32_16x16x32_bf16 v[44:47], v[160:163], v[200:203], v[44:47]
	v_mfma_f32_16x16x32_bf16 v[36:39], v[168:171], v[200:203], v[36:39]
	v_mfma_f32_16x16x32_bf16 v[28:31], v[160:163], v[208:211], v[28:31]
	v_mfma_f32_16x16x32_bf16 v[20:23], v[168:171], v[208:211], v[20:23]
	v_mfma_f32_16x16x32_bf16 v[12:15], v[160:163], v[216:219], v[12:15]
	v_mfma_f32_16x16x32_bf16 v[4:7], v[168:171], v[216:219], v[4:7]
	v_mfma_f32_16x16x32_bf16 v[56:59], v[172:175], v[188:191], v[56:59]
	v_mfma_f32_16x16x32_bf16 v[48:51], v[180:183], v[188:191], v[48:51]
	v_mfma_f32_16x16x32_bf16 v[40:43], v[172:175], v[196:199], v[40:43]
	v_mfma_f32_16x16x32_bf16 v[32:35], v[180:183], v[196:199], v[32:35]
	v_mfma_f32_16x16x32_bf16 v[24:27], v[172:175], v[204:207], v[24:27]
	v_mfma_f32_16x16x32_bf16 v[16:19], v[180:183], v[204:207], v[16:19]
	v_mfma_f32_16x16x32_bf16 v[8:11], v[172:175], v[212:215], v[8:11]
	v_mfma_f32_16x16x32_bf16 v[0:3], v[180:183], v[212:215], v[0:3]
	v_mfma_f32_16x16x32_bf16 v[56:59], v[176:179], v[192:195], v[56:59]
	v_mfma_f32_16x16x32_bf16 v[48:51], v[184:187], v[192:195], v[48:51]
	v_mfma_f32_16x16x32_bf16 v[40:43], v[176:179], v[200:203], v[40:43]
	v_mfma_f32_16x16x32_bf16 v[32:35], v[184:187], v[200:203], v[32:35]
	v_mfma_f32_16x16x32_bf16 v[24:27], v[176:179], v[208:211], v[24:27]
	v_mfma_f32_16x16x32_bf16 v[16:19], v[184:187], v[208:211], v[16:19]
	v_mfma_f32_16x16x32_bf16 v[8:11], v[176:179], v[216:219], v[8:11]
	v_mfma_f32_16x16x32_bf16 v[0:3], v[184:187], v[216:219], v[0:3]
	s_setprio 0
	s_barrier
	s_add_u32 s25, s25, 0x100
	s_addc_u32 s57, s57, 0
	s_add_u32 s26, s26, 0x100
	s_addc_u32 s27, s27, 0
	s_cmp_ge_i32 s58, s46
	s_cbranch_scc1 .LBB0_266

; #define LAS __attribute__((address_space(3)))
; #define PG8_STAGE(bufoff, gbase, voff) do { _Pragma("unroll") for (int _i = 0; _i < 2; ++_i) \
;         __builtin_amdgcn_global_load_lds((const unsigned*)((const char*)(gbase) + (voff)[_i]), (LAS unsigned*)(lds + (bufoff) + ldsw + _i * 8192), 16, 0, 0); } while (0)
; #define PG8_LDA(dst, b, h) do { _Pragma("unroll") for (int m = 0; m < 4; ++m) _Pragma("unroll") for (int k = 0; k < 2; ++k) dst[m][k] = *(const LAS bf16x8*)(lds + PG8_SA(b, h) + aoff + m * 2048 + k * 1024); } while (0)
; #define PG8_LDB(dst, b, h) do { _Pragma("unroll") for (int n = 0; n < 2; ++n) _Pragma("unroll") for (int k = 0; k < 2; ++k) dst[n][k] = *(const LAS bf16x8*)(lds + PG8_SB(b, h) + boff + n * 2048 + k * 1024); } while (0)
; #define PG8_WAIT_V(n) asm volatile("s_waitcnt vmcnt(" #n ")" ::: "memory")
; #define PG8_WAIT_L(n) asm volatile("s_waitcnt lgkmcnt(" #n ")" ::: "memory")
; #define PG8_BAR __builtin_amdgcn_s_barrier()
; template <class Epi>
; __device__ __forceinline__ void gemm_phase(LAS unsigned char* lds, const int tid, const Gemm g, const StaticOrder& S, const Epi& E) {
;     ...
;             const bool last = (t == nt - 2);
;             const char* a1 = cA + (size_t)(t + 1) * kstep;
;             const char* a2 = last ? nA : cA + (size_t)(t + 2) * kstep; const char* b2 = last ? nB : cB + (size_t)(t + 2) * kstep;
;             const char* a3 = a2 + kstep; const char* b3 = b2 + kstep;
;             if constexpr (Epi::SS_LDS) { if (last) {
;                 const char* sp = (const char*)E.ss + (size_t)cur.pm * (256 * 64) + (size_t)tid * 16;
;                 __builtin_amdgcn_global_load_lds((const unsigned*)sp, (LAS unsigned*)(lds + RS_OFF + ldsw), 16, 0, 0);
;                 __builtin_amdgcn_global_load_lds((const unsigned*)(sp + 8192), (LAS unsigned*)(lds + RS_OFF + 8192 + ldsw), 16, 0, 0); } }
;     ...
;             PG8_LDB(B0, 0, 0); PG8_LDB(B1, 0, 1); PG8_SCHED; PG8_LDA(At, 0, 0); PG8_STAGE(PG8_SA(1, 1), a1 + hstepA, voffA);
;             PG8_WAIT_V(8); PG8_WAIT_L(0); PG8_BAR; PG8_MMA(0, 0, At, B0); PG8_MMA(0, 1, At, B1); PG8_BAR; PG8_SCHED;
;             PG8_LDA(At, 0, 1); PG8_STAGE(PG8_SB(0, 0), b2, voffB); PG8_STAGE(PG8_SB(0, 1), b2 + hstepB, voffB); PG8_STAGE(PG8_SA(0, 0), a2, voffA);
;             PG8_WAIT_V(8); PG8_WAIT_L(0); PG8_BAR; PG8_MMA(1, 0, At, B0); PG8_MMA(1, 1, At, B1); PG8_BAR; PG8_SCHED;
.LBB0_352:
	ds_read_b128 v[144:147], v207
	ds_read_b128 v[148:151], v207 offset:1024
	ds_read_b128 v[152:155], v207 offset:2048
	ds_read_b128 v[156:159], v207 offset:3072
	ds_read_b128 v[160:163], v208
	ds_read_b128 v[164:167], v208 offset:1024
	ds_read_b128 v[168:171], v208 offset:2048
	ds_read_b128 v[172:175], v208 offset:3072
	s_add_i32 s60, s30, 2
	s_add_u32 s28, s26, 0x100
	s_addc_u32 s29, s27, 0
	s_cmp_eq_u32 s49, s30
	s_cselect_b32 s30, s24, s58
	s_cselect_b32 s35, s7, s29
	s_cselect_b32 s34, s6, s28
	s_cselect_b32 s31, s25, s59
	v_lshl_add_u64 v[214:215], s[26:27], 0, v[138:139]
	s_add_i32 m0, s41, 0xc000
	ds_read_b128 v[176:179], v209
	ds_read_b128 v[180:183], v209 offset:1024
	ds_read_b128 v[184:187], v209 offset:2048
	ds_read_b128 v[188:191], v209 offset:3072
	ds_read_b128 v[192:195], v209 offset:4096
	ds_read_b128 v[196:199], v209 offset:5120
	ds_read_b128 v[200:203], v209 offset:6144
	ds_read_b128 v[210:213], v209 offset:7168
	global_load_lds_dwordx4 v[214:215], off
	v_lshl_add_u64 v[214:215], s[26:27], 0, v[136:137]
	s_add_i32 m0, s41, 0xe000
	s_nop 0
	global_load_lds_dwordx4 v[214:215], off
	s_waitcnt vmcnt(8)
	s_waitcnt lgkmcnt(0)
	s_barrier
	s_setprio 1
	v_mfma_f32_16x16x32_bf16 v[124:127], v[144:147], v[176:179], v[124:127]
	v_mfma_f32_16x16x32_bf16 v[120:123], v[152:155], v[176:179], v[120:123]
	v_mfma_f32_16x16x32_bf16 v[116:119], v[144:147], v[184:187], v[116:119]
	v_mfma_f32_16x16x32_bf16 v[112:115], v[152:155], v[184:187], v[112:115]
	v_mfma_f32_16x16x32_bf16 v[104:107], v[144:147], v[192:195], v[104:107]
	v_mfma_f32_16x16x32_bf16 v[96:99], v[152:155], v[192:195], v[96:99]
	v_mfma_f32_16x16x32_bf16 v[88:91], v[144:147], v[200:203], v[88:91]
	v_mfma_f32_16x16x32_bf16 v[80:83], v[152:155], v[200:203], v[80:83]
	v_mfma_f32_16x16x32_bf16 v[124:127], v[148:151], v[180:183], v[124:127]
	v_mfma_f32_16x16x32_bf16 v[120:123], v[156:159], v[180:183], v[120:123]
	v_mfma_f32_16x16x32_bf16 v[116:119], v[148:151], v[188:191], v[116:119]
	v_mfma_f32_16x16x32_bf16 v[112:115], v[156:159], v[188:191], v[112:115]
	v_mfma_f32_16x16x32_bf16 v[104:107], v[148:151], v[196:199], v[104:107]
	v_mfma_f32_16x16x32_bf16 v[96:99], v[156:159], v[196:199], v[96:99]
	v_mfma_f32_16x16x32_bf16 v[88:91], v[148:151], v[210:213], v[88:91]
	v_mfma_f32_16x16x32_bf16 v[80:83], v[156:159], v[210:213], v[80:83]
	v_mfma_f32_16x16x32_bf16 v[108:111], v[160:163], v[176:179], v[108:111]
	v_mfma_f32_16x16x32_bf16 v[100:103], v[168:171], v[176:179], v[100:103]
	v_mfma_f32_16x16x32_bf16 v[92:95], v[160:163], v[184:187], v[92:95]
	v_mfma_f32_16x16x32_bf16 v[84:87], v[168:171], v[184:187], v[84:87]
	v_mfma_f32_16x16x32_bf16 v[76:79], v[160:163], v[192:195], v[76:79]
	v_mfma_f32_16x16x32_bf16 v[72:75], v[168:171], v[192:195], v[72:75]
	v_mfma_f32_16x16x32_bf16 v[68:71], v[160:163], v[200:203], v[68:71]
	v_mfma_f32_16x16x32_bf16 v[64:67], v[168:171], v[200:203], v[64:67]
	v_mfma_f32_16x16x32_bf16 v[108:111], v[164:167], v[180:183], v[108:111]
	v_mfma_f32_16x16x32_bf16 v[100:103], v[172:175], v[180:183], v[100:103]
	v_mfma_f32_16x16x32_bf16 v[92:95], v[164:167], v[188:191], v[92:95]
	v_mfma_f32_16x16x32_bf16 v[84:87], v[172:175], v[188:191], v[84:87]
	v_mfma_f32_16x16x32_bf16 v[76:79], v[164:167], v[196:199], v[76:79]
	v_mfma_f32_16x16x32_bf16 v[72:75], v[172:175], v[196:199], v[72:75]
	v_mfma_f32_16x16x32_bf16 v[68:71], v[164:167], v[210:213], v[68:71]
	v_mfma_f32_16x16x32_bf16 v[64:67], v[172:175], v[210:213], v[64:67]
	s_setprio 0
	s_barrier
	s_add_i32 s26, s52, s40
	v_lshl_add_u64 v[214:215], s[30:31], 0, v[130:131]
	s_mov_b32 m0, s26
	ds_read_b128 v[176:179], v209 offset:16384
	ds_read_b128 v[180:183], v209 offset:17408
	ds_read_b128 v[184:187], v209 offset:18432
	ds_read_b128 v[188:191], v209 offset:19456
	ds_read_b128 v[192:195], v209 offset:20480
	ds_read_b128 v[196:199], v209 offset:21504
	ds_read_b128 v[200:203], v209 offset:22528
	ds_read_b128 v[210:213], v209 offset:23552
	global_load_lds_dwordx4 v[214:215], off
	s_add_i32 m0, s26, 0x2000
	s_add_u32 s26, s30, 0xb0000
	v_lshl_add_u64 v[216:217], s[30:31], 0, v[134:135]
	s_addc_u32 s27, s31, 0
	s_add_i32 s61, s53, s40
	global_load_lds_dwordx4 v[216:217], off
	v_lshl_add_u64 v[218:219], s[26:27], 0, v[130:131]
	s_mov_b32 m0, s61
	v_lshl_add_u64 v[220:221], s[34:35], 0, v[132:133]
	global_load_lds_dwordx4 v[218:219], off
	v_lshl_add_u64 v[218:219], s[26:27], 0, v[134:135]
	s_add_i32 m0, s61, 0x2000
	s_nop 0
	global_load_lds_dwordx4 v[218:219], off
	v_lshl_add_u64 v[218:219], s[34:35], 0, v[128:129]
	s_mov_b32 m0, s41
	s_nop 0
	global_load_lds_dwordx4 v[218:219], off
	s_mov_b32 m0, s42
	s_nop 0
	global_load_lds_dwordx4 v[220:221], off
	s_waitcnt vmcnt(8)
	s_waitcnt lgkmcnt(0)
	s_barrier
; #define PG8_STAGE(bufoff, gbase, voff) do { _Pragma("unroll") for (int _i = 0; _i < 2; ++_i) \
;         __builtin_amdgcn_global_load_lds((const unsigned*)((const char*)(gbase) + (voff)[_i]), (LAS unsigned*)(lds + (bufoff) + ldsw + _i * 8192), 16, 0, 0); } while (0)
; #define PG8_LDA(dst, b, h) do { _Pragma("unroll") for (int m = 0; m < 4; ++m) _Pragma("unroll") for (int k = 0; k < 2; ++k) dst[m][k] = *(const LAS bf16x8*)(lds + PG8_SA(b, h) + aoff + m * 2048 + k * 1024); } while (0)
; #define PG8_LDB(dst, b, h) do { _Pragma("unroll") for (int n = 0; n < 2; ++n) _Pragma("unroll") for (int k = 0; k < 2; ++k) dst[n][k] = *(const LAS bf16x8*)(lds + PG8_SB(b, h) + boff + n * 2048 + k * 1024); } while (0)
; #define PG8_MMA(ai, bj, At, Bt) do { __builtin_amdgcn_s_setprio(1); _Pragma("unroll") for (int m = 0; m < 4; ++m) _Pragma("unroll") for (int n = 0; n < 2; ++n) _Pragma("unroll") for (int k = 0; k < 2; ++k) \
;         acc[ai][bj][m][n] = __builtin_amdgcn_mfma_f32_16x16x32_bf16(Bt[n][k], At[m][k], acc[ai][bj][m][n], 0, 0, 0); __builtin_amdgcn_s_setprio(0); } while (0)
; #define PG8_WAIT_V(n) asm volatile("s_waitcnt vmcnt(" #n ")" ::: "memory")
; #define PG8_WAIT_L(n) asm volatile("s_waitcnt lgkmcnt(" #n ")" ::: "memory")
; #define PG8_BAR __builtin_amdgcn_s_barrier()
; #define PG8_SCHED __builtin_amdgcn_sched_barrier(0)
; template <class Epi>
; __device__ __forceinline__ void gemm_phase(LAS unsigned char* lds, const int tid, const Gemm g, const StaticOrder& S, const Epi& E) {
;     ...
;             PG8_WAIT_V(8); PG8_WAIT_L(0); PG8_BAR; PG8_MMA(1, 0, At, B0); PG8_MMA(1, 1, At, B1); PG8_BAR; PG8_SCHED;
;             PG8_LDB(B0, 1, 0); PG8_LDB(B1, 1, 1); PG8_SCHED; PG8_LDA(At, 1, 0); PG8_STAGE(PG8_SA(0, 1), a2 + hstepA, voffA);
;             PG8_WAIT_V(8); PG8_WAIT_L(0); PG8_BAR; PG8_MMA(0, 0, At, B0); PG8_MMA(0, 1, At, B1); PG8_BAR; PG8_SCHED;
;             PG8_LDA(At, 1, 1); PG8_STAGE(PG8_SB(1, 0), b3, voffB); PG8_STAGE(PG8_SB(1, 1), b3 + hstepB, voffB); PG8_STAGE(PG8_SA(1, 0), a3, voffA);
	s_setprio 1
	v_mfma_f32_16x16x32_bf16 v[60:63], v[144:147], v[176:179], v[60:63]
	v_mfma_f32_16x16x32_bf16 v[56:59], v[152:155], v[176:179], v[56:59]
	v_mfma_f32_16x16x32_bf16 v[52:55], v[144:147], v[184:187], v[52:55]
	v_mfma_f32_16x16x32_bf16 v[48:51], v[152:155], v[184:187], v[48:51]
	v_mfma_f32_16x16x32_bf16 v[40:43], v[144:147], v[192:195], v[40:43]
	v_mfma_f32_16x16x32_bf16 v[32:35], v[152:155], v[192:195], v[32:35]
	v_mfma_f32_16x16x32_bf16 v[24:27], v[144:147], v[200:203], v[24:27]
	v_mfma_f32_16x16x32_bf16 v[16:19], v[152:155], v[200:203], v[16:19]
	v_mfma_f32_16x16x32_bf16 v[60:63], v[148:151], v[180:183], v[60:63]
	v_mfma_f32_16x16x32_bf16 v[56:59], v[156:159], v[180:183], v[56:59]
	v_mfma_f32_16x16x32_bf16 v[52:55], v[148:151], v[188:191], v[52:55]
	v_mfma_f32_16x16x32_bf16 v[48:51], v[156:159], v[188:191], v[48:51]
	v_mfma_f32_16x16x32_bf16 v[40:43], v[148:151], v[196:199], v[40:43]
	v_mfma_f32_16x16x32_bf16 v[32:35], v[156:159], v[196:199], v[32:35]
	v_mfma_f32_16x16x32_bf16 v[24:27], v[148:151], v[210:213], v[24:27]
	v_mfma_f32_16x16x32_bf16 v[16:19], v[156:159], v[210:213], v[16:19]
	v_mfma_f32_16x16x32_bf16 v[44:47], v[160:163], v[176:179], v[44:47]
	v_mfma_f32_16x16x32_bf16 v[36:39], v[168:171], v[176:179], v[36:39]
	v_mfma_f32_16x16x32_bf16 v[28:31], v[160:163], v[184:187], v[28:31]
	v_mfma_f32_16x16x32_bf16 v[20:23], v[168:171], v[184:187], v[20:23]
	v_mfma_f32_16x16x32_bf16 v[12:15], v[160:163], v[192:195], v[12:15]
	v_mfma_f32_16x16x32_bf16 v[8:11], v[168:171], v[192:195], v[8:11]
	v_mfma_f32_16x16x32_bf16 v[4:7], v[160:163], v[200:203], v[4:7]
	v_mfma_f32_16x16x32_bf16 v[0:3], v[168:171], v[200:203], v[0:3]
	v_mfma_f32_16x16x32_bf16 v[44:47], v[164:167], v[180:183], v[44:47]
	v_mfma_f32_16x16x32_bf16 v[36:39], v[172:175], v[180:183], v[36:39]
	v_mfma_f32_16x16x32_bf16 v[28:31], v[164:167], v[188:191], v[28:31]
	v_mfma_f32_16x16x32_bf16 v[20:23], v[172:175], v[188:191], v[20:23]
	v_mfma_f32_16x16x32_bf16 v[12:15], v[164:167], v[196:199], v[12:15]
	v_mfma_f32_16x16x32_bf16 v[8:11], v[172:175], v[196:199], v[8:11]
	v_mfma_f32_16x16x32_bf16 v[4:7], v[164:167], v[210:213], v[4:7]
	v_mfma_f32_16x16x32_bf16 v[0:3], v[172:175], v[210:213], v[0:3]
	s_setprio 0
	s_barrier
	s_add_i32 s61, 0, 0x18000
	s_add_i32 s62, 0, 0x1c000
	v_add_u32_e32 v156, s61, v205
	v_add_u32_e32 v172, s62, v205
	ds_read_b128 v[144:147], v156
	ds_read_b128 v[148:151], v156 offset:1024
	ds_read_b128 v[152:155], v156 offset:2048
	ds_read_b128 v[156:159], v156 offset:3072
	ds_read_b128 v[160:163], v172
	ds_read_b128 v[164:167], v172 offset:1024
	ds_read_b128 v[168:171], v172 offset:2048
	ds_read_b128 v[172:175], v172 offset:3072
	s_add_u32 s26, s34, 0xb0000
	s_addc_u32 s27, s35, 0
	s_mov_b32 m0, s43
	v_lshl_add_u64 v[222:223], s[26:27], 0, v[128:129]
	ds_read_b128 v[176:179], v209 offset:32768
	ds_read_b128 v[180:183], v209 offset:33792
	ds_read_b128 v[184:187], v209 offset:34816
	ds_read_b128 v[188:191], v209 offset:35840
	ds_read_b128 v[192:195], v209 offset:36864
	ds_read_b128 v[196:199], v209 offset:37888
	ds_read_b128 v[200:203], v209 offset:38912
	ds_read_b128 v[210:213], v209 offset:39936
	global_load_lds_dwordx4 v[222:223], off
	v_lshl_add_u64 v[222:223], s[26:27], 0, v[132:133]
	s_mov_b32 m0, s44
	s_nop 0
	global_load_lds_dwordx4 v[222:223], off
	s_waitcnt vmcnt(8)
	s_waitcnt lgkmcnt(0)
	s_barrier
	s_setprio 1
	v_mfma_f32_16x16x32_bf16 v[124:127], v[144:147], v[176:179], v[124:127]
	v_mfma_f32_16x16x32_bf16 v[120:123], v[152:155], v[176:179], v[120:123]
	v_mfma_f32_16x16x32_bf16 v[116:119], v[144:147], v[184:187], v[116:119]
	v_mfma_f32_16x16x32_bf16 v[112:115], v[152:155], v[184:187], v[112:115]
	v_mfma_f32_16x16x32_bf16 v[104:107], v[144:147], v[192:195], v[104:107]
	v_mfma_f32_16x16x32_bf16 v[96:99], v[152:155], v[192:195], v[96:99]
	v_mfma_f32_16x16x32_bf16 v[88:91], v[144:147], v[200:203], v[88:91]
	v_mfma_f32_16x16x32_bf16 v[80:83], v[152:155], v[200:203], v[80:83]
	v_mfma_f32_16x16x32_bf16 v[124:127], v[148:151], v[180:183], v[124:127]
	v_mfma_f32_16x16x32_bf16 v[120:123], v[156:159], v[180:183], v[120:123]
	v_mfma_f32_16x16x32_bf16 v[116:119], v[148:151], v[188:191], v[116:119]
	v_mfma_f32_16x16x32_bf16 v[112:115], v[156:159], v[188:191], v[112:115]
	v_mfma_f32_16x16x32_bf16 v[104:107], v[148:151], v[196:199], v[104:107]
	v_mfma_f32_16x16x32_bf16 v[96:99], v[156:159], v[196:199], v[96:99]
	v_mfma_f32_16x16x32_bf16 v[88:91], v[148:151], v[210:213], v[88:91]
	v_mfma_f32_16x16x32_bf16 v[80:83], v[156:159], v[210:213], v[80:83]
	v_mfma_f32_16x16x32_bf16 v[108:111], v[160:163], v[176:179], v[108:111]
	v_mfma_f32_16x16x32_bf16 v[100:103], v[168:171], v[176:179], v[100:103]
	v_mfma_f32_16x16x32_bf16 v[92:95], v[160:163], v[184:187], v[92:95]
	v_mfma_f32_16x16x32_bf16 v[84:87], v[168:171], v[184:187], v[84:87]
	v_mfma_f32_16x16x32_bf16 v[76:79], v[160:163], v[192:195], v[76:79]
	v_mfma_f32_16x16x32_bf16 v[72:75], v[168:171], v[192:195], v[72:75]
	v_mfma_f32_16x16x32_bf16 v[68:71], v[160:163], v[200:203], v[68:71]
	v_mfma_f32_16x16x32_bf16 v[64:67], v[168:171], v[200:203], v[64:67]
	v_mfma_f32_16x16x32_bf16 v[108:111], v[164:167], v[180:183], v[108:111]
	v_mfma_f32_16x16x32_bf16 v[100:103], v[172:175], v[180:183], v[100:103]
	v_mfma_f32_16x16x32_bf16 v[92:95], v[164:167], v[188:191], v[92:95]
	v_mfma_f32_16x16x32_bf16 v[84:87], v[172:175], v[188:191], v[84:87]
	v_mfma_f32_16x16x32_bf16 v[76:79], v[164:167], v[196:199], v[76:79]
	v_mfma_f32_16x16x32_bf16 v[72:75], v[172:175], v[196:199], v[72:75]
	v_mfma_f32_16x16x32_bf16 v[68:71], v[164:167], v[210:213], v[68:71]
	v_mfma_f32_16x16x32_bf16 v[64:67], v[172:175], v[210:213], v[64:67]
	s_setprio 0
	s_barrier
; #define PG8_STAGE(bufoff, gbase, voff) do { _Pragma("unroll") for (int _i = 0; _i < 2; ++_i) \
;         __builtin_amdgcn_global_load_lds((const unsigned*)((const char*)(gbase) + (voff)[_i]), (LAS unsigned*)(lds + (bufoff) + ldsw + _i * 8192), 16, 0, 0); } while (0)
; #define PG8_LDA(dst, b, h) do { _Pragma("unroll") for (int m = 0; m < 4; ++m) _Pragma("unroll") for (int k = 0; k < 2; ++k) dst[m][k] = *(const LAS bf16x8*)(lds + PG8_SA(b, h) + aoff + m * 2048 + k * 1024); } while (0)
; #define PG8_MMA(ai, bj, At, Bt) do { __builtin_amdgcn_s_setprio(1); _Pragma("unroll") for (int m = 0; m < 4; ++m) _Pragma("unroll") for (int n = 0; n < 2; ++n) _Pragma("unroll") for (int k = 0; k < 2; ++k) \
;         acc[ai][bj][m][n] = __builtin_amdgcn_mfma_f32_16x16x32_bf16(Bt[n][k], At[m][k], acc[ai][bj][m][n], 0, 0, 0); __builtin_amdgcn_s_setprio(0); } while (0)
; #define PG8_WAIT_V(n) asm volatile("s_waitcnt vmcnt(" #n ")" ::: "memory")
; #define PG8_WAIT_L(n) asm volatile("s_waitcnt lgkmcnt(" #n ")" ::: "memory")
; #define PG8_BAR __builtin_amdgcn_s_barrier()
; #define PG8_SCHED __builtin_amdgcn_sched_barrier(0)
; template <class Epi>
; __device__ __forceinline__ void gemm_phase(LAS unsigned char* lds, const int tid, const Gemm g, const StaticOrder& S, const Epi& E) {
;     ...
;         for (int t = 0; t < nt; t += 2) {
;             const bool last = (t == nt - 2);
;             const char* a1 = cA + (size_t)(t + 1) * kstep;
;             const char* a2 = last ? nA : cA + (size_t)(t + 2) * kstep; const char* b2 = last ? nB : cB + (size_t)(t + 2) * kstep;
;             const char* a3 = a2 + kstep; const char* b3 = b2 + kstep;
;     ...
;             PG8_LDA(At, 1, 1); PG8_STAGE(PG8_SB(1, 0), b3, voffB); PG8_STAGE(PG8_SB(1, 1), b3 + hstepB, voffB); PG8_STAGE(PG8_SA(1, 0), a3, voffA);
;             PG8_WAIT_V(8); PG8_WAIT_L(0); PG8_BAR; PG8_MMA(1, 0, At, B0); PG8_MMA(1, 1, At, B1); PG8_BAR; PG8_SCHED;
	s_add_i32 s26, s61, s40
	v_lshl_add_u64 v[214:215], v[214:215], 0, s[18:19]
	s_mov_b32 m0, s26
	ds_read_b128 v[176:179], v209 offset:49152
	ds_read_b128 v[180:183], v209 offset:50176
	ds_read_b128 v[184:187], v209 offset:51200
	ds_read_b128 v[188:191], v209 offset:52224
	ds_read_b128 v[192:195], v209 offset:53248
	ds_read_b128 v[196:199], v209 offset:54272
	ds_read_b128 v[200:203], v209 offset:55296
	ds_read_b128 v[210:213], v209 offset:56320
	global_load_lds_dwordx4 v[214:215], off
	s_add_i32 m0, s26, 0x2000
	s_add_u32 s26, s30, 0xb0080
	v_lshl_add_u64 v[214:215], v[216:217], 0, s[18:19]
	s_addc_u32 s27, s31, 0
	s_add_i32 s30, s62, s40
	global_load_lds_dwordx4 v[214:215], off
	v_lshl_add_u64 v[214:215], s[26:27], 0, v[130:131]
	s_mov_b32 m0, s30
	s_nop 0
	global_load_lds_dwordx4 v[214:215], off
	v_lshl_add_u64 v[214:215], s[26:27], 0, v[134:135]
	s_add_i32 m0, s30, 0x2000
	s_nop 0
	global_load_lds_dwordx4 v[214:215], off
	v_lshl_add_u64 v[214:215], v[218:219], 0, s[18:19]
	s_mov_b32 m0, s47
	s_nop 0
	global_load_lds_dwordx4 v[214:215], off
	v_lshl_add_u64 v[214:215], v[220:221], 0, s[18:19]
	s_mov_b32 m0, s48
	s_nop 0
	global_load_lds_dwordx4 v[214:215], off
	s_waitcnt vmcnt(8)
	s_waitcnt lgkmcnt(0)
	s_barrier
	s_setprio 1
	v_mfma_f32_16x16x32_bf16 v[60:63], v[144:147], v[176:179], v[60:63]
	v_mfma_f32_16x16x32_bf16 v[56:59], v[152:155], v[176:179], v[56:59]
	v_mfma_f32_16x16x32_bf16 v[52:55], v[144:147], v[184:187], v[52:55]
	v_mfma_f32_16x16x32_bf16 v[48:51], v[152:155], v[184:187], v[48:51]
	v_mfma_f32_16x16x32_bf16 v[40:43], v[144:147], v[192:195], v[40:43]
	v_mfma_f32_16x16x32_bf16 v[32:35], v[152:155], v[192:195], v[32:35]
	v_mfma_f32_16x16x32_bf16 v[24:27], v[144:147], v[200:203], v[24:27]
	v_mfma_f32_16x16x32_bf16 v[16:19], v[152:155], v[200:203], v[16:19]
	v_mfma_f32_16x16x32_bf16 v[60:63], v[148:151], v[180:183], v[60:63]
	v_mfma_f32_16x16x32_bf16 v[56:59], v[156:159], v[180:183], v[56:59]
	v_mfma_f32_16x16x32_bf16 v[52:55], v[148:151], v[188:191], v[52:55]
	v_mfma_f32_16x16x32_bf16 v[48:51], v[156:159], v[188:191], v[48:51]
	v_mfma_f32_16x16x32_bf16 v[40:43], v[148:151], v[196:199], v[40:43]
	v_mfma_f32_16x16x32_bf16 v[32:35], v[156:159], v[196:199], v[32:35]
	v_mfma_f32_16x16x32_bf16 v[24:27], v[148:151], v[210:213], v[24:27]
	v_mfma_f32_16x16x32_bf16 v[16:19], v[156:159], v[210:213], v[16:19]
	v_mfma_f32_16x16x32_bf16 v[44:47], v[160:163], v[176:179], v[44:47]
	v_mfma_f32_16x16x32_bf16 v[36:39], v[168:171], v[176:179], v[36:39]
	v_mfma_f32_16x16x32_bf16 v[28:31], v[160:163], v[184:187], v[28:31]
	v_mfma_f32_16x16x32_bf16 v[20:23], v[168:171], v[184:187], v[20:23]
	v_mfma_f32_16x16x32_bf16 v[12:15], v[160:163], v[192:195], v[12:15]
	v_mfma_f32_16x16x32_bf16 v[8:11], v[168:171], v[192:195], v[8:11]
	v_mfma_f32_16x16x32_bf16 v[4:7], v[160:163], v[200:203], v[4:7]
	v_mfma_f32_16x16x32_bf16 v[0:3], v[168:171], v[200:203], v[0:3]
	v_mfma_f32_16x16x32_bf16 v[44:47], v[164:167], v[180:183], v[44:47]
	v_mfma_f32_16x16x32_bf16 v[36:39], v[172:175], v[180:183], v[36:39]
	v_mfma_f32_16x16x32_bf16 v[28:31], v[164:167], v[188:191], v[28:31]
	v_mfma_f32_16x16x32_bf16 v[20:23], v[172:175], v[188:191], v[20:23]
	v_mfma_f32_16x16x32_bf16 v[12:15], v[164:167], v[196:199], v[12:15]
	v_mfma_f32_16x16x32_bf16 v[8:11], v[172:175], v[196:199], v[8:11]
	v_mfma_f32_16x16x32_bf16 v[4:7], v[164:167], v[210:213], v[4:7]
	v_mfma_f32_16x16x32_bf16 v[0:3], v[172:175], v[210:213], v[0:3]
	s_setprio 0
	s_barrier
	s_add_u32 s58, s58, 0x100
	s_addc_u32 s59, s59, 0
	s_cmp_ge_i32 s60, s46
	s_mov_b64 s[26:27], s[28:29]
	s_mov_b32 s30, s60
	s_cbranch_scc0 .LBB0_352
;     __device__ __forceinline__ void operator()(const Acc& acc, const Unit& u, int wr, int wc, int fr, int fq) const {
;     ...
;                 for (int bj = 0; bj < 2; ++bj) {
;                     const size_t off = (size_t)row * D + colb + bj * 128;
;                     const f32x4 h0 = hv[m][bj][0] + acc[ai][bj][m][0] * scale, h1 = hv[m][bj][1] + acc[ai][bj][m][1] * scale;
	v_pk_mul_f32 v[178:179], v[126:127], 0.5 op_sel_hi:[1,0]
	v_pk_mul_f32 v[180:181], v[124:125], 0.5 op_sel_hi:[1,0]
	v_pk_mul_f32 v[182:183], v[122:123], 0.5 op_sel_hi:[1,0]
	v_pk_mul_f32 v[184:185], v[120:121], 0.5 op_sel_hi:[1,0]
	v_pk_mul_f32 v[192:193], v[110:111], 0.5 op_sel_hi:[1,0]
	v_pk_mul_f32 v[190:191], v[108:109], 0.5 op_sel_hi:[1,0]
	v_pk_mul_f32 v[188:189], v[102:103], 0.5 op_sel_hi:[1,0]
	v_pk_mul_f32 v[186:187], v[100:101], 0.5 op_sel_hi:[1,0]
	v_pk_mul_f32 v[176:177], v[118:119], 0.5 op_sel_hi:[1,0]
	v_pk_mul_f32 v[174:175], v[116:117], 0.5 op_sel_hi:[1,0]
	v_pk_mul_f32 v[172:173], v[114:115], 0.5 op_sel_hi:[1,0]
	v_pk_mul_f32 v[170:171], v[112:113], 0.5 op_sel_hi:[1,0]
	v_pk_mul_f32 v[168:169], v[94:95], 0.5 op_sel_hi:[1,0]
	v_pk_mul_f32 v[166:167], v[92:93], 0.5 op_sel_hi:[1,0]
	v_pk_mul_f32 v[164:165], v[86:87], 0.5 op_sel_hi:[1,0]
	v_pk_mul_f32 v[162:163], v[84:85], 0.5 op_sel_hi:[1,0]
	v_pk_mul_f32 v[160:161], v[106:107], 0.5 op_sel_hi:[1,0]
	v_pk_mul_f32 v[158:159], v[104:105], 0.5 op_sel_hi:[1,0]
	v_pk_mul_f32 v[156:157], v[98:99], 0.5 op_sel_hi:[1,0]
	v_pk_mul_f32 v[154:155], v[96:97], 0.5 op_sel_hi:[1,0]
	v_pk_mul_f32 v[152:153], v[78:79], 0.5 op_sel_hi:[1,0]
	v_pk_mul_f32 v[150:151], v[76:77], 0.5 op_sel_hi:[1,0]
	v_pk_mul_f32 v[148:149], v[74:75], 0.5 op_sel_hi:[1,0]
	v_pk_mul_f32 v[146:147], v[72:73], 0.5 op_sel_hi:[1,0]
	v_pk_mul_f32 v[144:145], v[90:91], 0.5 op_sel_hi:[1,0]
	v_pk_mul_f32 v[126:127], v[88:89], 0.5 op_sel_hi:[1,0]
	v_pk_mul_f32 v[124:125], v[82:83], 0.5 op_sel_hi:[1,0]
	v_pk_mul_f32 v[122:123], v[80:81], 0.5 op_sel_hi:[1,0]
	v_pk_mul_f32 v[120:121], v[70:71], 0.5 op_sel_hi:[1,0]
	v_pk_mul_f32 v[118:119], v[68:69], 0.5 op_sel_hi:[1,0]
	v_pk_mul_f32 v[116:117], v[66:67], 0.5 op_sel_hi:[1,0]
	v_pk_mul_f32 v[114:115], v[64:65], 0.5 op_sel_hi:[1,0]
	v_pk_mul_f32 v[96:97], v[62:63], 0.5 op_sel_hi:[1,0]
	v_pk_mul_f32 v[98:99], v[60:61], 0.5 op_sel_hi:[1,0]
	v_pk_mul_f32 v[100:101], v[58:59], 0.5 op_sel_hi:[1,0]
	v_pk_mul_f32 v[102:103], v[56:57], 0.5 op_sel_hi:[1,0]
	v_pk_mul_f32 v[110:111], v[46:47], 0.5 op_sel_hi:[1,0]
	v_pk_mul_f32 v[108:109], v[44:45], 0.5 op_sel_hi:[1,0]
	v_pk_mul_f32 v[106:107], v[38:39], 0.5 op_sel_hi:[1,0]
	v_pk_mul_f32 v[104:105], v[36:37], 0.5 op_sel_hi:[1,0]
	v_pk_mul_f32 v[94:95], v[54:55], 0.5 op_sel_hi:[1,0]
	v_pk_mul_f32 v[92:93], v[52:53], 0.5 op_sel_hi:[1,0]
	v_pk_mul_f32 v[90:91], v[50:51], 0.5 op_sel_hi:[1,0]
	v_pk_mul_f32 v[88:89], v[48:49], 0.5 op_sel_hi:[1,0]
	v_pk_mul_f32 v[86:87], v[30:31], 0.5 op_sel_hi:[1,0]
	v_pk_mul_f32 v[84:85], v[28:29], 0.5 op_sel_hi:[1,0]
	v_pk_mul_f32 v[82:83], v[22:23], 0.5 op_sel_hi:[1,0]
	v_pk_mul_f32 v[80:81], v[20:21], 0.5 op_sel_hi:[1,0]
	v_pk_mul_f32 v[78:79], v[42:43], 0.5 op_sel_hi:[1,0]
	v_pk_mul_f32 v[76:77], v[40:41], 0.5 op_sel_hi:[1,0]
	v_pk_mul_f32 v[74:75], v[34:35], 0.5 op_sel_hi:[1,0]
	v_pk_mul_f32 v[72:73], v[32:33], 0.5 op_sel_hi:[1,0]
	v_pk_mul_f32 v[70:71], v[14:15], 0.5 op_sel_hi:[1,0]
	v_pk_mul_f32 v[68:69], v[12:13], 0.5 op_sel_hi:[1,0]
	v_pk_mul_f32 v[66:67], v[10:11], 0.5 op_sel_hi:[1,0]
	v_pk_mul_f32 v[64:65], v[8:9], 0.5 op_sel_hi:[1,0]
	v_pk_mul_f32 v[62:63], v[26:27], 0.5 op_sel_hi:[1,0]
	v_pk_mul_f32 v[60:61], v[24:25], 0.5 op_sel_hi:[1,0]
	v_pk_mul_f32 v[58:59], v[18:19], 0.5 op_sel_hi:[1,0]
	v_pk_mul_f32 v[56:57], v[16:17], 0.5 op_sel_hi:[1,0]
	v_pk_mul_f32 v[54:55], v[6:7], 0.5 op_sel_hi:[1,0]
	v_pk_mul_f32 v[52:53], v[4:5], 0.5 op_sel_hi:[1,0]
	v_pk_mul_f32 v[50:51], v[2:3], 0.5 op_sel_hi:[1,0]
	v_pk_mul_f32 v[48:49], v[0:1], 0.5 op_sel_hi:[1,0]

; #define LAS __attribute__((address_space(3)))
; #define PG8_STAGE(bufoff, gbase, voff) do { _Pragma("unroll") for (int _i = 0; _i < 2; ++_i) \
;         __builtin_amdgcn_global_load_lds((const unsigned*)((const char*)(gbase) + (voff)[_i]), (LAS unsigned*)(lds + (bufoff) + ldsw + _i * 8192), 16, 0, 0); } while (0)
; #define PG8_LDA(dst, b, h) do { _Pragma("unroll") for (int m = 0; m < 4; ++m) _Pragma("unroll") for (int k = 0; k < 2; ++k) dst[m][k] = *(const LAS bf16x8*)(lds + PG8_SA(b, h) + aoff + m * 2048 + k * 1024); } while (0)
; #define PG8_LDB(dst, b, h) do { _Pragma("unroll") for (int n = 0; n < 2; ++n) _Pragma("unroll") for (int k = 0; k < 2; ++k) dst[n][k] = *(const LAS bf16x8*)(lds + PG8_SB(b, h) + boff + n * 2048 + k * 1024); } while (0)
; #define PG8_WAIT_V(n) asm volatile("s_waitcnt vmcnt(" #n ")" ::: "memory")
; #define PG8_WAIT_L(n) asm volatile("s_waitcnt lgkmcnt(" #n ")" ::: "memory")
; #define PG8_BAR __builtin_amdgcn_s_barrier()
; template <class Epi>
; __device__ __forceinline__ void gemm_phase(LAS unsigned char* lds, const int tid, const Gemm g, const StaticOrder& S, const Epi& E) {
;     ...
;             const bool last = (t == nt - 2);
;             const char* a1 = cA + (size_t)(t + 1) * kstep;
;             const char* a2 = last ? nA : cA + (size_t)(t + 2) * kstep; const char* b2 = last ? nB : cB + (size_t)(t + 2) * kstep;
;             const char* a3 = a2 + kstep; const char* b3 = b2 + kstep;
;             if constexpr (Epi::SS_LDS) { if (last) {
;                 const char* sp = (const char*)E.ss + (size_t)cur.pm * (256 * 64) + (size_t)tid * 16;
;                 __builtin_amdgcn_global_load_lds((const unsigned*)sp, (LAS unsigned*)(lds + RS_OFF + ldsw), 16, 0, 0);
;                 __builtin_amdgcn_global_load_lds((const unsigned*)(sp + 8192), (LAS unsigned*)(lds + RS_OFF + 8192 + ldsw), 16, 0, 0); } }
;     ...
;             PG8_LDB(B0, 0, 0); PG8_LDB(B1, 0, 1); PG8_SCHED; PG8_LDA(At, 0, 0); PG8_STAGE(PG8_SA(1, 1), a1 + hstepA, voffA);
;             PG8_WAIT_V(8); PG8_WAIT_L(0); PG8_BAR; PG8_MMA(0, 0, At, B0); PG8_MMA(0, 1, At, B1); PG8_BAR; PG8_SCHED;
;             PG8_LDA(At, 0, 1); PG8_STAGE(PG8_SB(0, 0), b2, voffB); PG8_STAGE(PG8_SB(0, 1), b2 + hstepB, voffB); PG8_STAGE(PG8_SA(0, 0), a2, voffA);
;             PG8_WAIT_V(8); PG8_WAIT_L(0); PG8_BAR; PG8_MMA(1, 0, At, B0); PG8_MMA(1, 1, At, B1); PG8_BAR; PG8_SCHED;
.LBB0_442:
	v_add_u32_e32 v136, s61, v171
	ds_read_b128 v[154:157], v136
	ds_read_b128 v[158:161], v136 offset:1024
	ds_read_b128 v[162:165], v136 offset:2048
	ds_read_b128 v[166:169], v136 offset:3072
	v_add_u32_e32 v136, s62, v171
	ds_read_b128 v[176:179], v136
	ds_read_b128 v[180:183], v136 offset:1024
	ds_read_b128 v[184:187], v136 offset:2048
	ds_read_b128 v[188:191], v136 offset:3072
	s_add_i32 s68, s68, 2
	s_add_u32 s40, s36, 0xfffc0080
	s_addc_u32 s41, s37, -1
	s_and_b64 s[38:39], s[38:39], exec
	s_cselect_b32 s41, s4, s41
	s_cselect_b32 s40, s25, s40
	s_cselect_b32 s39, s27, s67
	s_cselect_b32 s38, s66, s35
	v_lshl_add_u64 v[224:225], s[36:37], 0, v[144:145]
	s_add_i32 m0, s50, 0xc000
	ds_read_b128 v[192:195], v173
	ds_read_b128 v[196:199], v173 offset:1024
	ds_read_b128 v[200:203], v173 offset:2048
	ds_read_b128 v[204:207], v173 offset:3072
	ds_read_b128 v[208:211], v173 offset:4096
	ds_read_b128 v[212:215], v173 offset:5120
	ds_read_b128 v[216:219], v173 offset:6144
	ds_read_b128 v[220:223], v173 offset:7168
	global_load_lds_dwordx4 v[224:225], off
	v_lshl_add_u64 v[224:225], s[36:37], 0, v[142:143]
	s_add_i32 m0, s50, 0xe000
	s_nop 0
	global_load_lds_dwordx4 v[224:225], off
	s_waitcnt vmcnt(8)
	s_waitcnt lgkmcnt(0)
	s_barrier
	s_setprio 1
	v_mfma_f32_16x16x32_bf16 v[124:127], v[154:157], v[192:195], v[124:127]
	v_mfma_f32_16x16x32_bf16 v[120:123], v[162:165], v[192:195], v[120:123]
	v_mfma_f32_16x16x32_bf16 v[108:111], v[154:157], v[200:203], v[108:111]
	v_mfma_f32_16x16x32_bf16 v[104:107], v[162:165], v[200:203], v[104:107]
	v_mfma_f32_16x16x32_bf16 v[92:95], v[154:157], v[208:211], v[92:95]
	v_mfma_f32_16x16x32_bf16 v[88:91], v[162:165], v[208:211], v[88:91]
	v_mfma_f32_16x16x32_bf16 v[76:79], v[154:157], v[216:219], v[76:79]
	v_mfma_f32_16x16x32_bf16 v[72:75], v[162:165], v[216:219], v[72:75]
	v_mfma_f32_16x16x32_bf16 v[124:127], v[158:161], v[196:199], v[124:127]
	v_mfma_f32_16x16x32_bf16 v[120:123], v[166:169], v[196:199], v[120:123]
	v_mfma_f32_16x16x32_bf16 v[108:111], v[158:161], v[204:207], v[108:111]
	v_mfma_f32_16x16x32_bf16 v[104:107], v[166:169], v[204:207], v[104:107]
	v_mfma_f32_16x16x32_bf16 v[92:95], v[158:161], v[212:215], v[92:95]
	v_mfma_f32_16x16x32_bf16 v[88:91], v[166:169], v[212:215], v[88:91]
	v_mfma_f32_16x16x32_bf16 v[76:79], v[158:161], v[220:223], v[76:79]
	v_mfma_f32_16x16x32_bf16 v[72:75], v[166:169], v[220:223], v[72:75]
	v_mfma_f32_16x16x32_bf16 v[116:119], v[176:179], v[192:195], v[116:119]
	v_mfma_f32_16x16x32_bf16 v[112:115], v[184:187], v[192:195], v[112:115]
	v_mfma_f32_16x16x32_bf16 v[100:103], v[176:179], v[200:203], v[100:103]
	v_mfma_f32_16x16x32_bf16 v[96:99], v[184:187], v[200:203], v[96:99]
	v_mfma_f32_16x16x32_bf16 v[84:87], v[176:179], v[208:211], v[84:87]
	v_mfma_f32_16x16x32_bf16 v[80:83], v[184:187], v[208:211], v[80:83]
	v_mfma_f32_16x16x32_bf16 v[68:71], v[176:179], v[216:219], v[68:71]
	v_mfma_f32_16x16x32_bf16 v[64:67], v[184:187], v[216:219], v[64:67]
	v_mfma_f32_16x16x32_bf16 v[116:119], v[180:183], v[196:199], v[116:119]
	v_mfma_f32_16x16x32_bf16 v[112:115], v[188:191], v[196:199], v[112:115]
	v_mfma_f32_16x16x32_bf16 v[100:103], v[180:183], v[204:207], v[100:103]
	v_mfma_f32_16x16x32_bf16 v[96:99], v[188:191], v[204:207], v[96:99]
	v_mfma_f32_16x16x32_bf16 v[84:87], v[180:183], v[212:215], v[84:87]
	v_mfma_f32_16x16x32_bf16 v[80:83], v[188:191], v[212:215], v[80:83]
	v_mfma_f32_16x16x32_bf16 v[68:71], v[180:183], v[220:223], v[68:71]
	v_mfma_f32_16x16x32_bf16 v[64:67], v[188:191], v[220:223], v[64:67]
	s_setprio 0
	s_barrier
	s_add_i32 s69, s61, s47
	v_lshl_add_u64 v[224:225], s[38:39], 0, v[132:133]
	s_mov_b32 m0, s69
	ds_read_b128 v[192:195], v173 offset:16384
	ds_read_b128 v[196:199], v173 offset:17408
	ds_read_b128 v[200:203], v173 offset:18432
	ds_read_b128 v[204:207], v173 offset:19456
	ds_read_b128 v[208:211], v173 offset:20480
	ds_read_b128 v[212:215], v173 offset:21504
	ds_read_b128 v[216:219], v173 offset:22528
	ds_read_b128 v[220:223], v173 offset:23552
	global_load_lds_dwordx4 v[224:225], off
	s_add_i32 m0, s69, 0x2000
	s_add_u32 s70, s38, 0x40000
	v_lshl_add_u64 v[226:227], s[38:39], 0, v[128:129]
	s_addc_u32 s71, s39, 0
	s_add_i32 s69, s62, s47
	global_load_lds_dwordx4 v[226:227], off
	v_lshl_add_u64 v[228:229], s[70:71], 0, v[132:133]
	s_mov_b32 m0, s69
	v_lshl_add_u64 v[230:231], s[40:41], 0, v[130:131]
	global_load_lds_dwordx4 v[228:229], off
	v_lshl_add_u64 v[228:229], s[70:71], 0, v[128:129]
	s_add_i32 m0, s69, 0x2000
	s_nop 0
	global_load_lds_dwordx4 v[228:229], off
	v_lshl_add_u64 v[228:229], s[40:41], 0, v[134:135]
	s_mov_b32 m0, s50
	s_nop 0
	global_load_lds_dwordx4 v[228:229], off
	s_mov_b32 m0, s51
	s_nop 0
	global_load_lds_dwordx4 v[230:231], off
	s_waitcnt vmcnt(8)
	s_waitcnt lgkmcnt(0)
	s_barrier
; #define PG8_STAGE(bufoff, gbase, voff) do { _Pragma("unroll") for (int _i = 0; _i < 2; ++_i) \
;         __builtin_amdgcn_global_load_lds((const unsigned*)((const char*)(gbase) + (voff)[_i]), (LAS unsigned*)(lds + (bufoff) + ldsw + _i * 8192), 16, 0, 0); } while (0)
; #define PG8_LDA(dst, b, h) do { _Pragma("unroll") for (int m = 0; m < 4; ++m) _Pragma("unroll") for (int k = 0; k < 2; ++k) dst[m][k] = *(const LAS bf16x8*)(lds + PG8_SA(b, h) + aoff + m * 2048 + k * 1024); } while (0)
; #define PG8_LDB(dst, b, h) do { _Pragma("unroll") for (int n = 0; n < 2; ++n) _Pragma("unroll") for (int k = 0; k < 2; ++k) dst[n][k] = *(const LAS bf16x8*)(lds + PG8_SB(b, h) + boff + n * 2048 + k * 1024); } while (0)
; #define PG8_MMA(ai, bj, At, Bt) do { __builtin_amdgcn_s_setprio(1); _Pragma("unroll") for (int m = 0; m < 4; ++m) _Pragma("unroll") for (int n = 0; n < 2; ++n) _Pragma("unroll") for (int k = 0; k < 2; ++k) \
;         acc[ai][bj][m][n] = __builtin_amdgcn_mfma_f32_16x16x32_bf16(Bt[n][k], At[m][k], acc[ai][bj][m][n], 0, 0, 0); __builtin_amdgcn_s_setprio(0); } while (0)
; #define PG8_WAIT_V(n) asm volatile("s_waitcnt vmcnt(" #n ")" ::: "memory")
; #define PG8_WAIT_L(n) asm volatile("s_waitcnt lgkmcnt(" #n ")" ::: "memory")
; #define PG8_BAR __builtin_amdgcn_s_barrier()
; #define PG8_SCHED __builtin_amdgcn_sched_barrier(0)
; template <class Epi>
; __device__ __forceinline__ void gemm_phase(LAS unsigned char* lds, const int tid, const Gemm g, const StaticOrder& S, const Epi& E) {
;     ...
;             PG8_WAIT_V(8); PG8_WAIT_L(0); PG8_BAR; PG8_MMA(1, 0, At, B0); PG8_MMA(1, 1, At, B1); PG8_BAR; PG8_SCHED;
;             PG8_LDB(B0, 1, 0); PG8_LDB(B1, 1, 1); PG8_SCHED; PG8_LDA(At, 1, 0); PG8_STAGE(PG8_SA(0, 1), a2 + hstepA, voffA);
;             PG8_WAIT_V(8); PG8_WAIT_L(0); PG8_BAR; PG8_MMA(0, 0, At, B0); PG8_MMA(0, 1, At, B1); PG8_BAR; PG8_SCHED;
	s_setprio 1
	v_mfma_f32_16x16x32_bf16 v[60:63], v[154:157], v[192:195], v[60:63]
	v_mfma_f32_16x16x32_bf16 v[56:59], v[162:165], v[192:195], v[56:59]
	v_mfma_f32_16x16x32_bf16 v[44:47], v[154:157], v[200:203], v[44:47]
	v_mfma_f32_16x16x32_bf16 v[40:43], v[162:165], v[200:203], v[40:43]
	v_mfma_f32_16x16x32_bf16 v[28:31], v[154:157], v[208:211], v[28:31]
	v_mfma_f32_16x16x32_bf16 v[24:27], v[162:165], v[208:211], v[24:27]
	v_mfma_f32_16x16x32_bf16 v[12:15], v[154:157], v[216:219], v[12:15]
	v_mfma_f32_16x16x32_bf16 v[8:11], v[162:165], v[216:219], v[8:11]
	v_mfma_f32_16x16x32_bf16 v[60:63], v[158:161], v[196:199], v[60:63]
	v_mfma_f32_16x16x32_bf16 v[56:59], v[166:169], v[196:199], v[56:59]
	v_mfma_f32_16x16x32_bf16 v[44:47], v[158:161], v[204:207], v[44:47]
	v_mfma_f32_16x16x32_bf16 v[40:43], v[166:169], v[204:207], v[40:43]
	v_mfma_f32_16x16x32_bf16 v[28:31], v[158:161], v[212:215], v[28:31]
	v_mfma_f32_16x16x32_bf16 v[24:27], v[166:169], v[212:215], v[24:27]
	v_mfma_f32_16x16x32_bf16 v[12:15], v[158:161], v[220:223], v[12:15]
	v_mfma_f32_16x16x32_bf16 v[8:11], v[166:169], v[220:223], v[8:11]
	v_mfma_f32_16x16x32_bf16 v[52:55], v[176:179], v[192:195], v[52:55]
	v_mfma_f32_16x16x32_bf16 v[48:51], v[184:187], v[192:195], v[48:51]
	v_mfma_f32_16x16x32_bf16 v[36:39], v[176:179], v[200:203], v[36:39]
	v_mfma_f32_16x16x32_bf16 v[32:35], v[184:187], v[200:203], v[32:35]
	v_mfma_f32_16x16x32_bf16 v[20:23], v[176:179], v[208:211], v[20:23]
	v_mfma_f32_16x16x32_bf16 v[16:19], v[184:187], v[208:211], v[16:19]
	v_mfma_f32_16x16x32_bf16 v[4:7], v[176:179], v[216:219], v[4:7]
	v_mfma_f32_16x16x32_bf16 v[0:3], v[184:187], v[216:219], v[0:3]
	v_mfma_f32_16x16x32_bf16 v[52:55], v[180:183], v[196:199], v[52:55]
	v_mfma_f32_16x16x32_bf16 v[48:51], v[188:191], v[196:199], v[48:51]
	v_mfma_f32_16x16x32_bf16 v[36:39], v[180:183], v[204:207], v[36:39]
	v_mfma_f32_16x16x32_bf16 v[32:35], v[188:191], v[204:207], v[32:35]
	v_mfma_f32_16x16x32_bf16 v[20:23], v[180:183], v[212:215], v[20:23]
	v_mfma_f32_16x16x32_bf16 v[16:19], v[188:191], v[212:215], v[16:19]
	v_mfma_f32_16x16x32_bf16 v[4:7], v[180:183], v[220:223], v[4:7]
	v_mfma_f32_16x16x32_bf16 v[0:3], v[188:191], v[220:223], v[0:3]
	s_setprio 0
	s_barrier
	s_add_i32 s69, 0, 0x18000
	v_add_u32_e32 v136, s69, v171
	s_add_i32 s70, 0, 0x1c000
	ds_read_b128 v[154:157], v136
	ds_read_b128 v[158:161], v136 offset:1024
	ds_read_b128 v[162:165], v136 offset:2048
	ds_read_b128 v[166:169], v136 offset:3072
	v_add_u32_e32 v136, s70, v171
	ds_read_b128 v[176:179], v136
	ds_read_b128 v[180:183], v136 offset:1024
	ds_read_b128 v[184:187], v136 offset:2048
	ds_read_b128 v[188:191], v136 offset:3072
	s_add_u32 s40, s40, 0x40000
	s_addc_u32 s41, s41, 0
	s_mov_b32 m0, s52
	v_lshl_add_u64 v[232:233], s[40:41], 0, v[134:135]
	ds_read_b128 v[192:195], v173 offset:32768
	ds_read_b128 v[196:199], v173 offset:33792
	ds_read_b128 v[200:203], v173 offset:34816
	ds_read_b128 v[204:207], v173 offset:35840
	ds_read_b128 v[208:211], v173 offset:36864
	ds_read_b128 v[212:215], v173 offset:37888
	ds_read_b128 v[216:219], v173 offset:38912
	ds_read_b128 v[220:223], v173 offset:39936
	global_load_lds_dwordx4 v[232:233], off
	v_lshl_add_u64 v[232:233], s[40:41], 0, v[130:131]
	s_mov_b32 m0, s53
	s_nop 0
	global_load_lds_dwordx4 v[232:233], off
	s_waitcnt vmcnt(8)
	s_waitcnt lgkmcnt(0)
	s_barrier
	s_setprio 1
	v_mfma_f32_16x16x32_bf16 v[124:127], v[154:157], v[192:195], v[124:127]
	v_mfma_f32_16x16x32_bf16 v[120:123], v[162:165], v[192:195], v[120:123]
	v_mfma_f32_16x16x32_bf16 v[108:111], v[154:157], v[200:203], v[108:111]
	v_mfma_f32_16x16x32_bf16 v[104:107], v[162:165], v[200:203], v[104:107]
	v_mfma_f32_16x16x32_bf16 v[92:95], v[154:157], v[208:211], v[92:95]
	v_mfma_f32_16x16x32_bf16 v[88:91], v[162:165], v[208:211], v[88:91]
	v_mfma_f32_16x16x32_bf16 v[76:79], v[154:157], v[216:219], v[76:79]
	v_mfma_f32_16x16x32_bf16 v[72:75], v[162:165], v[216:219], v[72:75]
	v_mfma_f32_16x16x32_bf16 v[124:127], v[158:161], v[196:199], v[124:127]
	v_mfma_f32_16x16x32_bf16 v[120:123], v[166:169], v[196:199], v[120:123]
	v_mfma_f32_16x16x32_bf16 v[108:111], v[158:161], v[204:207], v[108:111]
	v_mfma_f32_16x16x32_bf16 v[104:107], v[166:169], v[204:207], v[104:107]
	v_mfma_f32_16x16x32_bf16 v[92:95], v[158:161], v[212:215], v[92:95]
	v_mfma_f32_16x16x32_bf16 v[88:91], v[166:169], v[212:215], v[88:91]
	v_mfma_f32_16x16x32_bf16 v[76:79], v[158:161], v[220:223], v[76:79]
	v_mfma_f32_16x16x32_bf16 v[72:75], v[166:169], v[220:223], v[72:75]
	v_mfma_f32_16x16x32_bf16 v[116:119], v[176:179], v[192:195], v[116:119]
	v_mfma_f32_16x16x32_bf16 v[112:115], v[184:187], v[192:195], v[112:115]
	v_mfma_f32_16x16x32_bf16 v[100:103], v[176:179], v[200:203], v[100:103]
	v_mfma_f32_16x16x32_bf16 v[96:99], v[184:187], v[200:203], v[96:99]
	v_mfma_f32_16x16x32_bf16 v[84:87], v[176:179], v[208:211], v[84:87]
	v_mfma_f32_16x16x32_bf16 v[80:83], v[184:187], v[208:211], v[80:83]
	v_mfma_f32_16x16x32_bf16 v[68:71], v[176:179], v[216:219], v[68:71]
	v_mfma_f32_16x16x32_bf16 v[64:67], v[184:187], v[216:219], v[64:67]
	v_mfma_f32_16x16x32_bf16 v[116:119], v[180:183], v[196:199], v[116:119]
	v_mfma_f32_16x16x32_bf16 v[112:115], v[188:191], v[196:199], v[112:115]
	v_mfma_f32_16x16x32_bf16 v[100:103], v[180:183], v[204:207], v[100:103]
	v_mfma_f32_16x16x32_bf16 v[96:99], v[188:191], v[204:207], v[96:99]
	v_mfma_f32_16x16x32_bf16 v[84:87], v[180:183], v[212:215], v[84:87]
	v_mfma_f32_16x16x32_bf16 v[80:83], v[188:191], v[212:215], v[80:83]
	v_mfma_f32_16x16x32_bf16 v[68:71], v[180:183], v[220:223], v[68:71]
	v_mfma_f32_16x16x32_bf16 v[64:67], v[188:191], v[220:223], v[64:67]
	s_setprio 0
	s_barrier
; #define PG8_STAGE(bufoff, gbase, voff) do { _Pragma("unroll") for (int _i = 0; _i < 2; ++_i) \
;         __builtin_amdgcn_global_load_lds((const unsigned*)((const char*)(gbase) + (voff)[_i]), (LAS unsigned*)(lds + (bufoff) + ldsw + _i * 8192), 16, 0, 0); } while (0)
; #define PG8_LDA(dst, b, h) do { _Pragma("unroll") for (int m = 0; m < 4; ++m) _Pragma("unroll") for (int k = 0; k < 2; ++k) dst[m][k] = *(const LAS bf16x8*)(lds + PG8_SA(b, h) + aoff + m * 2048 + k * 1024); } while (0)
; #define PG8_MMA(ai, bj, At, Bt) do { __builtin_amdgcn_s_setprio(1); _Pragma("unroll") for (int m = 0; m < 4; ++m) _Pragma("unroll") for (int n = 0; n < 2; ++n) _Pragma("unroll") for (int k = 0; k < 2; ++k) \
;         acc[ai][bj][m][n] = __builtin_amdgcn_mfma_f32_16x16x32_bf16(Bt[n][k], At[m][k], acc[ai][bj][m][n], 0, 0, 0); __builtin_amdgcn_s_setprio(0); } while (0)
; #define PG8_WAIT_V(n) asm volatile("s_waitcnt vmcnt(" #n ")" ::: "memory")
; #define PG8_WAIT_L(n) asm volatile("s_waitcnt lgkmcnt(" #n ")" ::: "memory")
; #define PG8_BAR __builtin_amdgcn_s_barrier()
; #define PG8_SCHED __builtin_amdgcn_sched_barrier(0)
; template <class Epi>
; __device__ __forceinline__ void gemm_phase(LAS unsigned char* lds, const int tid, const Gemm g, const StaticOrder& S, const Epi& E) {
;     ...
;         for (int t = 0; t < nt; t += 2) {
;     ...
;             PG8_LDA(At, 1, 1); PG8_STAGE(PG8_SB(1, 0), b3, voffB); PG8_STAGE(PG8_SB(1, 1), b3 + hstepB, voffB); PG8_STAGE(PG8_SA(1, 0), a3, voffA);
;             PG8_WAIT_V(8); PG8_WAIT_L(0); PG8_BAR; PG8_MMA(1, 0, At, B0); PG8_MMA(1, 1, At, B1); PG8_BAR; PG8_SCHED;
	s_add_i32 s40, s69, s47
	v_lshl_add_u64 v[224:225], v[224:225], 0, s[16:17]
	s_mov_b32 m0, s40
	ds_read_b128 v[192:195], v173 offset:49152
	ds_read_b128 v[196:199], v173 offset:50176
	ds_read_b128 v[200:203], v173 offset:51200
	ds_read_b128 v[204:207], v173 offset:52224
	ds_read_b128 v[208:211], v173 offset:53248
	ds_read_b128 v[212:215], v173 offset:54272
	ds_read_b128 v[216:219], v173 offset:55296
	ds_read_b128 v[220:223], v173 offset:56320
	global_load_lds_dwordx4 v[224:225], off
	s_add_i32 m0, s40, 0x2000
	s_add_u32 s38, s38, 0x40080
	v_lshl_add_u64 v[224:225], v[226:227], 0, s[16:17]
	s_addc_u32 s39, s39, 0
	s_add_i32 s40, s70, s47
	global_load_lds_dwordx4 v[224:225], off
	v_lshl_add_u64 v[224:225], s[38:39], 0, v[132:133]
	s_mov_b32 m0, s40
	s_nop 0
	global_load_lds_dwordx4 v[224:225], off
	v_lshl_add_u64 v[224:225], s[38:39], 0, v[128:129]
	s_add_i32 m0, s40, 0x2000
	s_nop 0
	global_load_lds_dwordx4 v[224:225], off
	v_lshl_add_u64 v[224:225], v[228:229], 0, s[16:17]
	s_mov_b32 m0, s57
	s_nop 0
	global_load_lds_dwordx4 v[224:225], off
	v_lshl_add_u64 v[224:225], v[230:231], 0, s[16:17]
	s_mov_b32 m0, s58
	s_nop 0
	global_load_lds_dwordx4 v[224:225], off
	s_waitcnt vmcnt(8)
	s_waitcnt lgkmcnt(0)
	s_barrier
	s_setprio 1
	v_mfma_f32_16x16x32_bf16 v[60:63], v[154:157], v[192:195], v[60:63]
	v_mfma_f32_16x16x32_bf16 v[56:59], v[162:165], v[192:195], v[56:59]
	v_mfma_f32_16x16x32_bf16 v[44:47], v[154:157], v[200:203], v[44:47]
	v_mfma_f32_16x16x32_bf16 v[40:43], v[162:165], v[200:203], v[40:43]
	v_mfma_f32_16x16x32_bf16 v[28:31], v[154:157], v[208:211], v[28:31]
	v_mfma_f32_16x16x32_bf16 v[24:27], v[162:165], v[208:211], v[24:27]
	v_mfma_f32_16x16x32_bf16 v[12:15], v[154:157], v[216:219], v[12:15]
	v_mfma_f32_16x16x32_bf16 v[8:11], v[162:165], v[216:219], v[8:11]
	v_mfma_f32_16x16x32_bf16 v[60:63], v[158:161], v[196:199], v[60:63]
	v_mfma_f32_16x16x32_bf16 v[56:59], v[166:169], v[196:199], v[56:59]
	v_mfma_f32_16x16x32_bf16 v[44:47], v[158:161], v[204:207], v[44:47]
	v_mfma_f32_16x16x32_bf16 v[40:43], v[166:169], v[204:207], v[40:43]
	v_mfma_f32_16x16x32_bf16 v[28:31], v[158:161], v[212:215], v[28:31]
	v_mfma_f32_16x16x32_bf16 v[24:27], v[166:169], v[212:215], v[24:27]
	v_mfma_f32_16x16x32_bf16 v[12:15], v[158:161], v[220:223], v[12:15]
	v_mfma_f32_16x16x32_bf16 v[8:11], v[166:169], v[220:223], v[8:11]
	v_mfma_f32_16x16x32_bf16 v[52:55], v[176:179], v[192:195], v[52:55]
	v_mfma_f32_16x16x32_bf16 v[48:51], v[184:187], v[192:195], v[48:51]
	v_mfma_f32_16x16x32_bf16 v[36:39], v[176:179], v[200:203], v[36:39]
	v_mfma_f32_16x16x32_bf16 v[32:35], v[184:187], v[200:203], v[32:35]
	v_mfma_f32_16x16x32_bf16 v[20:23], v[176:179], v[208:211], v[20:23]
	v_mfma_f32_16x16x32_bf16 v[16:19], v[184:187], v[208:211], v[16:19]
	v_mfma_f32_16x16x32_bf16 v[4:7], v[176:179], v[216:219], v[4:7]
	v_mfma_f32_16x16x32_bf16 v[0:3], v[184:187], v[216:219], v[0:3]
	v_mfma_f32_16x16x32_bf16 v[52:55], v[180:183], v[196:199], v[52:55]
	v_mfma_f32_16x16x32_bf16 v[48:51], v[188:191], v[196:199], v[48:51]
	v_mfma_f32_16x16x32_bf16 v[36:39], v[180:183], v[204:207], v[36:39]
	v_mfma_f32_16x16x32_bf16 v[32:35], v[188:191], v[204:207], v[32:35]
	v_mfma_f32_16x16x32_bf16 v[20:23], v[180:183], v[212:215], v[20:23]
	v_mfma_f32_16x16x32_bf16 v[16:19], v[188:191], v[212:215], v[16:19]
	v_mfma_f32_16x16x32_bf16 v[4:7], v[180:183], v[220:223], v[4:7]
	v_mfma_f32_16x16x32_bf16 v[0:3], v[188:191], v[220:223], v[0:3]
	s_setprio 0
	s_barrier
	s_add_u32 s35, s35, 0x100
	s_addc_u32 s67, s67, 0
	s_add_u32 s36, s36, 0x100
	s_addc_u32 s37, s37, 0
	s_cmp_ge_i32 s68, s55
	s_cbranch_scc1 .LBB0_445

; #define LAS __attribute__((address_space(3)))
; #define PG8_STAGE(bufoff, gbase, voff) do { _Pragma("unroll") for (int _i = 0; _i < 2; ++_i) \
;         __builtin_amdgcn_global_load_lds((const unsigned*)((const char*)(gbase) + (voff)[_i]), (LAS unsigned*)(lds + (bufoff) + ldsw + _i * 8192), 16, 0, 0); } while (0)
; #define PG8_LDA(dst, b, h) do { _Pragma("unroll") for (int m = 0; m < 4; ++m) _Pragma("unroll") for (int k = 0; k < 2; ++k) dst[m][k] = *(const LAS bf16x8*)(lds + PG8_SA(b, h) + aoff + m * 2048 + k * 1024); } while (0)
; #define PG8_LDB(dst, b, h) do { _Pragma("unroll") for (int n = 0; n < 2; ++n) _Pragma("unroll") for (int k = 0; k < 2; ++k) dst[n][k] = *(const LAS bf16x8*)(lds + PG8_SB(b, h) + boff + n * 2048 + k * 1024); } while (0)
; #define PG8_WAIT_V(n) asm volatile("s_waitcnt vmcnt(" #n ")" ::: "memory")
; #define PG8_WAIT_L(n) asm volatile("s_waitcnt lgkmcnt(" #n ")" ::: "memory")
; #define PG8_BAR __builtin_amdgcn_s_barrier()
; template <class Epi>
; __device__ __forceinline__ void gemm_phase(LAS unsigned char* lds, const int tid, const Gemm g, const StaticOrder& S, const Epi& E) {
;     ...
;             const bool last = (t == nt - 2);
;             const char* a1 = cA + (size_t)(t + 1) * kstep;
;             const char* a2 = last ? nA : cA + (size_t)(t + 2) * kstep; const char* b2 = last ? nB : cB + (size_t)(t + 2) * kstep;
;             const char* a3 = a2 + kstep; const char* b3 = b2 + kstep;
;             if constexpr (Epi::SS_LDS) { if (last) {
;                 const char* sp = (const char*)E.ss + (size_t)cur.pm * (256 * 64) + (size_t)tid * 16;
;                 __builtin_amdgcn_global_load_lds((const unsigned*)sp, (LAS unsigned*)(lds + RS_OFF + ldsw), 16, 0, 0);
;                 __builtin_amdgcn_global_load_lds((const unsigned*)(sp + 8192), (LAS unsigned*)(lds + RS_OFF + 8192 + ldsw), 16, 0, 0); } }
;     ...
;             PG8_LDB(B0, 0, 0); PG8_LDB(B1, 0, 1); PG8_SCHED; PG8_LDA(At, 0, 0); PG8_STAGE(PG8_SA(1, 1), a1 + hstepA, voffA);
;             PG8_WAIT_V(8); PG8_WAIT_L(0); PG8_BAR; PG8_MMA(0, 0, At, B0); PG8_MMA(0, 1, At, B1); PG8_BAR; PG8_SCHED;
;             PG8_LDA(At, 0, 1); PG8_STAGE(PG8_SB(0, 0), b2, voffB); PG8_STAGE(PG8_SB(0, 1), b2 + hstepB, voffB); PG8_STAGE(PG8_SA(0, 0), a2, voffA);
;             PG8_WAIT_V(8); PG8_WAIT_L(0); PG8_BAR; PG8_MMA(1, 0, At, B0); PG8_MMA(1, 1, At, B1); PG8_BAR; PG8_SCHED;
.LBB0_728:
	ds_read_b128 v[128:131], v189
	ds_read_b128 v[132:135], v189 offset:1024
	ds_read_b128 v[136:139], v189 offset:2048
	ds_read_b128 v[140:143], v189 offset:3072
	ds_read_b128 v[144:147], v190
	ds_read_b128 v[148:151], v190 offset:1024
	ds_read_b128 v[168:171], v190 offset:2048
	ds_read_b128 v[172:175], v190 offset:3072
	s_add_i32 s60, s34, 2
	s_add_u32 s35, s30, 0xfffc0080
	s_addc_u32 s36, s31, -1
	s_cmp_eq_u32 s51, s34
	s_cselect_b32 s34, s57, s58
	s_cselect_b32 s37, s21, s36
	s_cselect_b32 s36, s23, s35
	s_cselect_b32 s35, s29, s59
	v_lshl_add_u64 v[184:185], s[30:31], 0, v[162:163]
	s_add_i32 m0, s43, 0xc000
	ds_read_b128 v[176:179], v191
	ds_read_b128 v[180:183], v191 offset:1024
	ds_read_b128 v[192:195], v191 offset:2048
	ds_read_b128 v[196:199], v191 offset:3072
	ds_read_b128 v[200:203], v191 offset:4096
	ds_read_b128 v[204:207], v191 offset:5120
	ds_read_b128 v[208:211], v191 offset:6144
	ds_read_b128 v[212:215], v191 offset:7168
	global_load_lds_dwordx4 v[184:185], off
	v_lshl_add_u64 v[184:185], s[30:31], 0, v[160:161]
	s_add_i32 m0, s43, 0xe000
	s_nop 0
	global_load_lds_dwordx4 v[184:185], off
	s_waitcnt vmcnt(8)
	s_waitcnt lgkmcnt(0)
	s_barrier
	s_setprio 1
	v_mfma_f32_16x16x32_bf16 v[120:123], v[128:131], v[176:179], v[120:123]
	v_mfma_f32_16x16x32_bf16 v[124:127], v[136:139], v[176:179], v[124:127]
	v_mfma_f32_16x16x32_bf16 v[108:111], v[128:131], v[192:195], v[108:111]
	v_mfma_f32_16x16x32_bf16 v[104:107], v[136:139], v[192:195], v[104:107]
	v_mfma_f32_16x16x32_bf16 v[92:95], v[128:131], v[200:203], v[92:95]
	v_mfma_f32_16x16x32_bf16 v[88:91], v[136:139], v[200:203], v[88:91]
	v_mfma_f32_16x16x32_bf16 v[76:79], v[128:131], v[208:211], v[76:79]
	v_mfma_f32_16x16x32_bf16 v[72:75], v[136:139], v[208:211], v[72:75]
	v_mfma_f32_16x16x32_bf16 v[120:123], v[132:135], v[180:183], v[120:123]
	v_mfma_f32_16x16x32_bf16 v[124:127], v[140:143], v[180:183], v[124:127]
	v_mfma_f32_16x16x32_bf16 v[108:111], v[132:135], v[196:199], v[108:111]
	v_mfma_f32_16x16x32_bf16 v[104:107], v[140:143], v[196:199], v[104:107]
	v_mfma_f32_16x16x32_bf16 v[92:95], v[132:135], v[204:207], v[92:95]
	v_mfma_f32_16x16x32_bf16 v[88:91], v[140:143], v[204:207], v[88:91]
	v_mfma_f32_16x16x32_bf16 v[76:79], v[132:135], v[212:215], v[76:79]
	v_mfma_f32_16x16x32_bf16 v[72:75], v[140:143], v[212:215], v[72:75]
	v_mfma_f32_16x16x32_bf16 v[116:119], v[144:147], v[176:179], v[116:119]
	v_mfma_f32_16x16x32_bf16 v[112:115], v[168:171], v[176:179], v[112:115]
	v_mfma_f32_16x16x32_bf16 v[100:103], v[144:147], v[192:195], v[100:103]
	v_mfma_f32_16x16x32_bf16 v[96:99], v[168:171], v[192:195], v[96:99]
	v_mfma_f32_16x16x32_bf16 v[84:87], v[144:147], v[200:203], v[84:87]
	v_mfma_f32_16x16x32_bf16 v[80:83], v[168:171], v[200:203], v[80:83]
	v_mfma_f32_16x16x32_bf16 v[68:71], v[144:147], v[208:211], v[68:71]
	v_mfma_f32_16x16x32_bf16 v[64:67], v[168:171], v[208:211], v[64:67]
	v_mfma_f32_16x16x32_bf16 v[116:119], v[148:151], v[180:183], v[116:119]
	v_mfma_f32_16x16x32_bf16 v[112:115], v[172:175], v[180:183], v[112:115]
	v_mfma_f32_16x16x32_bf16 v[100:103], v[148:151], v[196:199], v[100:103]
	v_mfma_f32_16x16x32_bf16 v[96:99], v[172:175], v[196:199], v[96:99]
	v_mfma_f32_16x16x32_bf16 v[84:87], v[148:151], v[204:207], v[84:87]
	v_mfma_f32_16x16x32_bf16 v[80:83], v[172:175], v[204:207], v[80:83]
	v_mfma_f32_16x16x32_bf16 v[68:71], v[148:151], v[212:215], v[68:71]
	v_mfma_f32_16x16x32_bf16 v[64:67], v[172:175], v[212:215], v[64:67]
	s_setprio 0
	s_barrier
	s_add_i32 s61, s54, s42
	v_lshl_add_u64 v[184:185], s[34:35], 0, v[154:155]
	s_mov_b32 m0, s61
	ds_read_b128 v[176:179], v191 offset:16384
	ds_read_b128 v[180:183], v191 offset:17408
	ds_read_b128 v[192:195], v191 offset:18432
	ds_read_b128 v[196:199], v191 offset:19456
	ds_read_b128 v[200:203], v191 offset:20480
	ds_read_b128 v[204:207], v191 offset:21504
	ds_read_b128 v[208:211], v191 offset:22528
	ds_read_b128 v[212:215], v191 offset:23552
	global_load_lds_dwordx4 v[184:185], off
	s_add_i32 m0, s61, 0x2000
	s_add_u32 s62, s34, 0x40000
	v_lshl_add_u64 v[216:217], s[34:35], 0, v[158:159]
	s_addc_u32 s63, s35, 0
	s_add_i32 s61, s55, s42
	global_load_lds_dwordx4 v[216:217], off
	v_lshl_add_u64 v[218:219], s[62:63], 0, v[154:155]
	s_mov_b32 m0, s61
	v_lshl_add_u64 v[220:221], s[36:37], 0, v[156:157]
	global_load_lds_dwordx4 v[218:219], off
	v_lshl_add_u64 v[218:219], s[62:63], 0, v[158:159]
	s_add_i32 m0, s61, 0x2000
	s_nop 0
	global_load_lds_dwordx4 v[218:219], off
	v_lshl_add_u64 v[218:219], s[36:37], 0, v[152:153]
	s_mov_b32 m0, s43
	s_nop 0
	global_load_lds_dwordx4 v[218:219], off
	s_mov_b32 m0, s44
	s_nop 0
	global_load_lds_dwordx4 v[220:221], off
	s_waitcnt vmcnt(8)
	s_waitcnt lgkmcnt(0)
	s_barrier
; #define PG8_STAGE(bufoff, gbase, voff) do { _Pragma("unroll") for (int _i = 0; _i < 2; ++_i) \
;         __builtin_amdgcn_global_load_lds((const unsigned*)((const char*)(gbase) + (voff)[_i]), (LAS unsigned*)(lds + (bufoff) + ldsw + _i * 8192), 16, 0, 0); } while (0)
; #define PG8_LDA(dst, b, h) do { _Pragma("unroll") for (int m = 0; m < 4; ++m) _Pragma("unroll") for (int k = 0; k < 2; ++k) dst[m][k] = *(const LAS bf16x8*)(lds + PG8_SA(b, h) + aoff + m * 2048 + k * 1024); } while (0)
; #define PG8_LDB(dst, b, h) do { _Pragma("unroll") for (int n = 0; n < 2; ++n) _Pragma("unroll") for (int k = 0; k < 2; ++k) dst[n][k] = *(const LAS bf16x8*)(lds + PG8_SB(b, h) + boff + n * 2048 + k * 1024); } while (0)
; #define PG8_MMA(ai, bj, At, Bt) do { __builtin_amdgcn_s_setprio(1); _Pragma("unroll") for (int m = 0; m < 4; ++m) _Pragma("unroll") for (int n = 0; n < 2; ++n) _Pragma("unroll") for (int k = 0; k < 2; ++k) \
;         acc[ai][bj][m][n] = __builtin_amdgcn_mfma_f32_16x16x32_bf16(Bt[n][k], At[m][k], acc[ai][bj][m][n], 0, 0, 0); __builtin_amdgcn_s_setprio(0); } while (0)
; #define PG8_WAIT_V(n) asm volatile("s_waitcnt vmcnt(" #n ")" ::: "memory")
; #define PG8_WAIT_L(n) asm volatile("s_waitcnt lgkmcnt(" #n ")" ::: "memory")
; #define PG8_BAR __builtin_amdgcn_s_barrier()
; #define PG8_SCHED __builtin_amdgcn_sched_barrier(0)
; template <class Epi>
; __device__ __forceinline__ void gemm_phase(LAS unsigned char* lds, const int tid, const Gemm g, const StaticOrder& S, const Epi& E) {
;     ...
;             PG8_WAIT_V(8); PG8_WAIT_L(0); PG8_BAR; PG8_MMA(1, 0, At, B0); PG8_MMA(1, 1, At, B1); PG8_BAR; PG8_SCHED;
;             PG8_LDB(B0, 1, 0); PG8_LDB(B1, 1, 1); PG8_SCHED; PG8_LDA(At, 1, 0); PG8_STAGE(PG8_SA(0, 1), a2 + hstepA, voffA);
;             PG8_WAIT_V(8); PG8_WAIT_L(0); PG8_BAR; PG8_MMA(0, 0, At, B0); PG8_MMA(0, 1, At, B1); PG8_BAR; PG8_SCHED;
	s_setprio 1
	v_mfma_f32_16x16x32_bf16 v[60:63], v[128:131], v[176:179], v[60:63]
	v_mfma_f32_16x16x32_bf16 v[56:59], v[136:139], v[176:179], v[56:59]
	v_mfma_f32_16x16x32_bf16 v[44:47], v[128:131], v[192:195], v[44:47]
	v_mfma_f32_16x16x32_bf16 v[40:43], v[136:139], v[192:195], v[40:43]
	v_mfma_f32_16x16x32_bf16 v[28:31], v[128:131], v[200:203], v[28:31]
	v_mfma_f32_16x16x32_bf16 v[24:27], v[136:139], v[200:203], v[24:27]
	v_mfma_f32_16x16x32_bf16 v[12:15], v[128:131], v[208:211], v[12:15]
	v_mfma_f32_16x16x32_bf16 v[8:11], v[136:139], v[208:211], v[8:11]
	v_mfma_f32_16x16x32_bf16 v[60:63], v[132:135], v[180:183], v[60:63]
	v_mfma_f32_16x16x32_bf16 v[56:59], v[140:143], v[180:183], v[56:59]
	v_mfma_f32_16x16x32_bf16 v[44:47], v[132:135], v[196:199], v[44:47]
	v_mfma_f32_16x16x32_bf16 v[40:43], v[140:143], v[196:199], v[40:43]
	v_mfma_f32_16x16x32_bf16 v[28:31], v[132:135], v[204:207], v[28:31]
	v_mfma_f32_16x16x32_bf16 v[24:27], v[140:143], v[204:207], v[24:27]
	v_mfma_f32_16x16x32_bf16 v[12:15], v[132:135], v[212:215], v[12:15]
	v_mfma_f32_16x16x32_bf16 v[8:11], v[140:143], v[212:215], v[8:11]
	v_mfma_f32_16x16x32_bf16 v[52:55], v[144:147], v[176:179], v[52:55]
	v_mfma_f32_16x16x32_bf16 v[48:51], v[168:171], v[176:179], v[48:51]
	v_mfma_f32_16x16x32_bf16 v[36:39], v[144:147], v[192:195], v[36:39]
	v_mfma_f32_16x16x32_bf16 v[32:35], v[168:171], v[192:195], v[32:35]
	v_mfma_f32_16x16x32_bf16 v[20:23], v[144:147], v[200:203], v[20:23]
	v_mfma_f32_16x16x32_bf16 v[16:19], v[168:171], v[200:203], v[16:19]
	v_mfma_f32_16x16x32_bf16 v[4:7], v[144:147], v[208:211], v[4:7]
	v_mfma_f32_16x16x32_bf16 v[0:3], v[168:171], v[208:211], v[0:3]
	v_mfma_f32_16x16x32_bf16 v[52:55], v[148:151], v[180:183], v[52:55]
	v_mfma_f32_16x16x32_bf16 v[48:51], v[172:175], v[180:183], v[48:51]
	v_mfma_f32_16x16x32_bf16 v[36:39], v[148:151], v[196:199], v[36:39]
	v_mfma_f32_16x16x32_bf16 v[32:35], v[172:175], v[196:199], v[32:35]
	v_mfma_f32_16x16x32_bf16 v[20:23], v[148:151], v[204:207], v[20:23]
	v_mfma_f32_16x16x32_bf16 v[16:19], v[172:175], v[204:207], v[16:19]
	v_mfma_f32_16x16x32_bf16 v[4:7], v[148:151], v[212:215], v[4:7]
	v_mfma_f32_16x16x32_bf16 v[0:3], v[172:175], v[212:215], v[0:3]
	s_setprio 0
	s_barrier
	s_add_i32 s61, 0, 0x18000
	s_add_i32 s62, 0, 0x1c000
	v_add_u32_e32 v140, s61, v187
	v_add_u32_e32 v172, s62, v187
	ds_read_b128 v[128:131], v140
	ds_read_b128 v[132:135], v140 offset:1024
	ds_read_b128 v[136:139], v140 offset:2048
	ds_read_b128 v[140:143], v140 offset:3072
	ds_read_b128 v[144:147], v172
	ds_read_b128 v[148:151], v172 offset:1024
	ds_read_b128 v[168:171], v172 offset:2048
	ds_read_b128 v[172:175], v172 offset:3072
	s_add_u32 s36, s36, 0x40000
	s_addc_u32 s37, s37, 0
	s_mov_b32 m0, s45
	v_lshl_add_u64 v[222:223], s[36:37], 0, v[152:153]
	ds_read_b128 v[176:179], v191 offset:32768
	ds_read_b128 v[180:183], v191 offset:33792
	ds_read_b128 v[192:195], v191 offset:34816
	ds_read_b128 v[196:199], v191 offset:35840
	ds_read_b128 v[200:203], v191 offset:36864
	ds_read_b128 v[204:207], v191 offset:37888
	ds_read_b128 v[208:211], v191 offset:38912
	ds_read_b128 v[212:215], v191 offset:39936
	global_load_lds_dwordx4 v[222:223], off
	v_lshl_add_u64 v[222:223], s[36:37], 0, v[156:157]
	s_mov_b32 m0, s46
	s_nop 0
	global_load_lds_dwordx4 v[222:223], off
	s_waitcnt vmcnt(8)
	s_waitcnt lgkmcnt(0)
	s_barrier
	s_setprio 1
	v_mfma_f32_16x16x32_bf16 v[120:123], v[128:131], v[176:179], v[120:123]
	v_mfma_f32_16x16x32_bf16 v[124:127], v[136:139], v[176:179], v[124:127]
	v_mfma_f32_16x16x32_bf16 v[108:111], v[128:131], v[192:195], v[108:111]
	v_mfma_f32_16x16x32_bf16 v[104:107], v[136:139], v[192:195], v[104:107]
	v_mfma_f32_16x16x32_bf16 v[92:95], v[128:131], v[200:203], v[92:95]
	v_mfma_f32_16x16x32_bf16 v[88:91], v[136:139], v[200:203], v[88:91]
	v_mfma_f32_16x16x32_bf16 v[76:79], v[128:131], v[208:211], v[76:79]
	v_mfma_f32_16x16x32_bf16 v[72:75], v[136:139], v[208:211], v[72:75]
	v_mfma_f32_16x16x32_bf16 v[120:123], v[132:135], v[180:183], v[120:123]
	v_mfma_f32_16x16x32_bf16 v[124:127], v[140:143], v[180:183], v[124:127]
	v_mfma_f32_16x16x32_bf16 v[108:111], v[132:135], v[196:199], v[108:111]
	v_mfma_f32_16x16x32_bf16 v[104:107], v[140:143], v[196:199], v[104:107]
	v_mfma_f32_16x16x32_bf16 v[92:95], v[132:135], v[204:207], v[92:95]
	v_mfma_f32_16x16x32_bf16 v[88:91], v[140:143], v[204:207], v[88:91]
	v_mfma_f32_16x16x32_bf16 v[76:79], v[132:135], v[212:215], v[76:79]
	v_mfma_f32_16x16x32_bf16 v[72:75], v[140:143], v[212:215], v[72:75]
	v_mfma_f32_16x16x32_bf16 v[116:119], v[144:147], v[176:179], v[116:119]
	v_mfma_f32_16x16x32_bf16 v[112:115], v[168:171], v[176:179], v[112:115]
	v_mfma_f32_16x16x32_bf16 v[100:103], v[144:147], v[192:195], v[100:103]
	v_mfma_f32_16x16x32_bf16 v[96:99], v[168:171], v[192:195], v[96:99]
	v_mfma_f32_16x16x32_bf16 v[84:87], v[144:147], v[200:203], v[84:87]
	v_mfma_f32_16x16x32_bf16 v[80:83], v[168:171], v[200:203], v[80:83]
	v_mfma_f32_16x16x32_bf16 v[68:71], v[144:147], v[208:211], v[68:71]
	v_mfma_f32_16x16x32_bf16 v[64:67], v[168:171], v[208:211], v[64:67]
	v_mfma_f32_16x16x32_bf16 v[116:119], v[148:151], v[180:183], v[116:119]
	v_mfma_f32_16x16x32_bf16 v[112:115], v[172:175], v[180:183], v[112:115]
	v_mfma_f32_16x16x32_bf16 v[100:103], v[148:151], v[196:199], v[100:103]
	v_mfma_f32_16x16x32_bf16 v[96:99], v[172:175], v[196:199], v[96:99]
	v_mfma_f32_16x16x32_bf16 v[84:87], v[148:151], v[204:207], v[84:87]
	v_mfma_f32_16x16x32_bf16 v[80:83], v[172:175], v[204:207], v[80:83]
	v_mfma_f32_16x16x32_bf16 v[68:71], v[148:151], v[212:215], v[68:71]
	v_mfma_f32_16x16x32_bf16 v[64:67], v[172:175], v[212:215], v[64:67]
	s_setprio 0
	s_barrier
; #define PG8_STAGE(bufoff, gbase, voff) do { _Pragma("unroll") for (int _i = 0; _i < 2; ++_i) \
;         __builtin_amdgcn_global_load_lds((const unsigned*)((const char*)(gbase) + (voff)[_i]), (LAS unsigned*)(lds + (bufoff) + ldsw + _i * 8192), 16, 0, 0); } while (0)
; #define PG8_LDA(dst, b, h) do { _Pragma("unroll") for (int m = 0; m < 4; ++m) _Pragma("unroll") for (int k = 0; k < 2; ++k) dst[m][k] = *(const LAS bf16x8*)(lds + PG8_SA(b, h) + aoff + m * 2048 + k * 1024); } while (0)
; #define PG8_MMA(ai, bj, At, Bt) do { __builtin_amdgcn_s_setprio(1); _Pragma("unroll") for (int m = 0; m < 4; ++m) _Pragma("unroll") for (int n = 0; n < 2; ++n) _Pragma("unroll") for (int k = 0; k < 2; ++k) \
;         acc[ai][bj][m][n] = __builtin_amdgcn_mfma_f32_16x16x32_bf16(Bt[n][k], At[m][k], acc[ai][bj][m][n], 0, 0, 0); __builtin_amdgcn_s_setprio(0); } while (0)
; #define PG8_WAIT_V(n) asm volatile("s_waitcnt vmcnt(" #n ")" ::: "memory")
; #define PG8_WAIT_L(n) asm volatile("s_waitcnt lgkmcnt(" #n ")" ::: "memory")
; #define PG8_BAR __builtin_amdgcn_s_barrier()
; #define PG8_SCHED __builtin_amdgcn_sched_barrier(0)
; template <class Epi>
; __device__ __forceinline__ void gemm_phase(LAS unsigned char* lds, const int tid, const Gemm g, const StaticOrder& S, const Epi& E) {
;     ...
;         for (int t = 0; t < nt; t += 2) {
;     ...
;             PG8_LDA(At, 1, 1); PG8_STAGE(PG8_SB(1, 0), b3, voffB); PG8_STAGE(PG8_SB(1, 1), b3 + hstepB, voffB); PG8_STAGE(PG8_SA(1, 0), a3, voffA);
;             PG8_WAIT_V(8); PG8_WAIT_L(0); PG8_BAR; PG8_MMA(1, 0, At, B0); PG8_MMA(1, 1, At, B1); PG8_BAR; PG8_SCHED;
	s_add_i32 s36, s61, s42
	v_lshl_add_u64 v[184:185], v[184:185], 0, s[14:15]
	s_mov_b32 m0, s36
	ds_read_b128 v[176:179], v191 offset:49152
	ds_read_b128 v[180:183], v191 offset:50176
	ds_read_b128 v[192:195], v191 offset:51200
	ds_read_b128 v[196:199], v191 offset:52224
	ds_read_b128 v[200:203], v191 offset:53248
	ds_read_b128 v[204:207], v191 offset:54272
	ds_read_b128 v[208:211], v191 offset:55296
	ds_read_b128 v[212:215], v191 offset:56320
	global_load_lds_dwordx4 v[184:185], off
	s_add_i32 m0, s36, 0x2000
	s_add_u32 s34, s34, 0x40080
	v_lshl_add_u64 v[184:185], v[216:217], 0, s[14:15]
	s_addc_u32 s35, s35, 0
	s_add_i32 s36, s62, s42
	global_load_lds_dwordx4 v[184:185], off
	v_lshl_add_u64 v[184:185], s[34:35], 0, v[154:155]
	s_mov_b32 m0, s36
	s_nop 0
	global_load_lds_dwordx4 v[184:185], off
	v_lshl_add_u64 v[184:185], s[34:35], 0, v[158:159]
	s_add_i32 m0, s36, 0x2000
	s_nop 0
	global_load_lds_dwordx4 v[184:185], off
	v_lshl_add_u64 v[184:185], v[218:219], 0, s[14:15]
	s_mov_b32 m0, s49
	s_nop 0
	global_load_lds_dwordx4 v[184:185], off
	v_lshl_add_u64 v[184:185], v[220:221], 0, s[14:15]
	s_mov_b32 m0, s50
	s_nop 0
	global_load_lds_dwordx4 v[184:185], off
	s_waitcnt vmcnt(8)
	s_waitcnt lgkmcnt(0)
	s_barrier
	s_setprio 1
	v_mfma_f32_16x16x32_bf16 v[60:63], v[128:131], v[176:179], v[60:63]
	v_mfma_f32_16x16x32_bf16 v[56:59], v[136:139], v[176:179], v[56:59]
	v_mfma_f32_16x16x32_bf16 v[44:47], v[128:131], v[192:195], v[44:47]
	v_mfma_f32_16x16x32_bf16 v[40:43], v[136:139], v[192:195], v[40:43]
	v_mfma_f32_16x16x32_bf16 v[28:31], v[128:131], v[200:203], v[28:31]
	v_mfma_f32_16x16x32_bf16 v[24:27], v[136:139], v[200:203], v[24:27]
	v_mfma_f32_16x16x32_bf16 v[12:15], v[128:131], v[208:211], v[12:15]
	v_mfma_f32_16x16x32_bf16 v[8:11], v[136:139], v[208:211], v[8:11]
	v_mfma_f32_16x16x32_bf16 v[60:63], v[132:135], v[180:183], v[60:63]
	v_mfma_f32_16x16x32_bf16 v[56:59], v[140:143], v[180:183], v[56:59]
	v_mfma_f32_16x16x32_bf16 v[44:47], v[132:135], v[196:199], v[44:47]
	v_mfma_f32_16x16x32_bf16 v[40:43], v[140:143], v[196:199], v[40:43]
	v_mfma_f32_16x16x32_bf16 v[28:31], v[132:135], v[204:207], v[28:31]
	v_mfma_f32_16x16x32_bf16 v[24:27], v[140:143], v[204:207], v[24:27]
	v_mfma_f32_16x16x32_bf16 v[12:15], v[132:135], v[212:215], v[12:15]
	v_mfma_f32_16x16x32_bf16 v[8:11], v[140:143], v[212:215], v[8:11]
	v_mfma_f32_16x16x32_bf16 v[52:55], v[144:147], v[176:179], v[52:55]
	v_mfma_f32_16x16x32_bf16 v[48:51], v[168:171], v[176:179], v[48:51]
	v_mfma_f32_16x16x32_bf16 v[36:39], v[144:147], v[192:195], v[36:39]
	v_mfma_f32_16x16x32_bf16 v[32:35], v[168:171], v[192:195], v[32:35]
	v_mfma_f32_16x16x32_bf16 v[20:23], v[144:147], v[200:203], v[20:23]
	v_mfma_f32_16x16x32_bf16 v[16:19], v[168:171], v[200:203], v[16:19]
	v_mfma_f32_16x16x32_bf16 v[4:7], v[144:147], v[208:211], v[4:7]
	v_mfma_f32_16x16x32_bf16 v[0:3], v[168:171], v[208:211], v[0:3]
	v_mfma_f32_16x16x32_bf16 v[52:55], v[148:151], v[180:183], v[52:55]
	v_mfma_f32_16x16x32_bf16 v[48:51], v[172:175], v[180:183], v[48:51]
	v_mfma_f32_16x16x32_bf16 v[36:39], v[148:151], v[196:199], v[36:39]
	v_mfma_f32_16x16x32_bf16 v[32:35], v[172:175], v[196:199], v[32:35]
	v_mfma_f32_16x16x32_bf16 v[20:23], v[148:151], v[204:207], v[20:23]
	v_mfma_f32_16x16x32_bf16 v[16:19], v[172:175], v[204:207], v[16:19]
	v_mfma_f32_16x16x32_bf16 v[4:7], v[148:151], v[212:215], v[4:7]
	v_mfma_f32_16x16x32_bf16 v[0:3], v[172:175], v[212:215], v[0:3]
	s_setprio 0
	s_barrier
	s_add_u32 s58, s58, 0x100
	s_addc_u32 s59, s59, 0
	s_add_u32 s30, s30, 0x100
	s_addc_u32 s31, s31, 0
	s_cmp_ge_i32 s60, s48
	s_mov_b32 s34, s60
	s_cbranch_scc0 .LBB0_728

; #define LAS __attribute__((address_space(3)))
; #define PG8_STAGE(bufoff, gbase, voff) do { _Pragma("unroll") for (int _i = 0; _i < 2; ++_i) \
;         __builtin_amdgcn_global_load_lds((const unsigned*)((const char*)(gbase) + (voff)[_i]), (LAS unsigned*)(lds + (bufoff) + ldsw + _i * 8192), 16, 0, 0); } while (0)
; #define PG8_LDA(dst, b, h) do { _Pragma("unroll") for (int m = 0; m < 4; ++m) _Pragma("unroll") for (int k = 0; k < 2; ++k) dst[m][k] = *(const LAS bf16x8*)(lds + PG8_SA(b, h) + aoff + m * 2048 + k * 1024); } while (0)
; #define PG8_LDB(dst, b, h) do { _Pragma("unroll") for (int n = 0; n < 2; ++n) _Pragma("unroll") for (int k = 0; k < 2; ++k) dst[n][k] = *(const LAS bf16x8*)(lds + PG8_SB(b, h) + boff + n * 2048 + k * 1024); } while (0)
; #define PG8_WAIT_V(n) asm volatile("s_waitcnt vmcnt(" #n ")" ::: "memory")
; #define PG8_WAIT_L(n) asm volatile("s_waitcnt lgkmcnt(" #n ")" ::: "memory")
; #define PG8_BAR __builtin_amdgcn_s_barrier()
; template <class Epi>
; __device__ __forceinline__ void gemm_phase(LAS unsigned char* lds, const int tid, const Gemm g, const StaticOrder& S, const Epi& E) {
;     ...
;             const bool last = (t == nt - 2);
;             const char* a1 = cA + (size_t)(t + 1) * kstep;
;             const char* a2 = last ? nA : cA + (size_t)(t + 2) * kstep; const char* b2 = last ? nB : cB + (size_t)(t + 2) * kstep;
;             const char* a3 = a2 + kstep; const char* b3 = b2 + kstep;
;             if constexpr (Epi::SS_LDS) { if (last) {
;                 const char* sp = (const char*)E.ss + (size_t)cur.pm * (256 * 64) + (size_t)tid * 16;
;                 __builtin_amdgcn_global_load_lds((const unsigned*)sp, (LAS unsigned*)(lds + RS_OFF + ldsw), 16, 0, 0);
;                 __builtin_amdgcn_global_load_lds((const unsigned*)(sp + 8192), (LAS unsigned*)(lds + RS_OFF + 8192 + ldsw), 16, 0, 0); } }
;     ...
;             PG8_LDB(B0, 0, 0); PG8_LDB(B1, 0, 1); PG8_SCHED; PG8_LDA(At, 0, 0); PG8_STAGE(PG8_SA(1, 1), a1 + hstepA, voffA);
;             PG8_WAIT_V(8); PG8_WAIT_L(0); PG8_BAR; PG8_MMA(0, 0, At, B0); PG8_MMA(0, 1, At, B1); PG8_BAR; PG8_SCHED;
;             PG8_LDA(At, 0, 1); PG8_STAGE(PG8_SB(0, 0), b2, voffB); PG8_STAGE(PG8_SB(0, 1), b2 + hstepB, voffB); PG8_STAGE(PG8_SA(0, 0), a2, voffA);
;             PG8_WAIT_V(8); PG8_WAIT_L(0); PG8_BAR; PG8_MMA(1, 0, At, B0); PG8_MMA(1, 1, At, B1); PG8_BAR; PG8_SCHED;
.LBB0_906:
	ds_read_b128 v[144:147], v189
	ds_read_b128 v[148:151], v189 offset:1024
	ds_read_b128 v[152:155], v189 offset:2048
	ds_read_b128 v[156:159], v189 offset:3072
	ds_read_b128 v[160:163], v190
	ds_read_b128 v[164:167], v190 offset:1024
	ds_read_b128 v[168:171], v190 offset:2048
	ds_read_b128 v[172:175], v190 offset:3072
	s_add_i32 s58, s28, 2
	s_add_u32 s26, s24, 0x100
	s_addc_u32 s27, s25, 0
	s_cmp_eq_u32 s47, s28
	s_cselect_b32 s28, s22, s56
	s_cselect_b32 s31, s7, s27
	s_cselect_b32 s30, s6, s26
	s_cselect_b32 s29, s23, s57
	v_lshl_add_u64 v[184:185], s[24:25], 0, v[138:139]
	s_add_i32 m0, s39, 0xc000
	ds_read_b128 v[176:179], v191
	ds_read_b128 v[180:183], v191 offset:1024
	ds_read_b128 v[192:195], v191 offset:2048
	ds_read_b128 v[196:199], v191 offset:3072
	ds_read_b128 v[200:203], v191 offset:4096
	ds_read_b128 v[204:207], v191 offset:5120
	ds_read_b128 v[208:211], v191 offset:6144
	ds_read_b128 v[212:215], v191 offset:7168
	global_load_lds_dwordx4 v[184:185], off
	v_lshl_add_u64 v[184:185], s[24:25], 0, v[136:137]
	s_add_i32 m0, s39, 0xe000
	s_nop 0
	global_load_lds_dwordx4 v[184:185], off
	s_waitcnt vmcnt(8)
	s_waitcnt lgkmcnt(0)
	s_barrier
	s_setprio 1
	v_mfma_f32_16x16x32_bf16 v[124:127], v[144:147], v[176:179], v[124:127]
	v_mfma_f32_16x16x32_bf16 v[120:123], v[152:155], v[176:179], v[120:123]
	v_mfma_f32_16x16x32_bf16 v[116:119], v[144:147], v[192:195], v[116:119]
	v_mfma_f32_16x16x32_bf16 v[112:115], v[152:155], v[192:195], v[112:115]
	v_mfma_f32_16x16x32_bf16 v[104:107], v[144:147], v[200:203], v[104:107]
	v_mfma_f32_16x16x32_bf16 v[96:99], v[152:155], v[200:203], v[96:99]
	v_mfma_f32_16x16x32_bf16 v[88:91], v[144:147], v[208:211], v[88:91]
	v_mfma_f32_16x16x32_bf16 v[80:83], v[152:155], v[208:211], v[80:83]
	v_mfma_f32_16x16x32_bf16 v[124:127], v[148:151], v[180:183], v[124:127]
	v_mfma_f32_16x16x32_bf16 v[120:123], v[156:159], v[180:183], v[120:123]
	v_mfma_f32_16x16x32_bf16 v[116:119], v[148:151], v[196:199], v[116:119]
	v_mfma_f32_16x16x32_bf16 v[112:115], v[156:159], v[196:199], v[112:115]
	v_mfma_f32_16x16x32_bf16 v[104:107], v[148:151], v[204:207], v[104:107]
	v_mfma_f32_16x16x32_bf16 v[96:99], v[156:159], v[204:207], v[96:99]
	v_mfma_f32_16x16x32_bf16 v[88:91], v[148:151], v[212:215], v[88:91]
	v_mfma_f32_16x16x32_bf16 v[80:83], v[156:159], v[212:215], v[80:83]
	v_mfma_f32_16x16x32_bf16 v[108:111], v[160:163], v[176:179], v[108:111]
	v_mfma_f32_16x16x32_bf16 v[100:103], v[168:171], v[176:179], v[100:103]
	v_mfma_f32_16x16x32_bf16 v[92:95], v[160:163], v[192:195], v[92:95]
	v_mfma_f32_16x16x32_bf16 v[84:87], v[168:171], v[192:195], v[84:87]
	v_mfma_f32_16x16x32_bf16 v[76:79], v[160:163], v[200:203], v[76:79]
	v_mfma_f32_16x16x32_bf16 v[72:75], v[168:171], v[200:203], v[72:75]
	v_mfma_f32_16x16x32_bf16 v[68:71], v[160:163], v[208:211], v[68:71]
	v_mfma_f32_16x16x32_bf16 v[64:67], v[168:171], v[208:211], v[64:67]
	v_mfma_f32_16x16x32_bf16 v[108:111], v[164:167], v[180:183], v[108:111]
	v_mfma_f32_16x16x32_bf16 v[100:103], v[172:175], v[180:183], v[100:103]
	v_mfma_f32_16x16x32_bf16 v[92:95], v[164:167], v[196:199], v[92:95]
	v_mfma_f32_16x16x32_bf16 v[84:87], v[172:175], v[196:199], v[84:87]
	v_mfma_f32_16x16x32_bf16 v[76:79], v[164:167], v[204:207], v[76:79]
	v_mfma_f32_16x16x32_bf16 v[72:75], v[172:175], v[204:207], v[72:75]
	v_mfma_f32_16x16x32_bf16 v[68:71], v[164:167], v[212:215], v[68:71]
	v_mfma_f32_16x16x32_bf16 v[64:67], v[172:175], v[212:215], v[64:67]
	s_setprio 0
	s_barrier
	s_add_i32 s24, s50, s38
	v_lshl_add_u64 v[184:185], s[28:29], 0, v[130:131]
	s_mov_b32 m0, s24
	ds_read_b128 v[176:179], v191 offset:16384
	ds_read_b128 v[180:183], v191 offset:17408
	ds_read_b128 v[192:195], v191 offset:18432
	ds_read_b128 v[196:199], v191 offset:19456
	ds_read_b128 v[200:203], v191 offset:20480
	ds_read_b128 v[204:207], v191 offset:21504
	ds_read_b128 v[208:211], v191 offset:22528
	ds_read_b128 v[212:215], v191 offset:23552
	global_load_lds_dwordx4 v[184:185], off
	s_add_i32 m0, s24, 0x2000
	s_add_u32 s24, s28, 0xb0000
	v_lshl_add_u64 v[216:217], s[28:29], 0, v[134:135]
	s_addc_u32 s25, s29, 0
	s_add_i32 s59, s51, s38
	global_load_lds_dwordx4 v[216:217], off
	v_lshl_add_u64 v[218:219], s[24:25], 0, v[130:131]
	s_mov_b32 m0, s59
	v_lshl_add_u64 v[220:221], s[30:31], 0, v[132:133]
	global_load_lds_dwordx4 v[218:219], off
	v_lshl_add_u64 v[218:219], s[24:25], 0, v[134:135]
	s_add_i32 m0, s59, 0x2000
	s_nop 0
	global_load_lds_dwordx4 v[218:219], off
	v_lshl_add_u64 v[218:219], s[30:31], 0, v[128:129]
	s_mov_b32 m0, s39
	s_nop 0
	global_load_lds_dwordx4 v[218:219], off
	s_mov_b32 m0, s40
	s_nop 0
	global_load_lds_dwordx4 v[220:221], off
	s_waitcnt vmcnt(8)
	s_waitcnt lgkmcnt(0)
	s_barrier
; #define PG8_STAGE(bufoff, gbase, voff) do { _Pragma("unroll") for (int _i = 0; _i < 2; ++_i) \
;         __builtin_amdgcn_global_load_lds((const unsigned*)((const char*)(gbase) + (voff)[_i]), (LAS unsigned*)(lds + (bufoff) + ldsw + _i * 8192), 16, 0, 0); } while (0)
; #define PG8_LDA(dst, b, h) do { _Pragma("unroll") for (int m = 0; m < 4; ++m) _Pragma("unroll") for (int k = 0; k < 2; ++k) dst[m][k] = *(const LAS bf16x8*)(lds + PG8_SA(b, h) + aoff + m * 2048 + k * 1024); } while (0)
; #define PG8_LDB(dst, b, h) do { _Pragma("unroll") for (int n = 0; n < 2; ++n) _Pragma("unroll") for (int k = 0; k < 2; ++k) dst[n][k] = *(const LAS bf16x8*)(lds + PG8_SB(b, h) + boff + n * 2048 + k * 1024); } while (0)
; #define PG8_MMA(ai, bj, At, Bt) do { __builtin_amdgcn_s_setprio(1); _Pragma("unroll") for (int m = 0; m < 4; ++m) _Pragma("unroll") for (int n = 0; n < 2; ++n) _Pragma("unroll") for (int k = 0; k < 2; ++k) \
;         acc[ai][bj][m][n] = __builtin_amdgcn_mfma_f32_16x16x32_bf16(Bt[n][k], At[m][k], acc[ai][bj][m][n], 0, 0, 0); __builtin_amdgcn_s_setprio(0); } while (0)
; #define PG8_WAIT_V(n) asm volatile("s_waitcnt vmcnt(" #n ")" ::: "memory")
; #define PG8_WAIT_L(n) asm volatile("s_waitcnt lgkmcnt(" #n ")" ::: "memory")
; #define PG8_BAR __builtin_amdgcn_s_barrier()
; #define PG8_SCHED __builtin_amdgcn_sched_barrier(0)
; template <class Epi>
; __device__ __forceinline__ void gemm_phase(LAS unsigned char* lds, const int tid, const Gemm g, const StaticOrder& S, const Epi& E) {
;     ...
;             PG8_WAIT_V(8); PG8_WAIT_L(0); PG8_BAR; PG8_MMA(1, 0, At, B0); PG8_MMA(1, 1, At, B1); PG8_BAR; PG8_SCHED;
;             PG8_LDB(B0, 1, 0); PG8_LDB(B1, 1, 1); PG8_SCHED; PG8_LDA(At, 1, 0); PG8_STAGE(PG8_SA(0, 1), a2 + hstepA, voffA);
;             PG8_WAIT_V(8); PG8_WAIT_L(0); PG8_BAR; PG8_MMA(0, 0, At, B0); PG8_MMA(0, 1, At, B1); PG8_BAR; PG8_SCHED;
	s_setprio 1
	v_mfma_f32_16x16x32_bf16 v[60:63], v[144:147], v[176:179], v[60:63]
	v_mfma_f32_16x16x32_bf16 v[56:59], v[152:155], v[176:179], v[56:59]
	v_mfma_f32_16x16x32_bf16 v[52:55], v[144:147], v[192:195], v[52:55]
	v_mfma_f32_16x16x32_bf16 v[48:51], v[152:155], v[192:195], v[48:51]
	v_mfma_f32_16x16x32_bf16 v[40:43], v[144:147], v[200:203], v[40:43]
	v_mfma_f32_16x16x32_bf16 v[32:35], v[152:155], v[200:203], v[32:35]
	v_mfma_f32_16x16x32_bf16 v[24:27], v[144:147], v[208:211], v[24:27]
	v_mfma_f32_16x16x32_bf16 v[16:19], v[152:155], v[208:211], v[16:19]
	v_mfma_f32_16x16x32_bf16 v[60:63], v[148:151], v[180:183], v[60:63]
	v_mfma_f32_16x16x32_bf16 v[56:59], v[156:159], v[180:183], v[56:59]
	v_mfma_f32_16x16x32_bf16 v[52:55], v[148:151], v[196:199], v[52:55]
	v_mfma_f32_16x16x32_bf16 v[48:51], v[156:159], v[196:199], v[48:51]
	v_mfma_f32_16x16x32_bf16 v[40:43], v[148:151], v[204:207], v[40:43]
	v_mfma_f32_16x16x32_bf16 v[32:35], v[156:159], v[204:207], v[32:35]
	v_mfma_f32_16x16x32_bf16 v[24:27], v[148:151], v[212:215], v[24:27]
	v_mfma_f32_16x16x32_bf16 v[16:19], v[156:159], v[212:215], v[16:19]
	v_mfma_f32_16x16x32_bf16 v[44:47], v[160:163], v[176:179], v[44:47]
	v_mfma_f32_16x16x32_bf16 v[36:39], v[168:171], v[176:179], v[36:39]
	v_mfma_f32_16x16x32_bf16 v[28:31], v[160:163], v[192:195], v[28:31]
	v_mfma_f32_16x16x32_bf16 v[20:23], v[168:171], v[192:195], v[20:23]
	v_mfma_f32_16x16x32_bf16 v[12:15], v[160:163], v[200:203], v[12:15]
	v_mfma_f32_16x16x32_bf16 v[8:11], v[168:171], v[200:203], v[8:11]
	v_mfma_f32_16x16x32_bf16 v[4:7], v[160:163], v[208:211], v[4:7]
	v_mfma_f32_16x16x32_bf16 v[0:3], v[168:171], v[208:211], v[0:3]
	v_mfma_f32_16x16x32_bf16 v[44:47], v[164:167], v[180:183], v[44:47]
	v_mfma_f32_16x16x32_bf16 v[36:39], v[172:175], v[180:183], v[36:39]
	v_mfma_f32_16x16x32_bf16 v[28:31], v[164:167], v[196:199], v[28:31]
	v_mfma_f32_16x16x32_bf16 v[20:23], v[172:175], v[196:199], v[20:23]
	v_mfma_f32_16x16x32_bf16 v[12:15], v[164:167], v[204:207], v[12:15]
	v_mfma_f32_16x16x32_bf16 v[8:11], v[172:175], v[204:207], v[8:11]
	v_mfma_f32_16x16x32_bf16 v[4:7], v[164:167], v[212:215], v[4:7]
	v_mfma_f32_16x16x32_bf16 v[0:3], v[172:175], v[212:215], v[0:3]
	s_setprio 0
	s_barrier
	s_add_i32 s59, 0, 0x18000
	s_add_i32 s60, 0, 0x1c000
	v_add_u32_e32 v156, s59, v187
	v_add_u32_e32 v172, s60, v187
	ds_read_b128 v[144:147], v156
	ds_read_b128 v[148:151], v156 offset:1024
	ds_read_b128 v[152:155], v156 offset:2048
	ds_read_b128 v[156:159], v156 offset:3072
	ds_read_b128 v[160:163], v172
	ds_read_b128 v[164:167], v172 offset:1024
	ds_read_b128 v[168:171], v172 offset:2048
	ds_read_b128 v[172:175], v172 offset:3072
	s_add_u32 s24, s30, 0xb0000
	s_addc_u32 s25, s31, 0
	s_mov_b32 m0, s41
	v_lshl_add_u64 v[222:223], s[24:25], 0, v[128:129]
	ds_read_b128 v[176:179], v191 offset:32768
	ds_read_b128 v[180:183], v191 offset:33792
	ds_read_b128 v[192:195], v191 offset:34816
	ds_read_b128 v[196:199], v191 offset:35840
	ds_read_b128 v[200:203], v191 offset:36864
	ds_read_b128 v[204:207], v191 offset:37888
	ds_read_b128 v[208:211], v191 offset:38912
	ds_read_b128 v[212:215], v191 offset:39936
	global_load_lds_dwordx4 v[222:223], off
	v_lshl_add_u64 v[222:223], s[24:25], 0, v[132:133]
	s_mov_b32 m0, s42
	s_nop 0
	global_load_lds_dwordx4 v[222:223], off
	s_waitcnt vmcnt(8)
	s_waitcnt lgkmcnt(0)
	s_barrier
	s_setprio 1
	v_mfma_f32_16x16x32_bf16 v[124:127], v[144:147], v[176:179], v[124:127]
	v_mfma_f32_16x16x32_bf16 v[120:123], v[152:155], v[176:179], v[120:123]
	v_mfma_f32_16x16x32_bf16 v[116:119], v[144:147], v[192:195], v[116:119]
	v_mfma_f32_16x16x32_bf16 v[112:115], v[152:155], v[192:195], v[112:115]
	v_mfma_f32_16x16x32_bf16 v[104:107], v[144:147], v[200:203], v[104:107]
	v_mfma_f32_16x16x32_bf16 v[96:99], v[152:155], v[200:203], v[96:99]
	v_mfma_f32_16x16x32_bf16 v[88:91], v[144:147], v[208:211], v[88:91]
	v_mfma_f32_16x16x32_bf16 v[80:83], v[152:155], v[208:211], v[80:83]
	v_mfma_f32_16x16x32_bf16 v[124:127], v[148:151], v[180:183], v[124:127]
	v_mfma_f32_16x16x32_bf16 v[120:123], v[156:159], v[180:183], v[120:123]
	v_mfma_f32_16x16x32_bf16 v[116:119], v[148:151], v[196:199], v[116:119]
	v_mfma_f32_16x16x32_bf16 v[112:115], v[156:159], v[196:199], v[112:115]
	v_mfma_f32_16x16x32_bf16 v[104:107], v[148:151], v[204:207], v[104:107]
	v_mfma_f32_16x16x32_bf16 v[96:99], v[156:159], v[204:207], v[96:99]
	v_mfma_f32_16x16x32_bf16 v[88:91], v[148:151], v[212:215], v[88:91]
	v_mfma_f32_16x16x32_bf16 v[80:83], v[156:159], v[212:215], v[80:83]
	v_mfma_f32_16x16x32_bf16 v[108:111], v[160:163], v[176:179], v[108:111]
	v_mfma_f32_16x16x32_bf16 v[100:103], v[168:171], v[176:179], v[100:103]
	v_mfma_f32_16x16x32_bf16 v[92:95], v[160:163], v[192:195], v[92:95]
	v_mfma_f32_16x16x32_bf16 v[84:87], v[168:171], v[192:195], v[84:87]
	v_mfma_f32_16x16x32_bf16 v[76:79], v[160:163], v[200:203], v[76:79]
	v_mfma_f32_16x16x32_bf16 v[72:75], v[168:171], v[200:203], v[72:75]
	v_mfma_f32_16x16x32_bf16 v[68:71], v[160:163], v[208:211], v[68:71]
	v_mfma_f32_16x16x32_bf16 v[64:67], v[168:171], v[208:211], v[64:67]
	v_mfma_f32_16x16x32_bf16 v[108:111], v[164:167], v[180:183], v[108:111]
	v_mfma_f32_16x16x32_bf16 v[100:103], v[172:175], v[180:183], v[100:103]
	v_mfma_f32_16x16x32_bf16 v[92:95], v[164:167], v[196:199], v[92:95]
	v_mfma_f32_16x16x32_bf16 v[84:87], v[172:175], v[196:199], v[84:87]
	v_mfma_f32_16x16x32_bf16 v[76:79], v[164:167], v[204:207], v[76:79]
	v_mfma_f32_16x16x32_bf16 v[72:75], v[172:175], v[204:207], v[72:75]
	v_mfma_f32_16x16x32_bf16 v[68:71], v[164:167], v[212:215], v[68:71]
	v_mfma_f32_16x16x32_bf16 v[64:67], v[172:175], v[212:215], v[64:67]
	s_setprio 0
	s_barrier
; #define PG8_STAGE(bufoff, gbase, voff) do { _Pragma("unroll") for (int _i = 0; _i < 2; ++_i) \
;         __builtin_amdgcn_global_load_lds((const unsigned*)((const char*)(gbase) + (voff)[_i]), (LAS unsigned*)(lds + (bufoff) + ldsw + _i * 8192), 16, 0, 0); } while (0)
; #define PG8_LDA(dst, b, h) do { _Pragma("unroll") for (int m = 0; m < 4; ++m) _Pragma("unroll") for (int k = 0; k < 2; ++k) dst[m][k] = *(const LAS bf16x8*)(lds + PG8_SA(b, h) + aoff + m * 2048 + k * 1024); } while (0)
; #define PG8_MMA(ai, bj, At, Bt) do { __builtin_amdgcn_s_setprio(1); _Pragma("unroll") for (int m = 0; m < 4; ++m) _Pragma("unroll") for (int n = 0; n < 2; ++n) _Pragma("unroll") for (int k = 0; k < 2; ++k) \
;         acc[ai][bj][m][n] = __builtin_amdgcn_mfma_f32_16x16x32_bf16(Bt[n][k], At[m][k], acc[ai][bj][m][n], 0, 0, 0); __builtin_amdgcn_s_setprio(0); } while (0)
; #define PG8_WAIT_V(n) asm volatile("s_waitcnt vmcnt(" #n ")" ::: "memory")
; #define PG8_WAIT_L(n) asm volatile("s_waitcnt lgkmcnt(" #n ")" ::: "memory")
; #define PG8_BAR __builtin_amdgcn_s_barrier()
; #define PG8_SCHED __builtin_amdgcn_sched_barrier(0)
; template <class Epi>
; __device__ __forceinline__ void gemm_phase(LAS unsigned char* lds, const int tid, const Gemm g, const StaticOrder& S, const Epi& E) {
;     ...
;         for (int t = 0; t < nt; t += 2) {
;     ...
;             PG8_LDA(At, 1, 1); PG8_STAGE(PG8_SB(1, 0), b3, voffB); PG8_STAGE(PG8_SB(1, 1), b3 + hstepB, voffB); PG8_STAGE(PG8_SA(1, 0), a3, voffA);
;             PG8_WAIT_V(8); PG8_WAIT_L(0); PG8_BAR; PG8_MMA(1, 0, At, B0); PG8_MMA(1, 1, At, B1); PG8_BAR; PG8_SCHED;
	s_add_i32 s24, s59, s38
	v_lshl_add_u64 v[184:185], v[184:185], 0, s[16:17]
	s_mov_b32 m0, s24
	ds_read_b128 v[176:179], v191 offset:49152
	ds_read_b128 v[180:183], v191 offset:50176
	ds_read_b128 v[192:195], v191 offset:51200
	ds_read_b128 v[196:199], v191 offset:52224
	ds_read_b128 v[200:203], v191 offset:53248
	ds_read_b128 v[204:207], v191 offset:54272
	ds_read_b128 v[208:211], v191 offset:55296
	ds_read_b128 v[212:215], v191 offset:56320
	global_load_lds_dwordx4 v[184:185], off
	s_add_i32 m0, s24, 0x2000
	s_add_u32 s24, s28, 0xb0080
	v_lshl_add_u64 v[184:185], v[216:217], 0, s[16:17]
	s_addc_u32 s25, s29, 0
	s_add_i32 s28, s60, s38
	global_load_lds_dwordx4 v[184:185], off
	v_lshl_add_u64 v[184:185], s[24:25], 0, v[130:131]
	s_mov_b32 m0, s28
	s_nop 0
	global_load_lds_dwordx4 v[184:185], off
	v_lshl_add_u64 v[184:185], s[24:25], 0, v[134:135]
	s_add_i32 m0, s28, 0x2000
	s_nop 0
	global_load_lds_dwordx4 v[184:185], off
	v_lshl_add_u64 v[184:185], v[218:219], 0, s[16:17]
	s_mov_b32 m0, s45
	s_nop 0
	global_load_lds_dwordx4 v[184:185], off
	v_lshl_add_u64 v[184:185], v[220:221], 0, s[16:17]
	s_mov_b32 m0, s46
	s_nop 0
	global_load_lds_dwordx4 v[184:185], off
	s_waitcnt vmcnt(8)
	s_waitcnt lgkmcnt(0)
	s_barrier
	s_setprio 1
	v_mfma_f32_16x16x32_bf16 v[60:63], v[144:147], v[176:179], v[60:63]
	v_mfma_f32_16x16x32_bf16 v[56:59], v[152:155], v[176:179], v[56:59]
	v_mfma_f32_16x16x32_bf16 v[52:55], v[144:147], v[192:195], v[52:55]
	v_mfma_f32_16x16x32_bf16 v[48:51], v[152:155], v[192:195], v[48:51]
	v_mfma_f32_16x16x32_bf16 v[40:43], v[144:147], v[200:203], v[40:43]
	v_mfma_f32_16x16x32_bf16 v[32:35], v[152:155], v[200:203], v[32:35]
	v_mfma_f32_16x16x32_bf16 v[24:27], v[144:147], v[208:211], v[24:27]
	v_mfma_f32_16x16x32_bf16 v[16:19], v[152:155], v[208:211], v[16:19]
	v_mfma_f32_16x16x32_bf16 v[60:63], v[148:151], v[180:183], v[60:63]
	v_mfma_f32_16x16x32_bf16 v[56:59], v[156:159], v[180:183], v[56:59]
	v_mfma_f32_16x16x32_bf16 v[52:55], v[148:151], v[196:199], v[52:55]
	v_mfma_f32_16x16x32_bf16 v[48:51], v[156:159], v[196:199], v[48:51]
	v_mfma_f32_16x16x32_bf16 v[40:43], v[148:151], v[204:207], v[40:43]
	v_mfma_f32_16x16x32_bf16 v[32:35], v[156:159], v[204:207], v[32:35]
	v_mfma_f32_16x16x32_bf16 v[24:27], v[148:151], v[212:215], v[24:27]
	v_mfma_f32_16x16x32_bf16 v[16:19], v[156:159], v[212:215], v[16:19]
	v_mfma_f32_16x16x32_bf16 v[44:47], v[160:163], v[176:179], v[44:47]
	v_mfma_f32_16x16x32_bf16 v[36:39], v[168:171], v[176:179], v[36:39]
	v_mfma_f32_16x16x32_bf16 v[28:31], v[160:163], v[192:195], v[28:31]
	v_mfma_f32_16x16x32_bf16 v[20:23], v[168:171], v[192:195], v[20:23]
	v_mfma_f32_16x16x32_bf16 v[12:15], v[160:163], v[200:203], v[12:15]
	v_mfma_f32_16x16x32_bf16 v[8:11], v[168:171], v[200:203], v[8:11]
	v_mfma_f32_16x16x32_bf16 v[4:7], v[160:163], v[208:211], v[4:7]
	v_mfma_f32_16x16x32_bf16 v[0:3], v[168:171], v[208:211], v[0:3]
	v_mfma_f32_16x16x32_bf16 v[44:47], v[164:167], v[180:183], v[44:47]
	v_mfma_f32_16x16x32_bf16 v[36:39], v[172:175], v[180:183], v[36:39]
	v_mfma_f32_16x16x32_bf16 v[28:31], v[164:167], v[196:199], v[28:31]
	v_mfma_f32_16x16x32_bf16 v[20:23], v[172:175], v[196:199], v[20:23]
	v_mfma_f32_16x16x32_bf16 v[12:15], v[164:167], v[204:207], v[12:15]
	v_mfma_f32_16x16x32_bf16 v[8:11], v[172:175], v[204:207], v[8:11]
	v_mfma_f32_16x16x32_bf16 v[4:7], v[164:167], v[212:215], v[4:7]
	v_mfma_f32_16x16x32_bf16 v[0:3], v[172:175], v[212:215], v[0:3]
	s_setprio 0
	s_barrier
	s_add_u32 s56, s56, 0x100
	s_addc_u32 s57, s57, 0
	s_cmp_ge_i32 s58, s44
	s_mov_b64 s[24:25], s[26:27]
	s_mov_b32 s28, s58
	s_cbranch_scc0 .LBB0_906
;     __device__ __forceinline__ void operator()(const Acc& acc, const Unit& u, int wr, int wc, int fr, int fq) const {
;     ...
;                     const f32x4 h0 = hv[m][bj][0] + acc[ai][bj][m][0] * scale, h1 = hv[m][bj][1] + acc[ai][bj][m][1] * scale;
	v_pk_mul_f32 v[154:155], v[126:127], 0.5 op_sel_hi:[1,0]
	v_pk_mul_f32 v[156:157], v[124:125], 0.5 op_sel_hi:[1,0]
	v_pk_mul_f32 v[158:159], v[122:123], 0.5 op_sel_hi:[1,0]
	v_pk_mul_f32 v[160:161], v[120:121], 0.5 op_sel_hi:[1,0]
	v_pk_mul_f32 v[168:169], v[110:111], 0.5 op_sel_hi:[1,0]
	v_pk_mul_f32 v[166:167], v[108:109], 0.5 op_sel_hi:[1,0]
	v_pk_mul_f32 v[164:165], v[102:103], 0.5 op_sel_hi:[1,0]
	v_pk_mul_f32 v[162:163], v[100:101], 0.5 op_sel_hi:[1,0]
	v_pk_mul_f32 v[152:153], v[118:119], 0.5 op_sel_hi:[1,0]
	v_pk_mul_f32 v[150:151], v[116:117], 0.5 op_sel_hi:[1,0]
	v_pk_mul_f32 v[148:149], v[114:115], 0.5 op_sel_hi:[1,0]
	v_pk_mul_f32 v[146:147], v[112:113], 0.5 op_sel_hi:[1,0]
	v_pk_mul_f32 v[144:145], v[94:95], 0.5 op_sel_hi:[1,0]
	v_pk_mul_f32 v[126:127], v[92:93], 0.5 op_sel_hi:[1,0]
	v_pk_mul_f32 v[124:125], v[86:87], 0.5 op_sel_hi:[1,0]
	v_pk_mul_f32 v[122:123], v[84:85], 0.5 op_sel_hi:[1,0]
	v_pk_mul_f32 v[120:121], v[106:107], 0.5 op_sel_hi:[1,0]
	v_pk_mul_f32 v[118:119], v[104:105], 0.5 op_sel_hi:[1,0]
	v_pk_mul_f32 v[116:117], v[98:99], 0.5 op_sel_hi:[1,0]
	v_pk_mul_f32 v[114:115], v[96:97], 0.5 op_sel_hi:[1,0]
	v_pk_mul_f32 v[112:113], v[78:79], 0.5 op_sel_hi:[1,0]
	v_pk_mul_f32 v[110:111], v[76:77], 0.5 op_sel_hi:[1,0]
	v_pk_mul_f32 v[108:109], v[74:75], 0.5 op_sel_hi:[1,0]
	v_pk_mul_f32 v[106:107], v[72:73], 0.5 op_sel_hi:[1,0]
	v_pk_mul_f32 v[104:105], v[90:91], 0.5 op_sel_hi:[1,0]
	v_pk_mul_f32 v[102:103], v[88:89], 0.5 op_sel_hi:[1,0]
	v_pk_mul_f32 v[100:101], v[82:83], 0.5 op_sel_hi:[1,0]
	v_pk_mul_f32 v[98:99], v[80:81], 0.5 op_sel_hi:[1,0]
	v_pk_mul_f32 v[96:97], v[70:71], 0.5 op_sel_hi:[1,0]
	v_pk_mul_f32 v[94:95], v[68:69], 0.5 op_sel_hi:[1,0]
	v_pk_mul_f32 v[92:93], v[66:67], 0.5 op_sel_hi:[1,0]
	v_pk_mul_f32 v[90:91], v[64:65], 0.5 op_sel_hi:[1,0]
	v_pk_mul_f32 v[72:73], v[62:63], 0.5 op_sel_hi:[1,0]
	v_pk_mul_f32 v[74:75], v[60:61], 0.5 op_sel_hi:[1,0]
	v_pk_mul_f32 v[76:77], v[58:59], 0.5 op_sel_hi:[1,0]
	v_pk_mul_f32 v[78:79], v[56:57], 0.5 op_sel_hi:[1,0]
	v_pk_mul_f32 v[86:87], v[46:47], 0.5 op_sel_hi:[1,0]
	v_pk_mul_f32 v[84:85], v[44:45], 0.5 op_sel_hi:[1,0]
	v_pk_mul_f32 v[82:83], v[38:39], 0.5 op_sel_hi:[1,0]
	v_pk_mul_f32 v[80:81], v[36:37], 0.5 op_sel_hi:[1,0]
	v_pk_mul_f32 v[70:71], v[54:55], 0.5 op_sel_hi:[1,0]
	v_pk_mul_f32 v[68:69], v[52:53], 0.5 op_sel_hi:[1,0]
	v_pk_mul_f32 v[66:67], v[50:51], 0.5 op_sel_hi:[1,0]
	v_pk_mul_f32 v[64:65], v[48:49], 0.5 op_sel_hi:[1,0]
	v_pk_mul_f32 v[62:63], v[30:31], 0.5 op_sel_hi:[1,0]
	v_pk_mul_f32 v[60:61], v[28:29], 0.5 op_sel_hi:[1,0]
	v_pk_mul_f32 v[58:59], v[22:23], 0.5 op_sel_hi:[1,0]
	v_pk_mul_f32 v[56:57], v[20:21], 0.5 op_sel_hi:[1,0]
	v_pk_mul_f32 v[54:55], v[42:43], 0.5 op_sel_hi:[1,0]
	v_pk_mul_f32 v[52:53], v[40:41], 0.5 op_sel_hi:[1,0]
	v_pk_mul_f32 v[50:51], v[34:35], 0.5 op_sel_hi:[1,0]
	v_pk_mul_f32 v[48:49], v[32:33], 0.5 op_sel_hi:[1,0]
	v_pk_mul_f32 v[46:47], v[14:15], 0.5 op_sel_hi:[1,0]
	v_pk_mul_f32 v[44:45], v[12:13], 0.5 op_sel_hi:[1,0]
	v_pk_mul_f32 v[42:43], v[10:11], 0.5 op_sel_hi:[1,0]
	v_pk_mul_f32 v[40:41], v[8:9], 0.5 op_sel_hi:[1,0]
	v_pk_mul_f32 v[38:39], v[26:27], 0.5 op_sel_hi:[1,0]
	v_pk_mul_f32 v[36:37], v[24:25], 0.5 op_sel_hi:[1,0]
	v_pk_mul_f32 v[34:35], v[18:19], 0.5 op_sel_hi:[1,0]
	v_pk_mul_f32 v[32:33], v[16:17], 0.5 op_sel_hi:[1,0]
	v_pk_mul_f32 v[30:31], v[6:7], 0.5 op_sel_hi:[1,0]
	v_pk_mul_f32 v[28:29], v[4:5], 0.5 op_sel_hi:[1,0]
	v_pk_mul_f32 v[26:27], v[2:3], 0.5 op_sel_hi:[1,0]
	v_pk_mul_f32 v[24:25], v[0:1], 0.5 op_sel_hi:[1,0]

; #define LAS __attribute__((address_space(3)))
; #define PG8_STAGE(bufoff, gbase, voff) do { _Pragma("unroll") for (int _i = 0; _i < 2; ++_i) \
;         __builtin_amdgcn_global_load_lds((const unsigned*)((const char*)(gbase) + (voff)[_i]), (LAS unsigned*)(lds + (bufoff) + ldsw + _i * 8192), 16, 0, 0); } while (0)
; #define PG8_LDA(dst, b, h) do { _Pragma("unroll") for (int m = 0; m < 4; ++m) _Pragma("unroll") for (int k = 0; k < 2; ++k) dst[m][k] = *(const LAS bf16x8*)(lds + PG8_SA(b, h) + aoff + m * 2048 + k * 1024); } while (0)
; #define PG8_LDB(dst, b, h) do { _Pragma("unroll") for (int n = 0; n < 2; ++n) _Pragma("unroll") for (int k = 0; k < 2; ++k) dst[n][k] = *(const LAS bf16x8*)(lds + PG8_SB(b, h) + boff + n * 2048 + k * 1024); } while (0)
; #define PG8_WAIT_V(n) asm volatile("s_waitcnt vmcnt(" #n ")" ::: "memory")
; #define PG8_WAIT_L(n) asm volatile("s_waitcnt lgkmcnt(" #n ")" ::: "memory")
; #define PG8_BAR __builtin_amdgcn_s_barrier()
; template <class Epi>
; __device__ __forceinline__ void gemm_phase(LAS unsigned char* lds, const int tid, const Gemm g, const StaticOrder& S, const Epi& E) {
;     ...
;             const bool last = (t == nt - 2);
;             const char* a1 = cA + (size_t)(t + 1) * kstep;
;             const char* a2 = last ? nA : cA + (size_t)(t + 2) * kstep; const char* b2 = last ? nB : cB + (size_t)(t + 2) * kstep;
;             const char* a3 = a2 + kstep; const char* b3 = b2 + kstep;
;             if constexpr (Epi::SS_LDS) { if (last) {
;                 const char* sp = (const char*)E.ss + (size_t)cur.pm * (256 * 64) + (size_t)tid * 16;
;                 __builtin_amdgcn_global_load_lds((const unsigned*)sp, (LAS unsigned*)(lds + RS_OFF + ldsw), 16, 0, 0);
;                 __builtin_amdgcn_global_load_lds((const unsigned*)(sp + 8192), (LAS unsigned*)(lds + RS_OFF + 8192 + ldsw), 16, 0, 0); } }
;     ...
;             PG8_LDB(B0, 0, 0); PG8_LDB(B1, 0, 1); PG8_SCHED; PG8_LDA(At, 0, 0); PG8_STAGE(PG8_SA(1, 1), a1 + hstepA, voffA);
;             PG8_WAIT_V(8); PG8_WAIT_L(0); PG8_BAR; PG8_MMA(0, 0, At, B0); PG8_MMA(0, 1, At, B1); PG8_BAR; PG8_SCHED;
;             PG8_LDA(At, 0, 1); PG8_STAGE(PG8_SB(0, 0), b2, voffB); PG8_STAGE(PG8_SB(0, 1), b2 + hstepB, voffB); PG8_STAGE(PG8_SA(0, 0), a2, voffA);
;             PG8_WAIT_V(8); PG8_WAIT_L(0); PG8_BAR; PG8_MMA(1, 0, At, B0); PG8_MMA(1, 1, At, B1); PG8_BAR; PG8_SCHED;
.LBB0_949:
	ds_read_b128 v[152:155], v148
	ds_read_b128 v[156:159], v148 offset:1024
	ds_read_b128 v[160:163], v148 offset:2048
	ds_read_b128 v[164:167], v148 offset:3072
	ds_read_b128 v[168:171], v149
	ds_read_b128 v[172:175], v149 offset:1024
	ds_read_b128 v[176:179], v149 offset:2048
	ds_read_b128 v[180:183], v149 offset:3072
	s_add_i32 s56, s28, 2
	s_add_u32 s29, s26, 0xffff0080
	s_addc_u32 s30, s27, -1
	s_cmp_eq_u32 s47, s28
	s_cselect_b32 s28, s53, s54
	s_cselect_b32 s31, s19, s30
	s_cselect_b32 s30, s21, s29
	s_cselect_b32 s29, s52, s55
	v_lshl_add_u64 v[216:217], s[26:27], 0, v[140:141]
	s_add_i32 m0, s40, 0xc000
	ds_read_b128 v[184:187], v150
	ds_read_b128 v[188:191], v150 offset:1024
	ds_read_b128 v[192:195], v150 offset:2048
	ds_read_b128 v[196:199], v150 offset:3072
	ds_read_b128 v[200:203], v150 offset:4096
	ds_read_b128 v[204:207], v150 offset:5120
	ds_read_b128 v[208:211], v150 offset:6144
	ds_read_b128 v[212:215], v150 offset:7168
	global_load_lds_dwordx4 v[216:217], off
	v_lshl_add_u64 v[216:217], s[26:27], 0, v[138:139]
	s_add_i32 m0, s40, 0xe000
	s_nop 0
	global_load_lds_dwordx4 v[216:217], off
	s_waitcnt vmcnt(8)
	s_waitcnt lgkmcnt(0)
	s_barrier
	s_setprio 1
	v_mfma_f32_16x16x32_bf16 v[120:123], v[152:155], v[184:187], v[120:123]
	v_mfma_f32_16x16x32_bf16 v[124:127], v[160:163], v[184:187], v[124:127]
	v_mfma_f32_16x16x32_bf16 v[108:111], v[152:155], v[192:195], v[108:111]
	v_mfma_f32_16x16x32_bf16 v[104:107], v[160:163], v[192:195], v[104:107]
	v_mfma_f32_16x16x32_bf16 v[92:95], v[152:155], v[200:203], v[92:95]
	v_mfma_f32_16x16x32_bf16 v[88:91], v[160:163], v[200:203], v[88:91]
	v_mfma_f32_16x16x32_bf16 v[76:79], v[152:155], v[208:211], v[76:79]
	v_mfma_f32_16x16x32_bf16 v[72:75], v[160:163], v[208:211], v[72:75]
	v_mfma_f32_16x16x32_bf16 v[120:123], v[156:159], v[188:191], v[120:123]
	v_mfma_f32_16x16x32_bf16 v[124:127], v[164:167], v[188:191], v[124:127]
	v_mfma_f32_16x16x32_bf16 v[108:111], v[156:159], v[196:199], v[108:111]
	v_mfma_f32_16x16x32_bf16 v[104:107], v[164:167], v[196:199], v[104:107]
	v_mfma_f32_16x16x32_bf16 v[92:95], v[156:159], v[204:207], v[92:95]
	v_mfma_f32_16x16x32_bf16 v[88:91], v[164:167], v[204:207], v[88:91]
	v_mfma_f32_16x16x32_bf16 v[76:79], v[156:159], v[212:215], v[76:79]
	v_mfma_f32_16x16x32_bf16 v[72:75], v[164:167], v[212:215], v[72:75]
	v_mfma_f32_16x16x32_bf16 v[116:119], v[168:171], v[184:187], v[116:119]
	v_mfma_f32_16x16x32_bf16 v[112:115], v[176:179], v[184:187], v[112:115]
	v_mfma_f32_16x16x32_bf16 v[100:103], v[168:171], v[192:195], v[100:103]
	v_mfma_f32_16x16x32_bf16 v[96:99], v[176:179], v[192:195], v[96:99]
	v_mfma_f32_16x16x32_bf16 v[84:87], v[168:171], v[200:203], v[84:87]
	v_mfma_f32_16x16x32_bf16 v[80:83], v[176:179], v[200:203], v[80:83]
	v_mfma_f32_16x16x32_bf16 v[68:71], v[168:171], v[208:211], v[68:71]
	v_mfma_f32_16x16x32_bf16 v[64:67], v[176:179], v[208:211], v[64:67]
	v_mfma_f32_16x16x32_bf16 v[116:119], v[172:175], v[188:191], v[116:119]
	v_mfma_f32_16x16x32_bf16 v[112:115], v[180:183], v[188:191], v[112:115]
	v_mfma_f32_16x16x32_bf16 v[100:103], v[172:175], v[196:199], v[100:103]
	v_mfma_f32_16x16x32_bf16 v[96:99], v[180:183], v[196:199], v[96:99]
	v_mfma_f32_16x16x32_bf16 v[84:87], v[172:175], v[204:207], v[84:87]
	v_mfma_f32_16x16x32_bf16 v[80:83], v[180:183], v[204:207], v[80:83]
	v_mfma_f32_16x16x32_bf16 v[68:71], v[172:175], v[212:215], v[68:71]
	v_mfma_f32_16x16x32_bf16 v[64:67], v[180:183], v[212:215], v[64:67]
	s_setprio 0
	s_barrier
	s_add_i32 s57, s49, s39
	v_lshl_add_u64 v[216:217], s[28:29], 0, v[130:131]
	s_mov_b32 m0, s57
	ds_read_b128 v[184:187], v150 offset:16384
	ds_read_b128 v[188:191], v150 offset:17408
	ds_read_b128 v[192:195], v150 offset:18432
	ds_read_b128 v[196:199], v150 offset:19456
	ds_read_b128 v[200:203], v150 offset:20480
	ds_read_b128 v[204:207], v150 offset:21504
	ds_read_b128 v[208:211], v150 offset:22528
	ds_read_b128 v[212:215], v150 offset:23552
	global_load_lds_dwordx4 v[216:217], off
	s_add_i32 m0, s57, 0x2000
	s_add_u32 s58, s28, 0x10000
	v_lshl_add_u64 v[218:219], s[28:29], 0, v[134:135]
	s_addc_u32 s59, s29, 0
	s_add_i32 s57, s50, s39
	global_load_lds_dwordx4 v[218:219], off
	v_lshl_add_u64 v[220:221], s[58:59], 0, v[130:131]
	s_mov_b32 m0, s57
	v_lshl_add_u64 v[222:223], s[30:31], 0, v[132:133]
	global_load_lds_dwordx4 v[220:221], off
	v_lshl_add_u64 v[220:221], s[58:59], 0, v[134:135]
	s_add_i32 m0, s57, 0x2000
	s_nop 0
	global_load_lds_dwordx4 v[220:221], off
	v_lshl_add_u64 v[220:221], s[30:31], 0, v[128:129]
	s_mov_b32 m0, s40
	s_nop 0
	global_load_lds_dwordx4 v[220:221], off
	s_mov_b32 m0, s41
	s_nop 0
	global_load_lds_dwordx4 v[222:223], off
	s_waitcnt vmcnt(8)
	s_waitcnt lgkmcnt(0)
	s_barrier
; #define PG8_STAGE(bufoff, gbase, voff) do { _Pragma("unroll") for (int _i = 0; _i < 2; ++_i) \
;         __builtin_amdgcn_global_load_lds((const unsigned*)((const char*)(gbase) + (voff)[_i]), (LAS unsigned*)(lds + (bufoff) + ldsw + _i * 8192), 16, 0, 0); } while (0)
; #define PG8_LDA(dst, b, h) do { _Pragma("unroll") for (int m = 0; m < 4; ++m) _Pragma("unroll") for (int k = 0; k < 2; ++k) dst[m][k] = *(const LAS bf16x8*)(lds + PG8_SA(b, h) + aoff + m * 2048 + k * 1024); } while (0)
; #define PG8_LDB(dst, b, h) do { _Pragma("unroll") for (int n = 0; n < 2; ++n) _Pragma("unroll") for (int k = 0; k < 2; ++k) dst[n][k] = *(const LAS bf16x8*)(lds + PG8_SB(b, h) + boff + n * 2048 + k * 1024); } while (0)
; #define PG8_MMA(ai, bj, At, Bt) do { __builtin_amdgcn_s_setprio(1); _Pragma("unroll") for (int m = 0; m < 4; ++m) _Pragma("unroll") for (int n = 0; n < 2; ++n) _Pragma("unroll") for (int k = 0; k < 2; ++k) \
;         acc[ai][bj][m][n] = __builtin_amdgcn_mfma_f32_16x16x32_bf16(Bt[n][k], At[m][k], acc[ai][bj][m][n], 0, 0, 0); __builtin_amdgcn_s_setprio(0); } while (0)
; #define PG8_WAIT_V(n) asm volatile("s_waitcnt vmcnt(" #n ")" ::: "memory")
; #define PG8_WAIT_L(n) asm volatile("s_waitcnt lgkmcnt(" #n ")" ::: "memory")
; #define PG8_BAR __builtin_amdgcn_s_barrier()
; #define PG8_SCHED __builtin_amdgcn_sched_barrier(0)
; template <class Epi>
; __device__ __forceinline__ void gemm_phase(LAS unsigned char* lds, const int tid, const Gemm g, const StaticOrder& S, const Epi& E) {
;     ...
;             PG8_WAIT_V(8); PG8_WAIT_L(0); PG8_BAR; PG8_MMA(1, 0, At, B0); PG8_MMA(1, 1, At, B1); PG8_BAR; PG8_SCHED;
;             PG8_LDB(B0, 1, 0); PG8_LDB(B1, 1, 1); PG8_SCHED; PG8_LDA(At, 1, 0); PG8_STAGE(PG8_SA(0, 1), a2 + hstepA, voffA);
;             PG8_WAIT_V(8); PG8_WAIT_L(0); PG8_BAR; PG8_MMA(0, 0, At, B0); PG8_MMA(0, 1, At, B1); PG8_BAR; PG8_SCHED;
	s_setprio 1
	v_mfma_f32_16x16x32_bf16 v[60:63], v[152:155], v[184:187], v[60:63]
	v_mfma_f32_16x16x32_bf16 v[56:59], v[160:163], v[184:187], v[56:59]
	v_mfma_f32_16x16x32_bf16 v[44:47], v[152:155], v[192:195], v[44:47]
	v_mfma_f32_16x16x32_bf16 v[40:43], v[160:163], v[192:195], v[40:43]
	v_mfma_f32_16x16x32_bf16 v[28:31], v[152:155], v[200:203], v[28:31]
	v_mfma_f32_16x16x32_bf16 v[24:27], v[160:163], v[200:203], v[24:27]
	v_mfma_f32_16x16x32_bf16 v[12:15], v[152:155], v[208:211], v[12:15]
	v_mfma_f32_16x16x32_bf16 v[8:11], v[160:163], v[208:211], v[8:11]
	v_mfma_f32_16x16x32_bf16 v[60:63], v[156:159], v[188:191], v[60:63]
	v_mfma_f32_16x16x32_bf16 v[56:59], v[164:167], v[188:191], v[56:59]
	v_mfma_f32_16x16x32_bf16 v[44:47], v[156:159], v[196:199], v[44:47]
	v_mfma_f32_16x16x32_bf16 v[40:43], v[164:167], v[196:199], v[40:43]
	v_mfma_f32_16x16x32_bf16 v[28:31], v[156:159], v[204:207], v[28:31]
	v_mfma_f32_16x16x32_bf16 v[24:27], v[164:167], v[204:207], v[24:27]
	v_mfma_f32_16x16x32_bf16 v[12:15], v[156:159], v[212:215], v[12:15]
	v_mfma_f32_16x16x32_bf16 v[8:11], v[164:167], v[212:215], v[8:11]
	v_mfma_f32_16x16x32_bf16 v[52:55], v[168:171], v[184:187], v[52:55]
	v_mfma_f32_16x16x32_bf16 v[48:51], v[176:179], v[184:187], v[48:51]
	v_mfma_f32_16x16x32_bf16 v[36:39], v[168:171], v[192:195], v[36:39]
	v_mfma_f32_16x16x32_bf16 v[32:35], v[176:179], v[192:195], v[32:35]
	v_mfma_f32_16x16x32_bf16 v[20:23], v[168:171], v[200:203], v[20:23]
	v_mfma_f32_16x16x32_bf16 v[16:19], v[176:179], v[200:203], v[16:19]
	v_mfma_f32_16x16x32_bf16 v[4:7], v[168:171], v[208:211], v[4:7]
	v_mfma_f32_16x16x32_bf16 v[0:3], v[176:179], v[208:211], v[0:3]
	v_mfma_f32_16x16x32_bf16 v[52:55], v[172:175], v[188:191], v[52:55]
	v_mfma_f32_16x16x32_bf16 v[48:51], v[180:183], v[188:191], v[48:51]
	v_mfma_f32_16x16x32_bf16 v[36:39], v[172:175], v[196:199], v[36:39]
	v_mfma_f32_16x16x32_bf16 v[32:35], v[180:183], v[196:199], v[32:35]
	v_mfma_f32_16x16x32_bf16 v[20:23], v[172:175], v[204:207], v[20:23]
	v_mfma_f32_16x16x32_bf16 v[16:19], v[180:183], v[204:207], v[16:19]
	v_mfma_f32_16x16x32_bf16 v[4:7], v[172:175], v[212:215], v[4:7]
	v_mfma_f32_16x16x32_bf16 v[0:3], v[180:183], v[212:215], v[0:3]
	s_setprio 0
	s_barrier
	s_add_i32 s57, 0, 0x18000
	v_add_u32_e32 v151, s57, v147
	s_add_i32 s58, 0, 0x1c000
	ds_read_b128 v[152:155], v151
	ds_read_b128 v[156:159], v151 offset:1024
	ds_read_b128 v[160:163], v151 offset:2048
	ds_read_b128 v[164:167], v151 offset:3072
	v_add_u32_e32 v151, s58, v147
	ds_read_b128 v[168:171], v151
	ds_read_b128 v[172:175], v151 offset:1024
	ds_read_b128 v[176:179], v151 offset:2048
	ds_read_b128 v[180:183], v151 offset:3072
	s_add_u32 s30, s30, 0x10000
	s_addc_u32 s31, s31, 0
	s_mov_b32 m0, s42
	v_lshl_add_u64 v[224:225], s[30:31], 0, v[128:129]
	ds_read_b128 v[184:187], v150 offset:32768
	ds_read_b128 v[188:191], v150 offset:33792
	ds_read_b128 v[192:195], v150 offset:34816
	ds_read_b128 v[196:199], v150 offset:35840
	ds_read_b128 v[200:203], v150 offset:36864
	ds_read_b128 v[204:207], v150 offset:37888
	ds_read_b128 v[208:211], v150 offset:38912
	ds_read_b128 v[212:215], v150 offset:39936
	global_load_lds_dwordx4 v[224:225], off
	v_lshl_add_u64 v[224:225], s[30:31], 0, v[132:133]
	s_mov_b32 m0, s43
	s_nop 0
	global_load_lds_dwordx4 v[224:225], off
	s_waitcnt vmcnt(8)
	s_waitcnt lgkmcnt(0)
	s_barrier
	s_setprio 1
	v_mfma_f32_16x16x32_bf16 v[120:123], v[152:155], v[184:187], v[120:123]
	v_mfma_f32_16x16x32_bf16 v[124:127], v[160:163], v[184:187], v[124:127]
	v_mfma_f32_16x16x32_bf16 v[108:111], v[152:155], v[192:195], v[108:111]
	v_mfma_f32_16x16x32_bf16 v[104:107], v[160:163], v[192:195], v[104:107]
	v_mfma_f32_16x16x32_bf16 v[92:95], v[152:155], v[200:203], v[92:95]
	v_mfma_f32_16x16x32_bf16 v[88:91], v[160:163], v[200:203], v[88:91]
	v_mfma_f32_16x16x32_bf16 v[76:79], v[152:155], v[208:211], v[76:79]
	v_mfma_f32_16x16x32_bf16 v[72:75], v[160:163], v[208:211], v[72:75]
	v_mfma_f32_16x16x32_bf16 v[120:123], v[156:159], v[188:191], v[120:123]
	v_mfma_f32_16x16x32_bf16 v[124:127], v[164:167], v[188:191], v[124:127]
	v_mfma_f32_16x16x32_bf16 v[108:111], v[156:159], v[196:199], v[108:111]
	v_mfma_f32_16x16x32_bf16 v[104:107], v[164:167], v[196:199], v[104:107]
	v_mfma_f32_16x16x32_bf16 v[92:95], v[156:159], v[204:207], v[92:95]
	v_mfma_f32_16x16x32_bf16 v[88:91], v[164:167], v[204:207], v[88:91]
	v_mfma_f32_16x16x32_bf16 v[76:79], v[156:159], v[212:215], v[76:79]
	v_mfma_f32_16x16x32_bf16 v[72:75], v[164:167], v[212:215], v[72:75]
	v_mfma_f32_16x16x32_bf16 v[116:119], v[168:171], v[184:187], v[116:119]
	v_mfma_f32_16x16x32_bf16 v[112:115], v[176:179], v[184:187], v[112:115]
	v_mfma_f32_16x16x32_bf16 v[100:103], v[168:171], v[192:195], v[100:103]
	v_mfma_f32_16x16x32_bf16 v[96:99], v[176:179], v[192:195], v[96:99]
	v_mfma_f32_16x16x32_bf16 v[84:87], v[168:171], v[200:203], v[84:87]
	v_mfma_f32_16x16x32_bf16 v[80:83], v[176:179], v[200:203], v[80:83]
	v_mfma_f32_16x16x32_bf16 v[68:71], v[168:171], v[208:211], v[68:71]
	v_mfma_f32_16x16x32_bf16 v[64:67], v[176:179], v[208:211], v[64:67]
	v_mfma_f32_16x16x32_bf16 v[116:119], v[172:175], v[188:191], v[116:119]
	v_mfma_f32_16x16x32_bf16 v[112:115], v[180:183], v[188:191], v[112:115]
	v_mfma_f32_16x16x32_bf16 v[100:103], v[172:175], v[196:199], v[100:103]
	v_mfma_f32_16x16x32_bf16 v[96:99], v[180:183], v[196:199], v[96:99]
	v_mfma_f32_16x16x32_bf16 v[84:87], v[172:175], v[204:207], v[84:87]
	v_mfma_f32_16x16x32_bf16 v[80:83], v[180:183], v[204:207], v[80:83]
	v_mfma_f32_16x16x32_bf16 v[68:71], v[172:175], v[212:215], v[68:71]
	v_mfma_f32_16x16x32_bf16 v[64:67], v[180:183], v[212:215], v[64:67]
	s_setprio 0
	s_barrier
; #define PG8_STAGE(bufoff, gbase, voff) do { _Pragma("unroll") for (int _i = 0; _i < 2; ++_i) \
;         __builtin_amdgcn_global_load_lds((const unsigned*)((const char*)(gbase) + (voff)[_i]), (LAS unsigned*)(lds + (bufoff) + ldsw + _i * 8192), 16, 0, 0); } while (0)
; #define PG8_LDA(dst, b, h) do { _Pragma("unroll") for (int m = 0; m < 4; ++m) _Pragma("unroll") for (int k = 0; k < 2; ++k) dst[m][k] = *(const LAS bf16x8*)(lds + PG8_SA(b, h) + aoff + m * 2048 + k * 1024); } while (0)
; #define PG8_MMA(ai, bj, At, Bt) do { __builtin_amdgcn_s_setprio(1); _Pragma("unroll") for (int m = 0; m < 4; ++m) _Pragma("unroll") for (int n = 0; n < 2; ++n) _Pragma("unroll") for (int k = 0; k < 2; ++k) \
;         acc[ai][bj][m][n] = __builtin_amdgcn_mfma_f32_16x16x32_bf16(Bt[n][k], At[m][k], acc[ai][bj][m][n], 0, 0, 0); __builtin_amdgcn_s_setprio(0); } while (0)
; #define PG8_WAIT_V(n) asm volatile("s_waitcnt vmcnt(" #n ")" ::: "memory")
; #define PG8_WAIT_L(n) asm volatile("s_waitcnt lgkmcnt(" #n ")" ::: "memory")
; #define PG8_BAR __builtin_amdgcn_s_barrier()
; #define PG8_SCHED __builtin_amdgcn_sched_barrier(0)
; template <class Epi>
; __device__ __forceinline__ void gemm_phase(LAS unsigned char* lds, const int tid, const Gemm g, const StaticOrder& S, const Epi& E) {
;     ...
;         for (int t = 0; t < nt; t += 2) {
;     ...
;             PG8_LDA(At, 1, 1); PG8_STAGE(PG8_SB(1, 0), b3, voffB); PG8_STAGE(PG8_SB(1, 1), b3 + hstepB, voffB); PG8_STAGE(PG8_SA(1, 0), a3, voffA);
;             PG8_WAIT_V(8); PG8_WAIT_L(0); PG8_BAR; PG8_MMA(1, 0, At, B0); PG8_MMA(1, 1, At, B1); PG8_BAR; PG8_SCHED;
	s_add_i32 s30, s57, s39
	v_lshl_add_u64 v[216:217], v[216:217], 0, s[10:11]
	s_mov_b32 m0, s30
	ds_read_b128 v[184:187], v150 offset:49152
	ds_read_b128 v[188:191], v150 offset:50176
	ds_read_b128 v[192:195], v150 offset:51200
	ds_read_b128 v[196:199], v150 offset:52224
	ds_read_b128 v[200:203], v150 offset:53248
	ds_read_b128 v[204:207], v150 offset:54272
	ds_read_b128 v[208:211], v150 offset:55296
	ds_read_b128 v[212:215], v150 offset:56320
	global_load_lds_dwordx4 v[216:217], off
	s_add_i32 m0, s30, 0x2000
	s_add_u32 s28, s28, 0x10080
	v_lshl_add_u64 v[216:217], v[218:219], 0, s[10:11]
	s_addc_u32 s29, s29, 0
	s_add_i32 s30, s58, s39
	global_load_lds_dwordx4 v[216:217], off
	v_lshl_add_u64 v[216:217], s[28:29], 0, v[130:131]
	s_mov_b32 m0, s30
	s_nop 0
	global_load_lds_dwordx4 v[216:217], off
	v_lshl_add_u64 v[216:217], s[28:29], 0, v[134:135]
	s_add_i32 m0, s30, 0x2000
	s_nop 0
	global_load_lds_dwordx4 v[216:217], off
	v_lshl_add_u64 v[216:217], v[220:221], 0, s[10:11]
	s_mov_b32 m0, s45
	s_nop 0
	global_load_lds_dwordx4 v[216:217], off
	v_lshl_add_u64 v[216:217], v[222:223], 0, s[10:11]
	s_mov_b32 m0, s46
	s_nop 0
	global_load_lds_dwordx4 v[216:217], off
	s_waitcnt vmcnt(8)
	s_waitcnt lgkmcnt(0)
	s_barrier
	s_setprio 1
	v_mfma_f32_16x16x32_bf16 v[60:63], v[152:155], v[184:187], v[60:63]
	v_mfma_f32_16x16x32_bf16 v[56:59], v[160:163], v[184:187], v[56:59]
	v_mfma_f32_16x16x32_bf16 v[44:47], v[152:155], v[192:195], v[44:47]
	v_mfma_f32_16x16x32_bf16 v[40:43], v[160:163], v[192:195], v[40:43]
	v_mfma_f32_16x16x32_bf16 v[28:31], v[152:155], v[200:203], v[28:31]
	v_mfma_f32_16x16x32_bf16 v[24:27], v[160:163], v[200:203], v[24:27]
	v_mfma_f32_16x16x32_bf16 v[12:15], v[152:155], v[208:211], v[12:15]
	v_mfma_f32_16x16x32_bf16 v[8:11], v[160:163], v[208:211], v[8:11]
	v_mfma_f32_16x16x32_bf16 v[60:63], v[156:159], v[188:191], v[60:63]
	v_mfma_f32_16x16x32_bf16 v[56:59], v[164:167], v[188:191], v[56:59]
	v_mfma_f32_16x16x32_bf16 v[44:47], v[156:159], v[196:199], v[44:47]
	v_mfma_f32_16x16x32_bf16 v[40:43], v[164:167], v[196:199], v[40:43]
	v_mfma_f32_16x16x32_bf16 v[28:31], v[156:159], v[204:207], v[28:31]
	v_mfma_f32_16x16x32_bf16 v[24:27], v[164:167], v[204:207], v[24:27]
	v_mfma_f32_16x16x32_bf16 v[12:15], v[156:159], v[212:215], v[12:15]
	v_mfma_f32_16x16x32_bf16 v[8:11], v[164:167], v[212:215], v[8:11]
	v_mfma_f32_16x16x32_bf16 v[52:55], v[168:171], v[184:187], v[52:55]
	v_mfma_f32_16x16x32_bf16 v[48:51], v[176:179], v[184:187], v[48:51]
	v_mfma_f32_16x16x32_bf16 v[36:39], v[168:171], v[192:195], v[36:39]
	v_mfma_f32_16x16x32_bf16 v[32:35], v[176:179], v[192:195], v[32:35]
	v_mfma_f32_16x16x32_bf16 v[20:23], v[168:171], v[200:203], v[20:23]
	v_mfma_f32_16x16x32_bf16 v[16:19], v[176:179], v[200:203], v[16:19]
	v_mfma_f32_16x16x32_bf16 v[4:7], v[168:171], v[208:211], v[4:7]
	v_mfma_f32_16x16x32_bf16 v[0:3], v[176:179], v[208:211], v[0:3]
	v_mfma_f32_16x16x32_bf16 v[52:55], v[172:175], v[188:191], v[52:55]
	v_mfma_f32_16x16x32_bf16 v[48:51], v[180:183], v[188:191], v[48:51]
	v_mfma_f32_16x16x32_bf16 v[36:39], v[172:175], v[196:199], v[36:39]
	v_mfma_f32_16x16x32_bf16 v[32:35], v[180:183], v[196:199], v[32:35]
	v_mfma_f32_16x16x32_bf16 v[20:23], v[172:175], v[204:207], v[20:23]
	v_mfma_f32_16x16x32_bf16 v[16:19], v[180:183], v[204:207], v[16:19]
	v_mfma_f32_16x16x32_bf16 v[4:7], v[172:175], v[212:215], v[4:7]
	v_mfma_f32_16x16x32_bf16 v[0:3], v[180:183], v[212:215], v[0:3]
	s_setprio 0
	s_barrier
	s_add_u32 s54, s54, 0x100
	s_addc_u32 s55, s55, 0
	s_add_u32 s26, s26, 0x100
	s_addc_u32 s27, s27, 0
	s_cmp_ge_i32 s56, s44
	s_mov_b32 s28, s56
	s_cbranch_scc0 .LBB0_949

; #define LAS __attribute__((address_space(3)))
; #define PG8_STAGE(bufoff, gbase, voff) do { _Pragma("unroll") for (int _i = 0; _i < 2; ++_i) \
;         __builtin_amdgcn_global_load_lds((const unsigned*)((const char*)(gbase) + (voff)[_i]), (LAS unsigned*)(lds + (bufoff) + ldsw + _i * 8192), 16, 0, 0); } while (0)
; #define PG8_LDA(dst, b, h) do { _Pragma("unroll") for (int m = 0; m < 4; ++m) _Pragma("unroll") for (int k = 0; k < 2; ++k) dst[m][k] = *(const LAS bf16x8*)(lds + PG8_SA(b, h) + aoff + m * 2048 + k * 1024); } while (0)
; #define PG8_LDB(dst, b, h) do { _Pragma("unroll") for (int n = 0; n < 2; ++n) _Pragma("unroll") for (int k = 0; k < 2; ++k) dst[n][k] = *(const LAS bf16x8*)(lds + PG8_SB(b, h) + boff + n * 2048 + k * 1024); } while (0)
; #define PG8_WAIT_V(n) asm volatile("s_waitcnt vmcnt(" #n ")" ::: "memory")
; #define PG8_WAIT_L(n) asm volatile("s_waitcnt lgkmcnt(" #n ")" ::: "memory")
; #define PG8_BAR __builtin_amdgcn_s_barrier()
; template <class Epi>
; __device__ __forceinline__ void gemm_phase(LAS unsigned char* lds, const int tid, const Gemm g, const StaticOrder& S, const Epi& E) {
;     ...
;             const bool last = (t == nt - 2);
;             const char* a1 = cA + (size_t)(t + 1) * kstep;
;             const char* a2 = last ? nA : cA + (size_t)(t + 2) * kstep; const char* b2 = last ? nB : cB + (size_t)(t + 2) * kstep;
;             const char* a3 = a2 + kstep; const char* b3 = b2 + kstep;
;             if constexpr (Epi::SS_LDS) { if (last) {
;                 const char* sp = (const char*)E.ss + (size_t)cur.pm * (256 * 64) + (size_t)tid * 16;
;                 __builtin_amdgcn_global_load_lds((const unsigned*)sp, (LAS unsigned*)(lds + RS_OFF + ldsw), 16, 0, 0);
;                 __builtin_amdgcn_global_load_lds((const unsigned*)(sp + 8192), (LAS unsigned*)(lds + RS_OFF + 8192 + ldsw), 16, 0, 0); } }
;     ...
;             PG8_LDB(B0, 0, 0); PG8_LDB(B1, 0, 1); PG8_SCHED; PG8_LDA(At, 0, 0); PG8_STAGE(PG8_SA(1, 1), a1 + hstepA, voffA);
;             PG8_WAIT_V(8); PG8_WAIT_L(0); PG8_BAR; PG8_MMA(0, 0, At, B0); PG8_MMA(0, 1, At, B1); PG8_BAR; PG8_SCHED;
;             PG8_LDA(At, 0, 1); PG8_STAGE(PG8_SB(0, 0), b2, voffB); PG8_STAGE(PG8_SB(0, 1), b2 + hstepB, voffB); PG8_STAGE(PG8_SA(0, 0), a2, voffA);
;             PG8_WAIT_V(8); PG8_WAIT_L(0); PG8_BAR; PG8_MMA(1, 0, At, B0); PG8_MMA(1, 1, At, B1); PG8_BAR; PG8_SCHED;
.LBB0_1032:
	v_add_u32_e32 v144, s59, v209
	v_add_u32_e32 v160, s60, v209
	ds_read_b128 v[132:135], v144
	ds_read_b128 v[136:139], v144 offset:1024
	ds_read_b128 v[140:143], v144 offset:2048
	ds_read_b128 v[144:147], v144 offset:3072
	ds_read_b128 v[148:151], v160
	ds_read_b128 v[152:155], v160 offset:1024
	ds_read_b128 v[156:159], v160 offset:2048
	ds_read_b128 v[160:163], v160 offset:3072
	s_add_i32 s64, s64, 2
	s_add_u32 s42, s38, 0xfffc0080
	s_addc_u32 s43, s39, -1
	s_and_b64 s[40:41], s[40:41], exec
	s_cselect_b32 s43, s27, s43
	s_cselect_b32 s42, s29, s42
	s_cselect_b32 s41, s33, s63
	s_cselect_b32 s40, s62, s37
	v_lshl_add_u64 v[206:207], s[38:39], 0, v[192:193]
	s_add_i32 m0, s48, 0xc000
	ds_read_b128 v[164:167], v211
	ds_read_b128 v[168:171], v211 offset:1024
	ds_read_b128 v[172:175], v211 offset:2048
	ds_read_b128 v[176:179], v211 offset:3072
	ds_read_b128 v[198:201], v211 offset:4096
	ds_read_b128 v[202:205], v211 offset:5120
	ds_read_b128 v[214:217], v211 offset:6144
	ds_read_b128 v[218:221], v211 offset:7168
	global_load_lds_dwordx4 v[206:207], off
	v_lshl_add_u64 v[206:207], s[38:39], 0, v[190:191]
	s_add_i32 m0, s48, 0xe000
	s_nop 0
	global_load_lds_dwordx4 v[206:207], off
	s_waitcnt vmcnt(8)
	s_waitcnt lgkmcnt(0)
	s_barrier
	s_setprio 1
	v_mfma_f32_16x16x32_bf16 v[124:127], v[132:135], v[164:167], v[124:127]
	v_mfma_f32_16x16x32_bf16 v[120:123], v[140:143], v[164:167], v[120:123]
	v_mfma_f32_16x16x32_bf16 v[108:111], v[132:135], v[172:175], v[108:111]
	v_mfma_f32_16x16x32_bf16 v[104:107], v[140:143], v[172:175], v[104:107]
	v_mfma_f32_16x16x32_bf16 v[92:95], v[132:135], v[198:201], v[92:95]
	v_mfma_f32_16x16x32_bf16 v[88:91], v[140:143], v[198:201], v[88:91]
	v_mfma_f32_16x16x32_bf16 v[76:79], v[132:135], v[214:217], v[76:79]
	v_mfma_f32_16x16x32_bf16 v[72:75], v[140:143], v[214:217], v[72:75]
	v_mfma_f32_16x16x32_bf16 v[124:127], v[136:139], v[168:171], v[124:127]
	v_mfma_f32_16x16x32_bf16 v[120:123], v[144:147], v[168:171], v[120:123]
	v_mfma_f32_16x16x32_bf16 v[108:111], v[136:139], v[176:179], v[108:111]
	v_mfma_f32_16x16x32_bf16 v[104:107], v[144:147], v[176:179], v[104:107]
	v_mfma_f32_16x16x32_bf16 v[92:95], v[136:139], v[202:205], v[92:95]
	v_mfma_f32_16x16x32_bf16 v[88:91], v[144:147], v[202:205], v[88:91]
	v_mfma_f32_16x16x32_bf16 v[76:79], v[136:139], v[218:221], v[76:79]
	v_mfma_f32_16x16x32_bf16 v[72:75], v[144:147], v[218:221], v[72:75]
	v_mfma_f32_16x16x32_bf16 v[116:119], v[148:151], v[164:167], v[116:119]
	v_mfma_f32_16x16x32_bf16 v[112:115], v[156:159], v[164:167], v[112:115]
	v_mfma_f32_16x16x32_bf16 v[100:103], v[148:151], v[172:175], v[100:103]
	v_mfma_f32_16x16x32_bf16 v[96:99], v[156:159], v[172:175], v[96:99]
	v_mfma_f32_16x16x32_bf16 v[84:87], v[148:151], v[198:201], v[84:87]
	v_mfma_f32_16x16x32_bf16 v[80:83], v[156:159], v[198:201], v[80:83]
	v_mfma_f32_16x16x32_bf16 v[68:71], v[148:151], v[214:217], v[68:71]
	v_mfma_f32_16x16x32_bf16 v[64:67], v[156:159], v[214:217], v[64:67]
	v_mfma_f32_16x16x32_bf16 v[116:119], v[152:155], v[168:171], v[116:119]
	v_mfma_f32_16x16x32_bf16 v[112:115], v[160:163], v[168:171], v[112:115]
	v_mfma_f32_16x16x32_bf16 v[100:103], v[152:155], v[176:179], v[100:103]
	v_mfma_f32_16x16x32_bf16 v[96:99], v[160:163], v[176:179], v[96:99]
	v_mfma_f32_16x16x32_bf16 v[84:87], v[152:155], v[202:205], v[84:87]
	v_mfma_f32_16x16x32_bf16 v[80:83], v[160:163], v[202:205], v[80:83]
	v_mfma_f32_16x16x32_bf16 v[68:71], v[152:155], v[218:221], v[68:71]
	v_mfma_f32_16x16x32_bf16 v[64:67], v[160:163], v[218:221], v[64:67]
	s_setprio 0
	s_barrier
	s_add_i32 s65, s59, s47
	v_lshl_add_u64 v[206:207], s[40:41], 0, v[182:183]
	s_mov_b32 m0, s65
	ds_read_b128 v[164:167], v211 offset:16384
	ds_read_b128 v[168:171], v211 offset:17408
	ds_read_b128 v[172:175], v211 offset:18432
	ds_read_b128 v[176:179], v211 offset:19456
	ds_read_b128 v[198:201], v211 offset:20480
	ds_read_b128 v[202:205], v211 offset:21504
	ds_read_b128 v[214:217], v211 offset:22528
	ds_read_b128 v[218:221], v211 offset:23552
	global_load_lds_dwordx4 v[206:207], off
	s_add_i32 m0, s65, 0x2000
	s_add_u32 s66, s40, 0x40000
	v_lshl_add_u64 v[222:223], s[40:41], 0, v[186:187]
	s_addc_u32 s67, s41, 0
	s_add_i32 s65, s60, s47
	global_load_lds_dwordx4 v[222:223], off
	v_lshl_add_u64 v[224:225], s[66:67], 0, v[182:183]
	s_mov_b32 m0, s65
	v_lshl_add_u64 v[226:227], s[42:43], 0, v[184:185]
	global_load_lds_dwordx4 v[224:225], off
	v_lshl_add_u64 v[224:225], s[66:67], 0, v[186:187]
	s_add_i32 m0, s65, 0x2000
	s_nop 0
	global_load_lds_dwordx4 v[224:225], off
	v_lshl_add_u64 v[224:225], s[42:43], 0, v[180:181]
	s_mov_b32 m0, s48
	s_nop 0
	global_load_lds_dwordx4 v[224:225], off
	s_mov_b32 m0, s49
	s_nop 0
	global_load_lds_dwordx4 v[226:227], off
	s_waitcnt vmcnt(8)
	s_waitcnt lgkmcnt(0)
	s_barrier
; #define PG8_STAGE(bufoff, gbase, voff) do { _Pragma("unroll") for (int _i = 0; _i < 2; ++_i) \
;         __builtin_amdgcn_global_load_lds((const unsigned*)((const char*)(gbase) + (voff)[_i]), (LAS unsigned*)(lds + (bufoff) + ldsw + _i * 8192), 16, 0, 0); } while (0)
; #define PG8_LDA(dst, b, h) do { _Pragma("unroll") for (int m = 0; m < 4; ++m) _Pragma("unroll") for (int k = 0; k < 2; ++k) dst[m][k] = *(const LAS bf16x8*)(lds + PG8_SA(b, h) + aoff + m * 2048 + k * 1024); } while (0)
; #define PG8_LDB(dst, b, h) do { _Pragma("unroll") for (int n = 0; n < 2; ++n) _Pragma("unroll") for (int k = 0; k < 2; ++k) dst[n][k] = *(const LAS bf16x8*)(lds + PG8_SB(b, h) + boff + n * 2048 + k * 1024); } while (0)
; #define PG8_MMA(ai, bj, At, Bt) do { __builtin_amdgcn_s_setprio(1); _Pragma("unroll") for (int m = 0; m < 4; ++m) _Pragma("unroll") for (int n = 0; n < 2; ++n) _Pragma("unroll") for (int k = 0; k < 2; ++k) \
;         acc[ai][bj][m][n] = __builtin_amdgcn_mfma_f32_16x16x32_bf16(Bt[n][k], At[m][k], acc[ai][bj][m][n], 0, 0, 0); __builtin_amdgcn_s_setprio(0); } while (0)
; #define PG8_WAIT_V(n) asm volatile("s_waitcnt vmcnt(" #n ")" ::: "memory")
; #define PG8_WAIT_L(n) asm volatile("s_waitcnt lgkmcnt(" #n ")" ::: "memory")
; #define PG8_BAR __builtin_amdgcn_s_barrier()
; #define PG8_SCHED __builtin_amdgcn_sched_barrier(0)
; template <class Epi>
; __device__ __forceinline__ void gemm_phase(LAS unsigned char* lds, const int tid, const Gemm g, const StaticOrder& S, const Epi& E) {
;     ...
;             PG8_WAIT_V(8); PG8_WAIT_L(0); PG8_BAR; PG8_MMA(1, 0, At, B0); PG8_MMA(1, 1, At, B1); PG8_BAR; PG8_SCHED;
;             PG8_LDB(B0, 1, 0); PG8_LDB(B1, 1, 1); PG8_SCHED; PG8_LDA(At, 1, 0); PG8_STAGE(PG8_SA(0, 1), a2 + hstepA, voffA);
;             PG8_WAIT_V(8); PG8_WAIT_L(0); PG8_BAR; PG8_MMA(0, 0, At, B0); PG8_MMA(0, 1, At, B1); PG8_BAR; PG8_SCHED;
	s_setprio 1
	v_mfma_f32_16x16x32_bf16 v[60:63], v[132:135], v[164:167], v[60:63]
	v_mfma_f32_16x16x32_bf16 v[56:59], v[140:143], v[164:167], v[56:59]
	v_mfma_f32_16x16x32_bf16 v[44:47], v[132:135], v[172:175], v[44:47]
	v_mfma_f32_16x16x32_bf16 v[40:43], v[140:143], v[172:175], v[40:43]
	v_mfma_f32_16x16x32_bf16 v[28:31], v[132:135], v[198:201], v[28:31]
	v_mfma_f32_16x16x32_bf16 v[24:27], v[140:143], v[198:201], v[24:27]
	v_mfma_f32_16x16x32_bf16 v[12:15], v[132:135], v[214:217], v[12:15]
	v_mfma_f32_16x16x32_bf16 v[8:11], v[140:143], v[214:217], v[8:11]
	v_mfma_f32_16x16x32_bf16 v[60:63], v[136:139], v[168:171], v[60:63]
	v_mfma_f32_16x16x32_bf16 v[56:59], v[144:147], v[168:171], v[56:59]
	v_mfma_f32_16x16x32_bf16 v[44:47], v[136:139], v[176:179], v[44:47]
	v_mfma_f32_16x16x32_bf16 v[40:43], v[144:147], v[176:179], v[40:43]
	v_mfma_f32_16x16x32_bf16 v[28:31], v[136:139], v[202:205], v[28:31]
	v_mfma_f32_16x16x32_bf16 v[24:27], v[144:147], v[202:205], v[24:27]
	v_mfma_f32_16x16x32_bf16 v[12:15], v[136:139], v[218:221], v[12:15]
	v_mfma_f32_16x16x32_bf16 v[8:11], v[144:147], v[218:221], v[8:11]
	v_mfma_f32_16x16x32_bf16 v[52:55], v[148:151], v[164:167], v[52:55]
	v_mfma_f32_16x16x32_bf16 v[48:51], v[156:159], v[164:167], v[48:51]
	v_mfma_f32_16x16x32_bf16 v[36:39], v[148:151], v[172:175], v[36:39]
	v_mfma_f32_16x16x32_bf16 v[32:35], v[156:159], v[172:175], v[32:35]
	v_mfma_f32_16x16x32_bf16 v[20:23], v[148:151], v[198:201], v[20:23]
	v_mfma_f32_16x16x32_bf16 v[16:19], v[156:159], v[198:201], v[16:19]
	v_mfma_f32_16x16x32_bf16 v[4:7], v[148:151], v[214:217], v[4:7]
	v_mfma_f32_16x16x32_bf16 v[0:3], v[156:159], v[214:217], v[0:3]
	v_mfma_f32_16x16x32_bf16 v[52:55], v[152:155], v[168:171], v[52:55]
	v_mfma_f32_16x16x32_bf16 v[48:51], v[160:163], v[168:171], v[48:51]
	v_mfma_f32_16x16x32_bf16 v[36:39], v[152:155], v[176:179], v[36:39]
	v_mfma_f32_16x16x32_bf16 v[32:35], v[160:163], v[176:179], v[32:35]
	v_mfma_f32_16x16x32_bf16 v[20:23], v[152:155], v[202:205], v[20:23]
	v_mfma_f32_16x16x32_bf16 v[16:19], v[160:163], v[202:205], v[16:19]
	v_mfma_f32_16x16x32_bf16 v[4:7], v[152:155], v[218:221], v[4:7]
	v_mfma_f32_16x16x32_bf16 v[0:3], v[160:163], v[218:221], v[0:3]
	s_setprio 0
	s_barrier
	s_add_i32 s65, 0, 0x18000
	s_add_i32 s66, 0, 0x1c000
	v_add_u32_e32 v144, s65, v209
	v_add_u32_e32 v160, s66, v209
	ds_read_b128 v[132:135], v144
	ds_read_b128 v[136:139], v144 offset:1024
	ds_read_b128 v[140:143], v144 offset:2048
	ds_read_b128 v[144:147], v144 offset:3072
	ds_read_b128 v[148:151], v160
	ds_read_b128 v[152:155], v160 offset:1024
	ds_read_b128 v[156:159], v160 offset:2048
	ds_read_b128 v[160:163], v160 offset:3072
	s_add_u32 s42, s42, 0x40000
	s_addc_u32 s43, s43, 0
	s_mov_b32 m0, s50
	v_lshl_add_u64 v[228:229], s[42:43], 0, v[180:181]
	ds_read_b128 v[164:167], v211 offset:32768
	ds_read_b128 v[168:171], v211 offset:33792
	ds_read_b128 v[172:175], v211 offset:34816
	ds_read_b128 v[176:179], v211 offset:35840
	ds_read_b128 v[198:201], v211 offset:36864
	ds_read_b128 v[202:205], v211 offset:37888
	ds_read_b128 v[214:217], v211 offset:38912
	ds_read_b128 v[218:221], v211 offset:39936
	global_load_lds_dwordx4 v[228:229], off
	v_lshl_add_u64 v[228:229], s[42:43], 0, v[184:185]
	s_mov_b32 m0, s51
	s_nop 0
	global_load_lds_dwordx4 v[228:229], off
	s_waitcnt vmcnt(8)
	s_waitcnt lgkmcnt(0)
	s_barrier
	s_setprio 1
	v_mfma_f32_16x16x32_bf16 v[124:127], v[132:135], v[164:167], v[124:127]
	v_mfma_f32_16x16x32_bf16 v[120:123], v[140:143], v[164:167], v[120:123]
	v_mfma_f32_16x16x32_bf16 v[108:111], v[132:135], v[172:175], v[108:111]
	v_mfma_f32_16x16x32_bf16 v[104:107], v[140:143], v[172:175], v[104:107]
	v_mfma_f32_16x16x32_bf16 v[92:95], v[132:135], v[198:201], v[92:95]
	v_mfma_f32_16x16x32_bf16 v[88:91], v[140:143], v[198:201], v[88:91]
	v_mfma_f32_16x16x32_bf16 v[76:79], v[132:135], v[214:217], v[76:79]
	v_mfma_f32_16x16x32_bf16 v[72:75], v[140:143], v[214:217], v[72:75]
	v_mfma_f32_16x16x32_bf16 v[124:127], v[136:139], v[168:171], v[124:127]
	v_mfma_f32_16x16x32_bf16 v[120:123], v[144:147], v[168:171], v[120:123]
	v_mfma_f32_16x16x32_bf16 v[108:111], v[136:139], v[176:179], v[108:111]
	v_mfma_f32_16x16x32_bf16 v[104:107], v[144:147], v[176:179], v[104:107]
	v_mfma_f32_16x16x32_bf16 v[92:95], v[136:139], v[202:205], v[92:95]
	v_mfma_f32_16x16x32_bf16 v[88:91], v[144:147], v[202:205], v[88:91]
	v_mfma_f32_16x16x32_bf16 v[76:79], v[136:139], v[218:221], v[76:79]
	v_mfma_f32_16x16x32_bf16 v[72:75], v[144:147], v[218:221], v[72:75]
	v_mfma_f32_16x16x32_bf16 v[116:119], v[148:151], v[164:167], v[116:119]
	v_mfma_f32_16x16x32_bf16 v[112:115], v[156:159], v[164:167], v[112:115]
	v_mfma_f32_16x16x32_bf16 v[100:103], v[148:151], v[172:175], v[100:103]
	v_mfma_f32_16x16x32_bf16 v[96:99], v[156:159], v[172:175], v[96:99]
	v_mfma_f32_16x16x32_bf16 v[84:87], v[148:151], v[198:201], v[84:87]
	v_mfma_f32_16x16x32_bf16 v[80:83], v[156:159], v[198:201], v[80:83]
	v_mfma_f32_16x16x32_bf16 v[68:71], v[148:151], v[214:217], v[68:71]
	v_mfma_f32_16x16x32_bf16 v[64:67], v[156:159], v[214:217], v[64:67]
	v_mfma_f32_16x16x32_bf16 v[116:119], v[152:155], v[168:171], v[116:119]
	v_mfma_f32_16x16x32_bf16 v[112:115], v[160:163], v[168:171], v[112:115]
	v_mfma_f32_16x16x32_bf16 v[100:103], v[152:155], v[176:179], v[100:103]
	v_mfma_f32_16x16x32_bf16 v[96:99], v[160:163], v[176:179], v[96:99]
	v_mfma_f32_16x16x32_bf16 v[84:87], v[152:155], v[202:205], v[84:87]
	v_mfma_f32_16x16x32_bf16 v[80:83], v[160:163], v[202:205], v[80:83]
	v_mfma_f32_16x16x32_bf16 v[68:71], v[152:155], v[218:221], v[68:71]
	v_mfma_f32_16x16x32_bf16 v[64:67], v[160:163], v[218:221], v[64:67]
	s_setprio 0
	s_barrier
; #define PG8_STAGE(bufoff, gbase, voff) do { _Pragma("unroll") for (int _i = 0; _i < 2; ++_i) \
;         __builtin_amdgcn_global_load_lds((const unsigned*)((const char*)(gbase) + (voff)[_i]), (LAS unsigned*)(lds + (bufoff) + ldsw + _i * 8192), 16, 0, 0); } while (0)
; #define PG8_LDA(dst, b, h) do { _Pragma("unroll") for (int m = 0; m < 4; ++m) _Pragma("unroll") for (int k = 0; k < 2; ++k) dst[m][k] = *(const LAS bf16x8*)(lds + PG8_SA(b, h) + aoff + m * 2048 + k * 1024); } while (0)
; #define PG8_MMA(ai, bj, At, Bt) do { __builtin_amdgcn_s_setprio(1); _Pragma("unroll") for (int m = 0; m < 4; ++m) _Pragma("unroll") for (int n = 0; n < 2; ++n) _Pragma("unroll") for (int k = 0; k < 2; ++k) \
;         acc[ai][bj][m][n] = __builtin_amdgcn_mfma_f32_16x16x32_bf16(Bt[n][k], At[m][k], acc[ai][bj][m][n], 0, 0, 0); __builtin_amdgcn_s_setprio(0); } while (0)
; #define PG8_WAIT_V(n) asm volatile("s_waitcnt vmcnt(" #n ")" ::: "memory")
; #define PG8_WAIT_L(n) asm volatile("s_waitcnt lgkmcnt(" #n ")" ::: "memory")
; #define PG8_BAR __builtin_amdgcn_s_barrier()
; #define PG8_SCHED __builtin_amdgcn_sched_barrier(0)
; template <class Epi>
; __device__ __forceinline__ void gemm_phase(LAS unsigned char* lds, const int tid, const Gemm g, const StaticOrder& S, const Epi& E) {
;     ...
;         for (int t = 0; t < nt; t += 2) {
;     ...
;             PG8_LDA(At, 1, 1); PG8_STAGE(PG8_SB(1, 0), b3, voffB); PG8_STAGE(PG8_SB(1, 1), b3 + hstepB, voffB); PG8_STAGE(PG8_SA(1, 0), a3, voffA);
;             PG8_WAIT_V(8); PG8_WAIT_L(0); PG8_BAR; PG8_MMA(1, 0, At, B0); PG8_MMA(1, 1, At, B1); PG8_BAR; PG8_SCHED;
	s_add_i32 s42, s65, s47
	v_lshl_add_u64 v[206:207], v[206:207], 0, s[20:21]
	s_mov_b32 m0, s42
	ds_read_b128 v[164:167], v211 offset:49152
	ds_read_b128 v[168:171], v211 offset:50176
	ds_read_b128 v[172:175], v211 offset:51200
	ds_read_b128 v[176:179], v211 offset:52224
	ds_read_b128 v[198:201], v211 offset:53248
	ds_read_b128 v[202:205], v211 offset:54272
	ds_read_b128 v[214:217], v211 offset:55296
	ds_read_b128 v[218:221], v211 offset:56320
	global_load_lds_dwordx4 v[206:207], off
	s_add_i32 m0, s42, 0x2000
	s_add_u32 s40, s40, 0x40080
	v_lshl_add_u64 v[206:207], v[222:223], 0, s[20:21]
	s_addc_u32 s41, s41, 0
	s_add_i32 s42, s66, s47
	global_load_lds_dwordx4 v[206:207], off
	v_lshl_add_u64 v[206:207], s[40:41], 0, v[182:183]
	s_mov_b32 m0, s42
	s_nop 0
	global_load_lds_dwordx4 v[206:207], off
	v_lshl_add_u64 v[206:207], s[40:41], 0, v[186:187]
	s_add_i32 m0, s42, 0x2000
	s_nop 0
	global_load_lds_dwordx4 v[206:207], off
	v_lshl_add_u64 v[206:207], v[224:225], 0, s[20:21]
	s_mov_b32 m0, s54
	s_nop 0
	global_load_lds_dwordx4 v[206:207], off
	v_lshl_add_u64 v[206:207], v[226:227], 0, s[20:21]
	s_mov_b32 m0, s55
	s_nop 0
	global_load_lds_dwordx4 v[206:207], off
	s_waitcnt vmcnt(8)
	s_waitcnt lgkmcnt(0)
	s_barrier
	s_setprio 1
	v_mfma_f32_16x16x32_bf16 v[60:63], v[132:135], v[164:167], v[60:63]
	v_mfma_f32_16x16x32_bf16 v[56:59], v[140:143], v[164:167], v[56:59]
	v_mfma_f32_16x16x32_bf16 v[44:47], v[132:135], v[172:175], v[44:47]
	v_mfma_f32_16x16x32_bf16 v[40:43], v[140:143], v[172:175], v[40:43]
	v_mfma_f32_16x16x32_bf16 v[28:31], v[132:135], v[198:201], v[28:31]
	v_mfma_f32_16x16x32_bf16 v[24:27], v[140:143], v[198:201], v[24:27]
	v_mfma_f32_16x16x32_bf16 v[12:15], v[132:135], v[214:217], v[12:15]
	v_mfma_f32_16x16x32_bf16 v[8:11], v[140:143], v[214:217], v[8:11]
	v_mfma_f32_16x16x32_bf16 v[60:63], v[136:139], v[168:171], v[60:63]
	v_mfma_f32_16x16x32_bf16 v[56:59], v[144:147], v[168:171], v[56:59]
	v_mfma_f32_16x16x32_bf16 v[44:47], v[136:139], v[176:179], v[44:47]
	v_mfma_f32_16x16x32_bf16 v[40:43], v[144:147], v[176:179], v[40:43]
	v_mfma_f32_16x16x32_bf16 v[28:31], v[136:139], v[202:205], v[28:31]
	v_mfma_f32_16x16x32_bf16 v[24:27], v[144:147], v[202:205], v[24:27]
	v_mfma_f32_16x16x32_bf16 v[12:15], v[136:139], v[218:221], v[12:15]
	v_mfma_f32_16x16x32_bf16 v[8:11], v[144:147], v[218:221], v[8:11]
	v_mfma_f32_16x16x32_bf16 v[52:55], v[148:151], v[164:167], v[52:55]
	v_mfma_f32_16x16x32_bf16 v[48:51], v[156:159], v[164:167], v[48:51]
	v_mfma_f32_16x16x32_bf16 v[36:39], v[148:151], v[172:175], v[36:39]
	v_mfma_f32_16x16x32_bf16 v[32:35], v[156:159], v[172:175], v[32:35]
	v_mfma_f32_16x16x32_bf16 v[20:23], v[148:151], v[198:201], v[20:23]
	v_mfma_f32_16x16x32_bf16 v[16:19], v[156:159], v[198:201], v[16:19]
	v_mfma_f32_16x16x32_bf16 v[4:7], v[148:151], v[214:217], v[4:7]
	v_mfma_f32_16x16x32_bf16 v[0:3], v[156:159], v[214:217], v[0:3]
	v_mfma_f32_16x16x32_bf16 v[52:55], v[152:155], v[168:171], v[52:55]
	v_mfma_f32_16x16x32_bf16 v[48:51], v[160:163], v[168:171], v[48:51]
	v_mfma_f32_16x16x32_bf16 v[36:39], v[152:155], v[176:179], v[36:39]
	v_mfma_f32_16x16x32_bf16 v[32:35], v[160:163], v[176:179], v[32:35]
	v_mfma_f32_16x16x32_bf16 v[20:23], v[152:155], v[202:205], v[20:23]
	v_mfma_f32_16x16x32_bf16 v[16:19], v[160:163], v[202:205], v[16:19]
	v_mfma_f32_16x16x32_bf16 v[4:7], v[152:155], v[218:221], v[4:7]
	v_mfma_f32_16x16x32_bf16 v[0:3], v[160:163], v[218:221], v[0:3]
	s_setprio 0
	s_barrier
	s_add_u32 s37, s37, 0x100
	s_addc_u32 s63, s63, 0
	s_add_u32 s38, s38, 0x100
	s_addc_u32 s39, s39, 0
	s_cmp_ge_i32 s64, s53
	s_cbranch_scc1 .LBB0_1035

; #define LAS __attribute__((address_space(3)))
; #define PG8_STAGE(bufoff, gbase, voff) do { _Pragma("unroll") for (int _i = 0; _i < 2; ++_i) \
;         __builtin_amdgcn_global_load_lds((const unsigned*)((const char*)(gbase) + (voff)[_i]), (LAS unsigned*)(lds + (bufoff) + ldsw + _i * 8192), 16, 0, 0); } while (0)
; #define PG8_LDA(dst, b, h) do { _Pragma("unroll") for (int m = 0; m < 4; ++m) _Pragma("unroll") for (int k = 0; k < 2; ++k) dst[m][k] = *(const LAS bf16x8*)(lds + PG8_SA(b, h) + aoff + m * 2048 + k * 1024); } while (0)
; #define PG8_LDB(dst, b, h) do { _Pragma("unroll") for (int n = 0; n < 2; ++n) _Pragma("unroll") for (int k = 0; k < 2; ++k) dst[n][k] = *(const LAS bf16x8*)(lds + PG8_SB(b, h) + boff + n * 2048 + k * 1024); } while (0)
; #define PG8_WAIT_V(n) asm volatile("s_waitcnt vmcnt(" #n ")" ::: "memory")
; #define PG8_WAIT_L(n) asm volatile("s_waitcnt lgkmcnt(" #n ")" ::: "memory")
; #define PG8_BAR __builtin_amdgcn_s_barrier()
; template <class Epi>
; __device__ __forceinline__ void gemm_phase(LAS unsigned char* lds, const int tid, const Gemm g, const StaticOrder& S, const Epi& E) {
;     ...
;             const bool last = (t == nt - 2);
;             const char* a1 = cA + (size_t)(t + 1) * kstep;
;             const char* a2 = last ? nA : cA + (size_t)(t + 2) * kstep; const char* b2 = last ? nB : cB + (size_t)(t + 2) * kstep;
;             const char* a3 = a2 + kstep; const char* b3 = b2 + kstep;
;             if constexpr (Epi::SS_LDS) { if (last) {
;                 const char* sp = (const char*)E.ss + (size_t)cur.pm * (256 * 64) + (size_t)tid * 16;
;                 __builtin_amdgcn_global_load_lds((const unsigned*)sp, (LAS unsigned*)(lds + RS_OFF + ldsw), 16, 0, 0);
;                 __builtin_amdgcn_global_load_lds((const unsigned*)(sp + 8192), (LAS unsigned*)(lds + RS_OFF + 8192 + ldsw), 16, 0, 0); } }
;     ...
;             PG8_LDB(B0, 0, 0); PG8_LDB(B1, 0, 1); PG8_SCHED; PG8_LDA(At, 0, 0); PG8_STAGE(PG8_SA(1, 1), a1 + hstepA, voffA);
;             PG8_WAIT_V(8); PG8_WAIT_L(0); PG8_BAR; PG8_MMA(0, 0, At, B0); PG8_MMA(0, 1, At, B1); PG8_BAR; PG8_SCHED;
;             PG8_LDA(At, 0, 1); PG8_STAGE(PG8_SB(0, 0), b2, voffB); PG8_STAGE(PG8_SB(0, 1), b2 + hstepB, voffB); PG8_STAGE(PG8_SA(0, 0), a2, voffA);
;             PG8_WAIT_V(8); PG8_WAIT_L(0); PG8_BAR; PG8_MMA(1, 0, At, B0); PG8_MMA(1, 1, At, B1); PG8_BAR; PG8_SCHED;
.LBB0_1312:
	v_add_u32_e32 v161, s52, v157
	ds_read_b128 v[152:155], v161
	ds_read_b128 v[162:165], v161 offset:1024
	ds_read_b128 v[166:169], v161 offset:2048
	ds_read_b128 v[170:173], v161 offset:3072
	v_add_u32_e32 v161, s53, v157
	ds_read_b128 v[174:177], v161
	ds_read_b128 v[178:181], v161 offset:1024
	ds_read_b128 v[182:185], v161 offset:2048
	ds_read_b128 v[186:189], v161 offset:3072
	s_add_i32 s58, s58, 2
	s_add_u32 s34, s28, 0xfffc0080
	s_addc_u32 s35, s29, -1
	s_and_b64 s[30:31], s[30:31], exec
	s_cselect_b32 s35, s19, s35
	s_cselect_b32 s34, s21, s34
	s_cselect_b32 s31, s33, s57
	s_cselect_b32 s30, s56, s5
	v_lshl_add_u64 v[222:223], s[28:29], 0, v[142:143]
	s_add_i32 m0, s27, 0xc000
	ds_read_b128 v[190:193], v158
	ds_read_b128 v[194:197], v158 offset:1024
	ds_read_b128 v[198:201], v158 offset:2048
	ds_read_b128 v[202:205], v158 offset:3072
	ds_read_b128 v[206:209], v158 offset:4096
	ds_read_b128 v[210:213], v158 offset:5120
	ds_read_b128 v[214:217], v158 offset:6144
	ds_read_b128 v[218:221], v158 offset:7168
	global_load_lds_dwordx4 v[222:223], off
	v_lshl_add_u64 v[222:223], s[28:29], 0, v[140:141]
	s_add_i32 m0, s27, 0xe000
	s_nop 0
	global_load_lds_dwordx4 v[222:223], off
	s_waitcnt vmcnt(8)
	s_waitcnt lgkmcnt(0)
	s_barrier
	s_setprio 1
	v_mfma_f32_16x16x32_bf16 v[124:127], v[152:155], v[190:193], v[124:127]
	v_mfma_f32_16x16x32_bf16 v[120:123], v[166:169], v[190:193], v[120:123]
	v_mfma_f32_16x16x32_bf16 v[108:111], v[152:155], v[198:201], v[108:111]
	v_mfma_f32_16x16x32_bf16 v[104:107], v[166:169], v[198:201], v[104:107]
	v_mfma_f32_16x16x32_bf16 v[92:95], v[152:155], v[206:209], v[92:95]
	v_mfma_f32_16x16x32_bf16 v[88:91], v[166:169], v[206:209], v[88:91]
	v_mfma_f32_16x16x32_bf16 v[76:79], v[152:155], v[214:217], v[76:79]
	v_mfma_f32_16x16x32_bf16 v[72:75], v[166:169], v[214:217], v[72:75]
	v_mfma_f32_16x16x32_bf16 v[124:127], v[162:165], v[194:197], v[124:127]
	v_mfma_f32_16x16x32_bf16 v[120:123], v[170:173], v[194:197], v[120:123]
	v_mfma_f32_16x16x32_bf16 v[108:111], v[162:165], v[202:205], v[108:111]
	v_mfma_f32_16x16x32_bf16 v[104:107], v[170:173], v[202:205], v[104:107]
	v_mfma_f32_16x16x32_bf16 v[92:95], v[162:165], v[210:213], v[92:95]
	v_mfma_f32_16x16x32_bf16 v[88:91], v[170:173], v[210:213], v[88:91]
	v_mfma_f32_16x16x32_bf16 v[76:79], v[162:165], v[218:221], v[76:79]
	v_mfma_f32_16x16x32_bf16 v[72:75], v[170:173], v[218:221], v[72:75]
	v_mfma_f32_16x16x32_bf16 v[116:119], v[174:177], v[190:193], v[116:119]
	v_mfma_f32_16x16x32_bf16 v[112:115], v[182:185], v[190:193], v[112:115]
	v_mfma_f32_16x16x32_bf16 v[100:103], v[174:177], v[198:201], v[100:103]
	v_mfma_f32_16x16x32_bf16 v[96:99], v[182:185], v[198:201], v[96:99]
	v_mfma_f32_16x16x32_bf16 v[84:87], v[174:177], v[206:209], v[84:87]
	v_mfma_f32_16x16x32_bf16 v[80:83], v[182:185], v[206:209], v[80:83]
	v_mfma_f32_16x16x32_bf16 v[68:71], v[174:177], v[214:217], v[68:71]
	v_mfma_f32_16x16x32_bf16 v[64:67], v[182:185], v[214:217], v[64:67]
	v_mfma_f32_16x16x32_bf16 v[116:119], v[178:181], v[194:197], v[116:119]
	v_mfma_f32_16x16x32_bf16 v[112:115], v[186:189], v[194:197], v[112:115]
	v_mfma_f32_16x16x32_bf16 v[100:103], v[178:181], v[202:205], v[100:103]
	v_mfma_f32_16x16x32_bf16 v[96:99], v[186:189], v[202:205], v[96:99]
	v_mfma_f32_16x16x32_bf16 v[84:87], v[178:181], v[210:213], v[84:87]
	v_mfma_f32_16x16x32_bf16 v[80:83], v[186:189], v[210:213], v[80:83]
	v_mfma_f32_16x16x32_bf16 v[68:71], v[178:181], v[218:221], v[68:71]
	v_mfma_f32_16x16x32_bf16 v[64:67], v[186:189], v[218:221], v[64:67]
	s_setprio 0
	s_barrier
	s_add_i32 s59, s52, s41
	v_lshl_add_u64 v[222:223], s[30:31], 0, v[130:131]
	s_mov_b32 m0, s59
	ds_read_b128 v[190:193], v158 offset:16384
	ds_read_b128 v[194:197], v158 offset:17408
	ds_read_b128 v[198:201], v158 offset:18432
	ds_read_b128 v[202:205], v158 offset:19456
	ds_read_b128 v[206:209], v158 offset:20480
	ds_read_b128 v[210:213], v158 offset:21504
	ds_read_b128 v[214:217], v158 offset:22528
	ds_read_b128 v[218:221], v158 offset:23552
	global_load_lds_dwordx4 v[222:223], off
	s_add_i32 m0, s59, 0x2000
	s_add_u32 s60, s30, 0x40000
	v_lshl_add_u64 v[224:225], s[30:31], 0, v[134:135]
	s_addc_u32 s61, s31, 0
	s_add_i32 s59, s53, s41
	global_load_lds_dwordx4 v[224:225], off
	v_lshl_add_u64 v[226:227], s[60:61], 0, v[130:131]
	s_mov_b32 m0, s59
	v_lshl_add_u64 v[228:229], s[34:35], 0, v[132:133]
	global_load_lds_dwordx4 v[226:227], off
	v_lshl_add_u64 v[226:227], s[60:61], 0, v[134:135]
	s_add_i32 m0, s59, 0x2000
	s_nop 0
	global_load_lds_dwordx4 v[226:227], off
	v_lshl_add_u64 v[226:227], s[34:35], 0, v[128:129]
	s_mov_b32 m0, s27
	s_nop 0
	global_load_lds_dwordx4 v[226:227], off
	s_mov_b32 m0, s42
	s_nop 0
	global_load_lds_dwordx4 v[228:229], off
	s_waitcnt vmcnt(8)
	s_waitcnt lgkmcnt(0)
	s_barrier
; #define PG8_STAGE(bufoff, gbase, voff) do { _Pragma("unroll") for (int _i = 0; _i < 2; ++_i) \
;         __builtin_amdgcn_global_load_lds((const unsigned*)((const char*)(gbase) + (voff)[_i]), (LAS unsigned*)(lds + (bufoff) + ldsw + _i * 8192), 16, 0, 0); } while (0)
; #define PG8_LDA(dst, b, h) do { _Pragma("unroll") for (int m = 0; m < 4; ++m) _Pragma("unroll") for (int k = 0; k < 2; ++k) dst[m][k] = *(const LAS bf16x8*)(lds + PG8_SA(b, h) + aoff + m * 2048 + k * 1024); } while (0)
; #define PG8_LDB(dst, b, h) do { _Pragma("unroll") for (int n = 0; n < 2; ++n) _Pragma("unroll") for (int k = 0; k < 2; ++k) dst[n][k] = *(const LAS bf16x8*)(lds + PG8_SB(b, h) + boff + n * 2048 + k * 1024); } while (0)
; #define PG8_MMA(ai, bj, At, Bt) do { __builtin_amdgcn_s_setprio(1); _Pragma("unroll") for (int m = 0; m < 4; ++m) _Pragma("unroll") for (int n = 0; n < 2; ++n) _Pragma("unroll") for (int k = 0; k < 2; ++k) \
;         acc[ai][bj][m][n] = __builtin_amdgcn_mfma_f32_16x16x32_bf16(Bt[n][k], At[m][k], acc[ai][bj][m][n], 0, 0, 0); __builtin_amdgcn_s_setprio(0); } while (0)
; #define PG8_WAIT_V(n) asm volatile("s_waitcnt vmcnt(" #n ")" ::: "memory")
; #define PG8_WAIT_L(n) asm volatile("s_waitcnt lgkmcnt(" #n ")" ::: "memory")
; #define PG8_BAR __builtin_amdgcn_s_barrier()
; #define PG8_SCHED __builtin_amdgcn_sched_barrier(0)
; template <class Epi>
; __device__ __forceinline__ void gemm_phase(LAS unsigned char* lds, const int tid, const Gemm g, const StaticOrder& S, const Epi& E) {
;     ...
;             PG8_WAIT_V(8); PG8_WAIT_L(0); PG8_BAR; PG8_MMA(1, 0, At, B0); PG8_MMA(1, 1, At, B1); PG8_BAR; PG8_SCHED;
;             PG8_LDB(B0, 1, 0); PG8_LDB(B1, 1, 1); PG8_SCHED; PG8_LDA(At, 1, 0); PG8_STAGE(PG8_SA(0, 1), a2 + hstepA, voffA);
;             PG8_WAIT_V(8); PG8_WAIT_L(0); PG8_BAR; PG8_MMA(0, 0, At, B0); PG8_MMA(0, 1, At, B1); PG8_BAR; PG8_SCHED;
	s_setprio 1
	v_mfma_f32_16x16x32_bf16 v[60:63], v[152:155], v[190:193], v[60:63]
	v_mfma_f32_16x16x32_bf16 v[56:59], v[166:169], v[190:193], v[56:59]
	v_mfma_f32_16x16x32_bf16 v[44:47], v[152:155], v[198:201], v[44:47]
	v_mfma_f32_16x16x32_bf16 v[40:43], v[166:169], v[198:201], v[40:43]
	v_mfma_f32_16x16x32_bf16 v[28:31], v[152:155], v[206:209], v[28:31]
	v_mfma_f32_16x16x32_bf16 v[24:27], v[166:169], v[206:209], v[24:27]
	v_mfma_f32_16x16x32_bf16 v[12:15], v[152:155], v[214:217], v[12:15]
	v_mfma_f32_16x16x32_bf16 v[8:11], v[166:169], v[214:217], v[8:11]
	v_mfma_f32_16x16x32_bf16 v[60:63], v[162:165], v[194:197], v[60:63]
	v_mfma_f32_16x16x32_bf16 v[56:59], v[170:173], v[194:197], v[56:59]
	v_mfma_f32_16x16x32_bf16 v[44:47], v[162:165], v[202:205], v[44:47]
	v_mfma_f32_16x16x32_bf16 v[40:43], v[170:173], v[202:205], v[40:43]
	v_mfma_f32_16x16x32_bf16 v[28:31], v[162:165], v[210:213], v[28:31]
	v_mfma_f32_16x16x32_bf16 v[24:27], v[170:173], v[210:213], v[24:27]
	v_mfma_f32_16x16x32_bf16 v[12:15], v[162:165], v[218:221], v[12:15]
	v_mfma_f32_16x16x32_bf16 v[8:11], v[170:173], v[218:221], v[8:11]
	v_mfma_f32_16x16x32_bf16 v[52:55], v[174:177], v[190:193], v[52:55]
	v_mfma_f32_16x16x32_bf16 v[48:51], v[182:185], v[190:193], v[48:51]
	v_mfma_f32_16x16x32_bf16 v[36:39], v[174:177], v[198:201], v[36:39]
	v_mfma_f32_16x16x32_bf16 v[32:35], v[182:185], v[198:201], v[32:35]
	v_mfma_f32_16x16x32_bf16 v[20:23], v[174:177], v[206:209], v[20:23]
	v_mfma_f32_16x16x32_bf16 v[16:19], v[182:185], v[206:209], v[16:19]
	v_mfma_f32_16x16x32_bf16 v[4:7], v[174:177], v[214:217], v[4:7]
	v_mfma_f32_16x16x32_bf16 v[0:3], v[182:185], v[214:217], v[0:3]
	v_mfma_f32_16x16x32_bf16 v[52:55], v[178:181], v[194:197], v[52:55]
	v_mfma_f32_16x16x32_bf16 v[48:51], v[186:189], v[194:197], v[48:51]
	v_mfma_f32_16x16x32_bf16 v[36:39], v[178:181], v[202:205], v[36:39]
	v_mfma_f32_16x16x32_bf16 v[32:35], v[186:189], v[202:205], v[32:35]
	v_mfma_f32_16x16x32_bf16 v[20:23], v[178:181], v[210:213], v[20:23]
	v_mfma_f32_16x16x32_bf16 v[16:19], v[186:189], v[210:213], v[16:19]
	v_mfma_f32_16x16x32_bf16 v[4:7], v[178:181], v[218:221], v[4:7]
	v_mfma_f32_16x16x32_bf16 v[0:3], v[186:189], v[218:221], v[0:3]
	s_setprio 0
	s_barrier
	s_add_i32 s59, 0, 0x18000
	v_add_u32_e32 v161, s59, v157
	s_add_i32 s60, 0, 0x1c000
	ds_read_b128 v[152:155], v161
	ds_read_b128 v[162:165], v161 offset:1024
	ds_read_b128 v[166:169], v161 offset:2048
	ds_read_b128 v[170:173], v161 offset:3072
	v_add_u32_e32 v161, s60, v157
	ds_read_b128 v[174:177], v161
	ds_read_b128 v[178:181], v161 offset:1024
	ds_read_b128 v[182:185], v161 offset:2048
	ds_read_b128 v[186:189], v161 offset:3072
	s_add_u32 s34, s34, 0x40000
	s_addc_u32 s35, s35, 0
	s_mov_b32 m0, s43
	v_lshl_add_u64 v[230:231], s[34:35], 0, v[128:129]
	ds_read_b128 v[190:193], v158 offset:32768
	ds_read_b128 v[194:197], v158 offset:33792
	ds_read_b128 v[198:201], v158 offset:34816
	ds_read_b128 v[202:205], v158 offset:35840
	ds_read_b128 v[206:209], v158 offset:36864
	ds_read_b128 v[210:213], v158 offset:37888
	ds_read_b128 v[214:217], v158 offset:38912
	ds_read_b128 v[218:221], v158 offset:39936
	global_load_lds_dwordx4 v[230:231], off
	v_lshl_add_u64 v[230:231], s[34:35], 0, v[132:133]
	s_mov_b32 m0, s44
	s_nop 0
	global_load_lds_dwordx4 v[230:231], off
	s_waitcnt vmcnt(8)
	s_waitcnt lgkmcnt(0)
	s_barrier
	s_setprio 1
	v_mfma_f32_16x16x32_bf16 v[124:127], v[152:155], v[190:193], v[124:127]
	v_mfma_f32_16x16x32_bf16 v[120:123], v[166:169], v[190:193], v[120:123]
	v_mfma_f32_16x16x32_bf16 v[108:111], v[152:155], v[198:201], v[108:111]
	v_mfma_f32_16x16x32_bf16 v[104:107], v[166:169], v[198:201], v[104:107]
	v_mfma_f32_16x16x32_bf16 v[92:95], v[152:155], v[206:209], v[92:95]
	v_mfma_f32_16x16x32_bf16 v[88:91], v[166:169], v[206:209], v[88:91]
	v_mfma_f32_16x16x32_bf16 v[76:79], v[152:155], v[214:217], v[76:79]
	v_mfma_f32_16x16x32_bf16 v[72:75], v[166:169], v[214:217], v[72:75]
	v_mfma_f32_16x16x32_bf16 v[124:127], v[162:165], v[194:197], v[124:127]
	v_mfma_f32_16x16x32_bf16 v[120:123], v[170:173], v[194:197], v[120:123]
	v_mfma_f32_16x16x32_bf16 v[108:111], v[162:165], v[202:205], v[108:111]
	v_mfma_f32_16x16x32_bf16 v[104:107], v[170:173], v[202:205], v[104:107]
	v_mfma_f32_16x16x32_bf16 v[92:95], v[162:165], v[210:213], v[92:95]
	v_mfma_f32_16x16x32_bf16 v[88:91], v[170:173], v[210:213], v[88:91]
	v_mfma_f32_16x16x32_bf16 v[76:79], v[162:165], v[218:221], v[76:79]
	v_mfma_f32_16x16x32_bf16 v[72:75], v[170:173], v[218:221], v[72:75]
	v_mfma_f32_16x16x32_bf16 v[116:119], v[174:177], v[190:193], v[116:119]
	v_mfma_f32_16x16x32_bf16 v[112:115], v[182:185], v[190:193], v[112:115]
	v_mfma_f32_16x16x32_bf16 v[100:103], v[174:177], v[198:201], v[100:103]
	v_mfma_f32_16x16x32_bf16 v[96:99], v[182:185], v[198:201], v[96:99]
	v_mfma_f32_16x16x32_bf16 v[84:87], v[174:177], v[206:209], v[84:87]
	v_mfma_f32_16x16x32_bf16 v[80:83], v[182:185], v[206:209], v[80:83]
	v_mfma_f32_16x16x32_bf16 v[68:71], v[174:177], v[214:217], v[68:71]
	v_mfma_f32_16x16x32_bf16 v[64:67], v[182:185], v[214:217], v[64:67]
	v_mfma_f32_16x16x32_bf16 v[116:119], v[178:181], v[194:197], v[116:119]
	v_mfma_f32_16x16x32_bf16 v[112:115], v[186:189], v[194:197], v[112:115]
	v_mfma_f32_16x16x32_bf16 v[100:103], v[178:181], v[202:205], v[100:103]
	v_mfma_f32_16x16x32_bf16 v[96:99], v[186:189], v[202:205], v[96:99]
	v_mfma_f32_16x16x32_bf16 v[84:87], v[178:181], v[210:213], v[84:87]
	v_mfma_f32_16x16x32_bf16 v[80:83], v[186:189], v[210:213], v[80:83]
	v_mfma_f32_16x16x32_bf16 v[68:71], v[178:181], v[218:221], v[68:71]
	v_mfma_f32_16x16x32_bf16 v[64:67], v[186:189], v[218:221], v[64:67]
	s_setprio 0
	s_barrier
; #define PG8_STAGE(bufoff, gbase, voff) do { _Pragma("unroll") for (int _i = 0; _i < 2; ++_i) \
;         __builtin_amdgcn_global_load_lds((const unsigned*)((const char*)(gbase) + (voff)[_i]), (LAS unsigned*)(lds + (bufoff) + ldsw + _i * 8192), 16, 0, 0); } while (0)
; #define PG8_LDA(dst, b, h) do { _Pragma("unroll") for (int m = 0; m < 4; ++m) _Pragma("unroll") for (int k = 0; k < 2; ++k) dst[m][k] = *(const LAS bf16x8*)(lds + PG8_SA(b, h) + aoff + m * 2048 + k * 1024); } while (0)
; #define PG8_MMA(ai, bj, At, Bt) do { __builtin_amdgcn_s_setprio(1); _Pragma("unroll") for (int m = 0; m < 4; ++m) _Pragma("unroll") for (int n = 0; n < 2; ++n) _Pragma("unroll") for (int k = 0; k < 2; ++k) \
;         acc[ai][bj][m][n] = __builtin_amdgcn_mfma_f32_16x16x32_bf16(Bt[n][k], At[m][k], acc[ai][bj][m][n], 0, 0, 0); __builtin_amdgcn_s_setprio(0); } while (0)
; #define PG8_WAIT_V(n) asm volatile("s_waitcnt vmcnt(" #n ")" ::: "memory")
; #define PG8_WAIT_L(n) asm volatile("s_waitcnt lgkmcnt(" #n ")" ::: "memory")
; #define PG8_BAR __builtin_amdgcn_s_barrier()
; #define PG8_SCHED __builtin_amdgcn_sched_barrier(0)
; template <class Epi>
; __device__ __forceinline__ void gemm_phase(LAS unsigned char* lds, const int tid, const Gemm g, const StaticOrder& S, const Epi& E) {
;     ...
;         for (int t = 0; t < nt; t += 2) {
;     ...
;             PG8_LDA(At, 1, 1); PG8_STAGE(PG8_SB(1, 0), b3, voffB); PG8_STAGE(PG8_SB(1, 1), b3 + hstepB, voffB); PG8_STAGE(PG8_SA(1, 0), a3, voffA);
;             PG8_WAIT_V(8); PG8_WAIT_L(0); PG8_BAR; PG8_MMA(1, 0, At, B0); PG8_MMA(1, 1, At, B1); PG8_BAR; PG8_SCHED;
	s_add_i32 s34, s59, s41
	v_lshl_add_u64 v[222:223], v[222:223], 0, s[10:11]
	s_mov_b32 m0, s34
	ds_read_b128 v[190:193], v158 offset:49152
	ds_read_b128 v[194:197], v158 offset:50176
	ds_read_b128 v[198:201], v158 offset:51200
	ds_read_b128 v[202:205], v158 offset:52224
	ds_read_b128 v[206:209], v158 offset:53248
	ds_read_b128 v[210:213], v158 offset:54272
	ds_read_b128 v[214:217], v158 offset:55296
	ds_read_b128 v[218:221], v158 offset:56320
	global_load_lds_dwordx4 v[222:223], off
	s_add_i32 m0, s34, 0x2000
	s_add_u32 s30, s30, 0x40080
	v_lshl_add_u64 v[222:223], v[224:225], 0, s[10:11]
	s_addc_u32 s31, s31, 0
	s_add_i32 s34, s60, s41
	global_load_lds_dwordx4 v[222:223], off
	v_lshl_add_u64 v[222:223], s[30:31], 0, v[130:131]
	s_mov_b32 m0, s34
	s_nop 0
	global_load_lds_dwordx4 v[222:223], off
	v_lshl_add_u64 v[222:223], s[30:31], 0, v[134:135]
	s_add_i32 m0, s34, 0x2000
	s_nop 0
	global_load_lds_dwordx4 v[222:223], off
	v_lshl_add_u64 v[222:223], v[226:227], 0, s[10:11]
	s_mov_b32 m0, s47
	s_nop 0
	global_load_lds_dwordx4 v[222:223], off
	v_lshl_add_u64 v[222:223], v[228:229], 0, s[10:11]
	s_mov_b32 m0, s48
	s_nop 0
	global_load_lds_dwordx4 v[222:223], off
	s_waitcnt vmcnt(8)
	s_waitcnt lgkmcnt(0)
	s_barrier
	s_setprio 1
	v_mfma_f32_16x16x32_bf16 v[60:63], v[152:155], v[190:193], v[60:63]
	v_mfma_f32_16x16x32_bf16 v[56:59], v[166:169], v[190:193], v[56:59]
	v_mfma_f32_16x16x32_bf16 v[44:47], v[152:155], v[198:201], v[44:47]
	v_mfma_f32_16x16x32_bf16 v[40:43], v[166:169], v[198:201], v[40:43]
	v_mfma_f32_16x16x32_bf16 v[28:31], v[152:155], v[206:209], v[28:31]
	v_mfma_f32_16x16x32_bf16 v[24:27], v[166:169], v[206:209], v[24:27]
	v_mfma_f32_16x16x32_bf16 v[12:15], v[152:155], v[214:217], v[12:15]
	v_mfma_f32_16x16x32_bf16 v[8:11], v[166:169], v[214:217], v[8:11]
	v_mfma_f32_16x16x32_bf16 v[60:63], v[162:165], v[194:197], v[60:63]
	v_mfma_f32_16x16x32_bf16 v[56:59], v[170:173], v[194:197], v[56:59]
	v_mfma_f32_16x16x32_bf16 v[44:47], v[162:165], v[202:205], v[44:47]
	v_mfma_f32_16x16x32_bf16 v[40:43], v[170:173], v[202:205], v[40:43]
	v_mfma_f32_16x16x32_bf16 v[28:31], v[162:165], v[210:213], v[28:31]
	v_mfma_f32_16x16x32_bf16 v[24:27], v[170:173], v[210:213], v[24:27]
	v_mfma_f32_16x16x32_bf16 v[12:15], v[162:165], v[218:221], v[12:15]
	v_mfma_f32_16x16x32_bf16 v[8:11], v[170:173], v[218:221], v[8:11]
	v_mfma_f32_16x16x32_bf16 v[52:55], v[174:177], v[190:193], v[52:55]
	v_mfma_f32_16x16x32_bf16 v[48:51], v[182:185], v[190:193], v[48:51]
	v_mfma_f32_16x16x32_bf16 v[36:39], v[174:177], v[198:201], v[36:39]
	v_mfma_f32_16x16x32_bf16 v[32:35], v[182:185], v[198:201], v[32:35]
	v_mfma_f32_16x16x32_bf16 v[20:23], v[174:177], v[206:209], v[20:23]
	v_mfma_f32_16x16x32_bf16 v[16:19], v[182:185], v[206:209], v[16:19]
	v_mfma_f32_16x16x32_bf16 v[4:7], v[174:177], v[214:217], v[4:7]
	v_mfma_f32_16x16x32_bf16 v[0:3], v[182:185], v[214:217], v[0:3]
	v_mfma_f32_16x16x32_bf16 v[52:55], v[178:181], v[194:197], v[52:55]
	v_mfma_f32_16x16x32_bf16 v[48:51], v[186:189], v[194:197], v[48:51]
	v_mfma_f32_16x16x32_bf16 v[36:39], v[178:181], v[202:205], v[36:39]
	v_mfma_f32_16x16x32_bf16 v[32:35], v[186:189], v[202:205], v[32:35]
	v_mfma_f32_16x16x32_bf16 v[20:23], v[178:181], v[210:213], v[20:23]
	v_mfma_f32_16x16x32_bf16 v[16:19], v[186:189], v[210:213], v[16:19]
	v_mfma_f32_16x16x32_bf16 v[4:7], v[178:181], v[218:221], v[4:7]
	v_mfma_f32_16x16x32_bf16 v[0:3], v[186:189], v[218:221], v[0:3]
	s_setprio 0
	s_barrier
	s_add_u32 s5, s5, 0x100
	s_addc_u32 s57, s57, 0
	s_add_u32 s28, s28, 0x100
	s_addc_u32 s29, s29, 0
	s_cmp_ge_i32 s58, s46
	s_cbranch_scc1 .LBB0_1315

; #define LAS __attribute__((address_space(3)))
; #define PG8_STAGE(bufoff, gbase, voff) do { _Pragma("unroll") for (int _i = 0; _i < 2; ++_i) \
;         __builtin_amdgcn_global_load_lds((const unsigned*)((const char*)(gbase) + (voff)[_i]), (LAS unsigned*)(lds + (bufoff) + ldsw + _i * 8192), 16, 0, 0); } while (0)
; #define PG8_LDA(dst, b, h) do { _Pragma("unroll") for (int m = 0; m < 4; ++m) _Pragma("unroll") for (int k = 0; k < 2; ++k) dst[m][k] = *(const LAS bf16x8*)(lds + PG8_SA(b, h) + aoff + m * 2048 + k * 1024); } while (0)
; #define PG8_LDB(dst, b, h) do { _Pragma("unroll") for (int n = 0; n < 2; ++n) _Pragma("unroll") for (int k = 0; k < 2; ++k) dst[n][k] = *(const LAS bf16x8*)(lds + PG8_SB(b, h) + boff + n * 2048 + k * 1024); } while (0)
; #define PG8_WAIT_V(n) asm volatile("s_waitcnt vmcnt(" #n ")" ::: "memory")
; #define PG8_WAIT_L(n) asm volatile("s_waitcnt lgkmcnt(" #n ")" ::: "memory")
; #define PG8_BAR __builtin_amdgcn_s_barrier()
; template <class Epi>
; __device__ __forceinline__ void gemm_phase(LAS unsigned char* lds, const int tid, const Gemm g, const StaticOrder& S, const Epi& E) {
;     ...
;             const bool last = (t == nt - 2);
;             const char* a1 = cA + (size_t)(t + 1) * kstep;
;             const char* a2 = last ? nA : cA + (size_t)(t + 2) * kstep; const char* b2 = last ? nB : cB + (size_t)(t + 2) * kstep;
;             const char* a3 = a2 + kstep; const char* b3 = b2 + kstep;
;             if constexpr (Epi::SS_LDS) { if (last) {
;                 const char* sp = (const char*)E.ss + (size_t)cur.pm * (256 * 64) + (size_t)tid * 16;
;                 __builtin_amdgcn_global_load_lds((const unsigned*)sp, (LAS unsigned*)(lds + RS_OFF + ldsw), 16, 0, 0);
;                 __builtin_amdgcn_global_load_lds((const unsigned*)(sp + 8192), (LAS unsigned*)(lds + RS_OFF + 8192 + ldsw), 16, 0, 0); } }
;     ...
;             PG8_LDB(B0, 0, 0); PG8_LDB(B1, 0, 1); PG8_SCHED; PG8_LDA(At, 0, 0); PG8_STAGE(PG8_SA(1, 1), a1 + hstepA, voffA);
;             PG8_WAIT_V(8); PG8_WAIT_L(0); PG8_BAR; PG8_MMA(0, 0, At, B0); PG8_MMA(0, 1, At, B1); PG8_BAR; PG8_SCHED;
;             PG8_LDA(At, 0, 1); PG8_STAGE(PG8_SB(0, 0), b2, voffB); PG8_STAGE(PG8_SB(0, 1), b2 + hstepB, voffB); PG8_STAGE(PG8_SA(0, 0), a2, voffA);
;             PG8_WAIT_V(8); PG8_WAIT_L(0); PG8_BAR; PG8_MMA(1, 0, At, B0); PG8_MMA(1, 1, At, B1); PG8_BAR; PG8_SCHED;
.LBB0_1525:
	ds_read_b128 v[40:43], v217
	ds_read_b128 v[48:51], v217 offset:1024
	ds_read_b128 v[52:55], v217 offset:2048
	ds_read_b128 v[60:63], v217 offset:3072
	ds_read_b128 v[64:67], v218
	ds_read_b128 v[68:71], v218 offset:1024
	ds_read_b128 v[80:83], v218 offset:2048
	ds_read_b128 v[100:103], v218 offset:3072
	s_add_i32 s64, s38, 2
	s_add_u32 s39, s36, 0xfffc0080
	s_addc_u32 s40, s37, -1
	s_cmp_eq_u32 s55, s38
	s_cselect_b32 s38, s61, s62
	s_cselect_b32 s41, s27, s40
	s_cselect_b32 s40, s29, s39
	s_cselect_b32 s39, s33, s63
	v_lshl_add_u64 v[208:209], s[36:37], 0, v[190:191]
	s_add_i32 m0, s47, 0xc000
	ds_read_b128 v[120:123], v219
	ds_read_b128 v[140:143], v219 offset:1024
	ds_read_b128 v[160:163], v219 offset:2048
	ds_read_b128 v[172:175], v219 offset:3072
	ds_read_b128 v[176:179], v219 offset:4096
	ds_read_b128 v[196:199], v219 offset:5120
	ds_read_b128 v[200:203], v219 offset:6144
	ds_read_b128 v[204:207], v219 offset:7168
	global_load_lds_dwordx4 v[208:209], off
	v_lshl_add_u64 v[208:209], s[36:37], 0, v[188:189]
	s_add_i32 m0, s47, 0xe000
	s_nop 0
	global_load_lds_dwordx4 v[208:209], off
	s_waitcnt vmcnt(8)
	s_waitcnt lgkmcnt(0)
	s_barrier
	s_setprio 1
	v_mfma_f32_16x16x32_bf16 v[168:171], v[40:43], v[120:123], v[168:171]
	v_mfma_f32_16x16x32_bf16 v[156:159], v[52:55], v[120:123], v[156:159]
	v_mfma_f32_16x16x32_bf16 v[148:151], v[40:43], v[160:163], v[148:151]
	v_mfma_f32_16x16x32_bf16 v[136:139], v[52:55], v[160:163], v[136:139]
	v_mfma_f32_16x16x32_bf16 v[128:131], v[40:43], v[176:179], v[128:131]
	v_mfma_f32_16x16x32_bf16 v[116:119], v[52:55], v[176:179], v[116:119]
	v_mfma_f32_16x16x32_bf16 v[108:111], v[40:43], v[200:203], v[108:111]
	v_mfma_f32_16x16x32_bf16 v[96:99], v[52:55], v[200:203], v[96:99]
	v_mfma_f32_16x16x32_bf16 v[168:171], v[48:51], v[140:143], v[168:171]
	v_mfma_f32_16x16x32_bf16 v[156:159], v[60:63], v[140:143], v[156:159]
	v_mfma_f32_16x16x32_bf16 v[148:151], v[48:51], v[172:175], v[148:151]
	v_mfma_f32_16x16x32_bf16 v[136:139], v[60:63], v[172:175], v[136:139]
	v_mfma_f32_16x16x32_bf16 v[128:131], v[48:51], v[196:199], v[128:131]
	v_mfma_f32_16x16x32_bf16 v[116:119], v[60:63], v[196:199], v[116:119]
	v_mfma_f32_16x16x32_bf16 v[108:111], v[48:51], v[204:207], v[108:111]
	v_mfma_f32_16x16x32_bf16 v[96:99], v[60:63], v[204:207], v[96:99]
	v_mfma_f32_16x16x32_bf16 v[164:167], v[64:67], v[120:123], v[164:167]
	v_mfma_f32_16x16x32_bf16 v[120:123], v[80:83], v[120:123], v[152:155]
	v_mfma_f32_16x16x32_bf16 v[132:135], v[80:83], v[160:163], v[132:135]
	v_mfma_f32_16x16x32_bf16 v[124:127], v[64:67], v[176:179], v[124:127]
	v_mfma_f32_16x16x32_bf16 v[112:115], v[80:83], v[176:179], v[112:115]
	v_mfma_f32_16x16x32_bf16 v[104:107], v[64:67], v[200:203], v[104:107]
	v_mfma_f32_16x16x32_bf16 v[92:95], v[80:83], v[200:203], v[92:95]
	v_mfma_f32_16x16x32_bf16 v[164:167], v[68:71], v[140:143], v[164:167]
	v_mfma_f32_16x16x32_bf16 v[120:123], v[100:103], v[140:143], v[120:123]
	v_mfma_f32_16x16x32_bf16 v[140:143], v[64:67], v[160:163], v[144:147]
	v_mfma_f32_16x16x32_bf16 v[132:135], v[100:103], v[172:175], v[132:135]
	v_mfma_f32_16x16x32_bf16 v[124:127], v[68:71], v[196:199], v[124:127]
	v_mfma_f32_16x16x32_bf16 v[112:115], v[100:103], v[196:199], v[112:115]
	v_mfma_f32_16x16x32_bf16 v[104:107], v[68:71], v[204:207], v[104:107]
	v_mfma_f32_16x16x32_bf16 v[92:95], v[100:103], v[204:207], v[92:95]
	v_mfma_f32_16x16x32_bf16 v[140:143], v[68:71], v[172:175], v[140:143]
	s_setprio 0
	s_barrier
	s_add_i32 s65, s57, s46
	v_lshl_add_u64 v[212:213], s[38:39], 0, v[182:183]
	s_mov_b32 m0, s65
	ds_read_b128 v[144:147], v219 offset:16384
	ds_read_b128 v[152:155], v219 offset:17408
	ds_read_b128 v[160:163], v219 offset:18432
	ds_read_b128 v[172:175], v219 offset:19456
	ds_read_b128 v[176:179], v219 offset:20480
	ds_read_b128 v[196:199], v219 offset:21504
	ds_read_b128 v[200:203], v219 offset:22528
	ds_read_b128 v[204:207], v219 offset:23552
	global_load_lds_dwordx4 v[212:213], off
	s_add_i32 m0, s65, 0x2000
	s_add_u32 s66, s38, 0x10000
	v_lshl_add_u64 v[226:227], s[38:39], 0, v[186:187]
	s_addc_u32 s67, s39, 0
	s_add_i32 s65, s58, s46
	global_load_lds_dwordx4 v[226:227], off
	v_lshl_add_u64 v[208:209], s[66:67], 0, v[182:183]
	s_mov_b32 m0, s65
	v_lshl_add_u64 v[228:229], s[40:41], 0, v[180:181]
	global_load_lds_dwordx4 v[208:209], off
	v_lshl_add_u64 v[208:209], s[66:67], 0, v[186:187]
	s_add_i32 m0, s65, 0x2000
	v_lshl_add_u64 v[230:231], s[40:41], 0, v[184:185]
	global_load_lds_dwordx4 v[208:209], off
	s_mov_b32 m0, s47
	s_nop 0
	global_load_lds_dwordx4 v[228:229], off
	s_mov_b32 m0, s48
	s_nop 0
	global_load_lds_dwordx4 v[230:231], off
	s_waitcnt vmcnt(8)
	s_waitcnt lgkmcnt(0)
	s_barrier
; #define PG8_STAGE(bufoff, gbase, voff) do { _Pragma("unroll") for (int _i = 0; _i < 2; ++_i) \
;         __builtin_amdgcn_global_load_lds((const unsigned*)((const char*)(gbase) + (voff)[_i]), (LAS unsigned*)(lds + (bufoff) + ldsw + _i * 8192), 16, 0, 0); } while (0)
; #define PG8_LDA(dst, b, h) do { _Pragma("unroll") for (int m = 0; m < 4; ++m) _Pragma("unroll") for (int k = 0; k < 2; ++k) dst[m][k] = *(const LAS bf16x8*)(lds + PG8_SA(b, h) + aoff + m * 2048 + k * 1024); } while (0)
; #define PG8_LDB(dst, b, h) do { _Pragma("unroll") for (int n = 0; n < 2; ++n) _Pragma("unroll") for (int k = 0; k < 2; ++k) dst[n][k] = *(const LAS bf16x8*)(lds + PG8_SB(b, h) + boff + n * 2048 + k * 1024); } while (0)
; #define PG8_MMA(ai, bj, At, Bt) do { __builtin_amdgcn_s_setprio(1); _Pragma("unroll") for (int m = 0; m < 4; ++m) _Pragma("unroll") for (int n = 0; n < 2; ++n) _Pragma("unroll") for (int k = 0; k < 2; ++k) \
;         acc[ai][bj][m][n] = __builtin_amdgcn_mfma_f32_16x16x32_bf16(Bt[n][k], At[m][k], acc[ai][bj][m][n], 0, 0, 0); __builtin_amdgcn_s_setprio(0); } while (0)
; #define PG8_WAIT_V(n) asm volatile("s_waitcnt vmcnt(" #n ")" ::: "memory")
; #define PG8_WAIT_L(n) asm volatile("s_waitcnt lgkmcnt(" #n ")" ::: "memory")
; #define PG8_BAR __builtin_amdgcn_s_barrier()
; #define PG8_SCHED __builtin_amdgcn_sched_barrier(0)
; template <class Epi>
; __device__ __forceinline__ void gemm_phase(LAS unsigned char* lds, const int tid, const Gemm g, const StaticOrder& S, const Epi& E) {
;     ...
;             PG8_WAIT_V(8); PG8_WAIT_L(0); PG8_BAR; PG8_MMA(1, 0, At, B0); PG8_MMA(1, 1, At, B1); PG8_BAR; PG8_SCHED;
;             PG8_LDB(B0, 1, 0); PG8_LDB(B1, 1, 1); PG8_SCHED; PG8_LDA(At, 1, 0); PG8_STAGE(PG8_SA(0, 1), a2 + hstepA, voffA);
;             PG8_WAIT_V(8); PG8_WAIT_L(0); PG8_BAR; PG8_MMA(0, 0, At, B0); PG8_MMA(0, 1, At, B1); PG8_BAR; PG8_SCHED;
	s_setprio 1
	v_mfma_f32_16x16x32_bf16 v[88:91], v[40:43], v[144:147], v[88:91]
	v_mfma_f32_16x16x32_bf16 v[76:79], v[52:55], v[144:147], v[76:79]
	v_mfma_f32_16x16x32_bf16 v[56:59], v[40:43], v[160:163], v[56:59]
	v_mfma_f32_16x16x32_bf16 v[36:39], v[52:55], v[160:163], v[36:39]
	v_mfma_f32_16x16x32_bf16 v[28:31], v[40:43], v[176:179], v[28:31]
	v_mfma_f32_16x16x32_bf16 v[20:23], v[52:55], v[176:179], v[20:23]
	v_mfma_f32_16x16x32_bf16 v[12:15], v[40:43], v[200:203], v[12:15]
	v_mfma_f32_16x16x32_bf16 v[4:7], v[52:55], v[200:203], v[4:7]
	v_mfma_f32_16x16x32_bf16 v[88:91], v[48:51], v[152:155], v[88:91]
	v_mfma_f32_16x16x32_bf16 v[76:79], v[60:63], v[152:155], v[76:79]
	v_mfma_f32_16x16x32_bf16 v[56:59], v[48:51], v[172:175], v[56:59]
	v_mfma_f32_16x16x32_bf16 v[36:39], v[60:63], v[172:175], v[36:39]
	v_mfma_f32_16x16x32_bf16 v[28:31], v[48:51], v[196:199], v[28:31]
	v_mfma_f32_16x16x32_bf16 v[20:23], v[60:63], v[196:199], v[20:23]
	v_mfma_f32_16x16x32_bf16 v[12:15], v[48:51], v[204:207], v[12:15]
	v_mfma_f32_16x16x32_bf16 v[4:7], v[60:63], v[204:207], v[4:7]
	v_mfma_f32_16x16x32_bf16 v[44:47], v[64:67], v[160:163], v[44:47]
	v_mfma_f32_16x16x32_bf16 v[32:35], v[80:83], v[160:163], v[32:35]
	v_mfma_f32_16x16x32_bf16 v[24:27], v[64:67], v[176:179], v[24:27]
	v_mfma_f32_16x16x32_bf16 v[16:19], v[80:83], v[176:179], v[16:19]
	v_mfma_f32_16x16x32_bf16 v[8:11], v[64:67], v[200:203], v[8:11]
	v_mfma_f32_16x16x32_bf16 v[0:3], v[80:83], v[200:203], v[0:3]
	v_mfma_f32_16x16x32_bf16 v[40:43], v[64:67], v[144:147], v[84:87]
	v_mfma_f32_16x16x32_bf16 v[48:51], v[80:83], v[144:147], v[72:75]
	v_mfma_f32_16x16x32_bf16 v[44:47], v[68:71], v[172:175], v[44:47]
	v_mfma_f32_16x16x32_bf16 v[32:35], v[100:103], v[172:175], v[32:35]
	v_mfma_f32_16x16x32_bf16 v[24:27], v[68:71], v[196:199], v[24:27]
	v_mfma_f32_16x16x32_bf16 v[16:19], v[100:103], v[196:199], v[16:19]
	v_mfma_f32_16x16x32_bf16 v[8:11], v[68:71], v[204:207], v[8:11]
	v_mfma_f32_16x16x32_bf16 v[0:3], v[100:103], v[204:207], v[0:3]
	v_mfma_f32_16x16x32_bf16 v[40:43], v[68:71], v[152:155], v[40:43]
	v_mfma_f32_16x16x32_bf16 v[48:51], v[100:103], v[152:155], v[48:51]
	s_setprio 0
	s_barrier
	s_add_i32 s65, 0, 0x18000
	s_add_i32 s66, 0, 0x1c000
	v_add_u32_e32 v68, s65, v215
	v_add_u32_e32 v72, s66, v215
	ds_read_b128 v[52:55], v68
	ds_read_b128 v[60:63], v68 offset:1024
	ds_read_b128 v[64:67], v68 offset:2048
	ds_read_b128 v[68:71], v68 offset:3072
	ds_read_b128 v[80:83], v72
	ds_read_b128 v[100:103], v72 offset:1024
	ds_read_b128 v[160:163], v72 offset:2048
	ds_read_b128 v[172:175], v72 offset:3072
	s_add_u32 s40, s40, 0x40000
	s_addc_u32 s41, s41, 0
	s_mov_b32 m0, s49
	v_lshl_add_u64 v[144:145], s[40:41], 0, v[180:181]
	ds_read_b128 v[72:75], v219 offset:32768
	ds_read_b128 v[84:87], v219 offset:33792
	ds_read_b128 v[176:179], v219 offset:34816
	ds_read_b128 v[196:199], v219 offset:35840
	ds_read_b128 v[200:203], v219 offset:36864
	ds_read_b128 v[204:207], v219 offset:37888
	ds_read_b128 v[208:211], v219 offset:38912
	ds_read_b128 v[222:225], v219 offset:39936
	global_load_lds_dwordx4 v[144:145], off
	v_lshl_add_u64 v[144:145], s[40:41], 0, v[184:185]
	s_mov_b32 m0, s50
	s_nop 0
	global_load_lds_dwordx4 v[144:145], off
	s_waitcnt vmcnt(8)
	s_waitcnt lgkmcnt(0)
	s_barrier
	s_setprio 1
	v_mfma_f32_16x16x32_bf16 v[144:147], v[52:55], v[72:75], v[168:171]
	v_mfma_f32_16x16x32_bf16 v[168:171], v[60:63], v[84:87], v[144:147]
	v_mfma_f32_16x16x32_bf16 v[144:147], v[64:67], v[72:75], v[156:159]
	v_mfma_f32_16x16x32_bf16 v[156:159], v[68:71], v[84:87], v[144:147]
	v_mfma_f32_16x16x32_bf16 v[144:147], v[52:55], v[176:179], v[148:151]
	v_mfma_f32_16x16x32_bf16 v[136:139], v[64:67], v[176:179], v[136:139]
	v_mfma_f32_16x16x32_bf16 v[128:131], v[52:55], v[200:203], v[128:131]
	v_mfma_f32_16x16x32_bf16 v[116:119], v[64:67], v[200:203], v[116:119]
	v_mfma_f32_16x16x32_bf16 v[108:111], v[52:55], v[208:211], v[108:111]
	v_mfma_f32_16x16x32_bf16 v[96:99], v[64:67], v[208:211], v[96:99]
	v_mfma_f32_16x16x32_bf16 v[148:151], v[60:63], v[196:199], v[144:147]
	v_mfma_f32_16x16x32_bf16 v[136:139], v[68:71], v[196:199], v[136:139]
	v_mfma_f32_16x16x32_bf16 v[128:131], v[60:63], v[204:207], v[128:131]
	v_mfma_f32_16x16x32_bf16 v[116:119], v[68:71], v[204:207], v[116:119]
	v_mfma_f32_16x16x32_bf16 v[108:111], v[60:63], v[222:225], v[108:111]
	v_mfma_f32_16x16x32_bf16 v[96:99], v[68:71], v[222:225], v[96:99]
	v_mfma_f32_16x16x32_bf16 v[144:147], v[80:83], v[72:75], v[164:167]
	v_mfma_f32_16x16x32_bf16 v[72:75], v[160:163], v[72:75], v[120:123]
	v_mfma_f32_16x16x32_bf16 v[152:155], v[172:175], v[84:87], v[72:75]
	v_mfma_f32_16x16x32_bf16 v[72:75], v[80:83], v[176:179], v[140:143]
	v_mfma_f32_16x16x32_bf16 v[164:167], v[100:103], v[84:87], v[144:147]
	v_mfma_f32_16x16x32_bf16 v[144:147], v[100:103], v[196:199], v[72:75]
	v_mfma_f32_16x16x32_bf16 v[72:75], v[160:163], v[176:179], v[132:135]
	v_mfma_f32_16x16x32_bf16 v[132:135], v[172:175], v[196:199], v[72:75]
	v_mfma_f32_16x16x32_bf16 v[72:75], v[80:83], v[200:203], v[124:127]
	v_mfma_f32_16x16x32_bf16 v[124:127], v[100:103], v[204:207], v[72:75]
	v_mfma_f32_16x16x32_bf16 v[72:75], v[160:163], v[200:203], v[112:115]
	v_mfma_f32_16x16x32_bf16 v[112:115], v[172:175], v[204:207], v[72:75]
	v_mfma_f32_16x16x32_bf16 v[72:75], v[80:83], v[208:211], v[104:107]
	v_mfma_f32_16x16x32_bf16 v[104:107], v[100:103], v[222:225], v[72:75]
	v_mfma_f32_16x16x32_bf16 v[72:75], v[160:163], v[208:211], v[92:95]
	v_mfma_f32_16x16x32_bf16 v[92:95], v[172:175], v[222:225], v[72:75]
	s_setprio 0
	s_barrier
; #define PG8_STAGE(bufoff, gbase, voff) do { _Pragma("unroll") for (int _i = 0; _i < 2; ++_i) \
;         __builtin_amdgcn_global_load_lds((const unsigned*)((const char*)(gbase) + (voff)[_i]), (LAS unsigned*)(lds + (bufoff) + ldsw + _i * 8192), 16, 0, 0); } while (0)
; #define PG8_LDA(dst, b, h) do { _Pragma("unroll") for (int m = 0; m < 4; ++m) _Pragma("unroll") for (int k = 0; k < 2; ++k) dst[m][k] = *(const LAS bf16x8*)(lds + PG8_SA(b, h) + aoff + m * 2048 + k * 1024); } while (0)
; #define PG8_MMA(ai, bj, At, Bt) do { __builtin_amdgcn_s_setprio(1); _Pragma("unroll") for (int m = 0; m < 4; ++m) _Pragma("unroll") for (int n = 0; n < 2; ++n) _Pragma("unroll") for (int k = 0; k < 2; ++k) \
;         acc[ai][bj][m][n] = __builtin_amdgcn_mfma_f32_16x16x32_bf16(Bt[n][k], At[m][k], acc[ai][bj][m][n], 0, 0, 0); __builtin_amdgcn_s_setprio(0); } while (0)
; #define PG8_WAIT_V(n) asm volatile("s_waitcnt vmcnt(" #n ")" ::: "memory")
; #define PG8_WAIT_L(n) asm volatile("s_waitcnt lgkmcnt(" #n ")" ::: "memory")
; #define PG8_BAR __builtin_amdgcn_s_barrier()
; #define PG8_SCHED __builtin_amdgcn_sched_barrier(0)
; template <class Epi>
; __device__ __forceinline__ void gemm_phase(LAS unsigned char* lds, const int tid, const Gemm g, const StaticOrder& S, const Epi& E) {
;     ...
;         for (int t = 0; t < nt; t += 2) {
;     ...
;             PG8_LDA(At, 1, 1); PG8_STAGE(PG8_SB(1, 0), b3, voffB); PG8_STAGE(PG8_SB(1, 1), b3 + hstepB, voffB); PG8_STAGE(PG8_SA(1, 0), a3, voffA);
;             PG8_WAIT_V(8); PG8_WAIT_L(0); PG8_BAR; PG8_MMA(1, 0, At, B0); PG8_MMA(1, 1, At, B1); PG8_BAR; PG8_SCHED;
	s_add_i32 s40, s65, s46
	v_lshl_add_u64 v[84:85], v[212:213], 0, s[16:17]
	s_mov_b32 m0, s40
	s_nop 1
	ds_read_b128 v[72:75], v219 offset:49152
	ds_read_b128 v[120:123], v219 offset:50176
	ds_read_b128 v[140:143], v219 offset:51200
	ds_read_b128 v[176:179], v219 offset:52224
	ds_read_b128 v[196:199], v219 offset:53248
	ds_read_b128 v[200:203], v219 offset:54272
	ds_read_b128 v[204:207], v219 offset:55296
	ds_read_b128 v[208:211], v219 offset:56320
	global_load_lds_dwordx4 v[84:85], off
	s_add_i32 m0, s40, 0x2000
	s_add_u32 s38, s38, 0x10080
	v_lshl_add_u64 v[84:85], v[226:227], 0, s[16:17]
	s_addc_u32 s39, s39, 0
	s_add_i32 s40, s66, s46
	global_load_lds_dwordx4 v[84:85], off
	v_lshl_add_u64 v[84:85], s[38:39], 0, v[182:183]
	s_mov_b32 m0, s40
	s_nop 0
	global_load_lds_dwordx4 v[84:85], off
	v_lshl_add_u64 v[84:85], s[38:39], 0, v[186:187]
	s_add_i32 m0, s40, 0x2000
	s_nop 0
	global_load_lds_dwordx4 v[84:85], off
	v_lshl_add_u64 v[84:85], v[228:229], 0, s[16:17]
	s_mov_b32 m0, s53
	s_nop 0
	global_load_lds_dwordx4 v[84:85], off
	v_lshl_add_u64 v[84:85], v[230:231], 0, s[16:17]
	s_mov_b32 m0, s54
	s_nop 0
	global_load_lds_dwordx4 v[84:85], off
	s_waitcnt vmcnt(8)
	s_waitcnt lgkmcnt(0)
	s_barrier
	s_setprio 1
	v_mfma_f32_16x16x32_bf16 v[84:87], v[52:55], v[72:75], v[88:91]
	v_mfma_f32_16x16x32_bf16 v[76:79], v[64:67], v[72:75], v[76:79]
	v_mfma_f32_16x16x32_bf16 v[56:59], v[52:55], v[140:143], v[56:59]
	v_mfma_f32_16x16x32_bf16 v[36:39], v[64:67], v[140:143], v[36:39]
	v_mfma_f32_16x16x32_bf16 v[28:31], v[52:55], v[196:199], v[28:31]
	v_mfma_f32_16x16x32_bf16 v[20:23], v[64:67], v[196:199], v[20:23]
	v_mfma_f32_16x16x32_bf16 v[12:15], v[52:55], v[204:207], v[12:15]
	v_mfma_f32_16x16x32_bf16 v[4:7], v[64:67], v[204:207], v[4:7]
	v_mfma_f32_16x16x32_bf16 v[88:91], v[60:63], v[120:123], v[84:87]
	v_mfma_f32_16x16x32_bf16 v[76:79], v[68:71], v[120:123], v[76:79]
	v_mfma_f32_16x16x32_bf16 v[56:59], v[60:63], v[176:179], v[56:59]
	v_mfma_f32_16x16x32_bf16 v[36:39], v[68:71], v[176:179], v[36:39]
	v_mfma_f32_16x16x32_bf16 v[28:31], v[60:63], v[200:203], v[28:31]
	v_mfma_f32_16x16x32_bf16 v[20:23], v[68:71], v[200:203], v[20:23]
	v_mfma_f32_16x16x32_bf16 v[12:15], v[60:63], v[208:211], v[12:15]
	v_mfma_f32_16x16x32_bf16 v[4:7], v[68:71], v[208:211], v[4:7]
	v_mfma_f32_16x16x32_bf16 v[40:43], v[80:83], v[72:75], v[40:43]
	v_mfma_f32_16x16x32_bf16 v[84:87], v[100:103], v[120:123], v[40:43]
	v_mfma_f32_16x16x32_bf16 v[40:43], v[160:163], v[72:75], v[48:51]
	v_mfma_f32_16x16x32_bf16 v[72:75], v[172:175], v[120:123], v[40:43]
	v_mfma_f32_16x16x32_bf16 v[40:43], v[80:83], v[140:143], v[44:47]
	v_mfma_f32_16x16x32_bf16 v[32:35], v[160:163], v[140:143], v[32:35]
	v_mfma_f32_16x16x32_bf16 v[24:27], v[80:83], v[196:199], v[24:27]
	v_mfma_f32_16x16x32_bf16 v[16:19], v[160:163], v[196:199], v[16:19]
	v_mfma_f32_16x16x32_bf16 v[8:11], v[80:83], v[204:207], v[8:11]
	v_mfma_f32_16x16x32_bf16 v[0:3], v[160:163], v[204:207], v[0:3]
	v_mfma_f32_16x16x32_bf16 v[44:47], v[100:103], v[176:179], v[40:43]
	v_mfma_f32_16x16x32_bf16 v[32:35], v[172:175], v[176:179], v[32:35]
	v_mfma_f32_16x16x32_bf16 v[24:27], v[100:103], v[200:203], v[24:27]
	v_mfma_f32_16x16x32_bf16 v[16:19], v[172:175], v[200:203], v[16:19]
	v_mfma_f32_16x16x32_bf16 v[8:11], v[100:103], v[208:211], v[8:11]
	v_mfma_f32_16x16x32_bf16 v[0:3], v[172:175], v[208:211], v[0:3]
	s_setprio 0
	s_barrier
	s_add_u32 s62, s62, 0x100
	s_addc_u32 s63, s63, 0
	s_add_u32 s36, s36, 0x100
	s_addc_u32 s37, s37, 0
	s_cmp_ge_i32 s64, s52
	s_mov_b32 s38, s64
	s_cbranch_scc0 .LBB0_1525

; #define LAS __attribute__((address_space(3)))
; #define PG8_STAGE(bufoff, gbase, voff) do { _Pragma("unroll") for (int _i = 0; _i < 2; ++_i) \
;         __builtin_amdgcn_global_load_lds((const unsigned*)((const char*)(gbase) + (voff)[_i]), (LAS unsigned*)(lds + (bufoff) + ldsw + _i * 8192), 16, 0, 0); } while (0)
; #define PG8_LDA(dst, b, h) do { _Pragma("unroll") for (int m = 0; m < 4; ++m) _Pragma("unroll") for (int k = 0; k < 2; ++k) dst[m][k] = *(const LAS bf16x8*)(lds + PG8_SA(b, h) + aoff + m * 2048 + k * 1024); } while (0)
; #define PG8_LDB(dst, b, h) do { _Pragma("unroll") for (int n = 0; n < 2; ++n) _Pragma("unroll") for (int k = 0; k < 2; ++k) dst[n][k] = *(const LAS bf16x8*)(lds + PG8_SB(b, h) + boff + n * 2048 + k * 1024); } while (0)
; #define PG8_WAIT_V(n) asm volatile("s_waitcnt vmcnt(" #n ")" ::: "memory")
; #define PG8_WAIT_L(n) asm volatile("s_waitcnt lgkmcnt(" #n ")" ::: "memory")
; #define PG8_BAR __builtin_amdgcn_s_barrier()
; template <class Epi>
; __device__ __forceinline__ void gemm_phase(LAS unsigned char* lds, const int tid, const Gemm g, const StaticOrder& S, const Epi& E) {
;     ...
;             const bool last = (t == nt - 2);
;             const char* a1 = cA + (size_t)(t + 1) * kstep;
;             const char* a2 = last ? nA : cA + (size_t)(t + 2) * kstep; const char* b2 = last ? nB : cB + (size_t)(t + 2) * kstep;
;             const char* a3 = a2 + kstep; const char* b3 = b2 + kstep;
;             if constexpr (Epi::SS_LDS) { if (last) {
;                 const char* sp = (const char*)E.ss + (size_t)cur.pm * (256 * 64) + (size_t)tid * 16;
;                 __builtin_amdgcn_global_load_lds((const unsigned*)sp, (LAS unsigned*)(lds + RS_OFF + ldsw), 16, 0, 0);
;                 __builtin_amdgcn_global_load_lds((const unsigned*)(sp + 8192), (LAS unsigned*)(lds + RS_OFF + 8192 + ldsw), 16, 0, 0); } }
;     ...
;             PG8_LDB(B0, 0, 0); PG8_LDB(B1, 0, 1); PG8_SCHED; PG8_LDA(At, 0, 0); PG8_STAGE(PG8_SA(1, 1), a1 + hstepA, voffA);
;             PG8_WAIT_V(8); PG8_WAIT_L(0); PG8_BAR; PG8_MMA(0, 0, At, B0); PG8_MMA(0, 1, At, B1); PG8_BAR; PG8_SCHED;
;             PG8_LDA(At, 0, 1); PG8_STAGE(PG8_SB(0, 0), b2, voffB); PG8_STAGE(PG8_SB(0, 1), b2 + hstepB, voffB); PG8_STAGE(PG8_SA(0, 0), a2, voffA);
;             PG8_WAIT_V(8); PG8_WAIT_L(0); PG8_BAR; PG8_MMA(1, 0, At, B0); PG8_MMA(1, 1, At, B1); PG8_BAR; PG8_SCHED;
.LBB0_1734:
	ds_read_b128 v[128:131], v189
	ds_read_b128 v[132:135], v189 offset:1024
	ds_read_b128 v[136:139], v189 offset:2048
	ds_read_b128 v[140:143], v189 offset:3072
	ds_read_b128 v[144:147], v190
	ds_read_b128 v[148:151], v190 offset:1024
	ds_read_b128 v[168:171], v190 offset:2048
	ds_read_b128 v[172:175], v190 offset:3072
	s_add_i32 s62, s38, 2
	s_add_u32 s39, s36, 0xfffc0080
	s_addc_u32 s40, s37, -1
	s_cmp_eq_u32 s53, s38
	s_cselect_b32 s38, s59, s60
	s_cselect_b32 s41, s25, s40
	s_cselect_b32 s40, s27, s39
	s_cselect_b32 s39, s35, s61
	v_lshl_add_u64 v[184:185], s[36:37], 0, v[162:163]
	s_add_i32 m0, s45, 0xc000
	ds_read_b128 v[176:179], v191
	ds_read_b128 v[180:183], v191 offset:1024
	ds_read_b128 v[192:195], v191 offset:2048
	ds_read_b128 v[196:199], v191 offset:3072
	ds_read_b128 v[200:203], v191 offset:4096
	ds_read_b128 v[204:207], v191 offset:5120
	ds_read_b128 v[208:211], v191 offset:6144
	ds_read_b128 v[212:215], v191 offset:7168
	global_load_lds_dwordx4 v[184:185], off
	v_lshl_add_u64 v[184:185], s[36:37], 0, v[160:161]
	s_add_i32 m0, s45, 0xe000
	s_nop 0
	global_load_lds_dwordx4 v[184:185], off
	s_waitcnt vmcnt(8)
	s_waitcnt lgkmcnt(0)
	s_barrier
	s_setprio 1
	v_mfma_f32_16x16x32_bf16 v[120:123], v[128:131], v[176:179], v[120:123]
	v_mfma_f32_16x16x32_bf16 v[124:127], v[136:139], v[176:179], v[124:127]
	v_mfma_f32_16x16x32_bf16 v[108:111], v[128:131], v[192:195], v[108:111]
	v_mfma_f32_16x16x32_bf16 v[104:107], v[136:139], v[192:195], v[104:107]
	v_mfma_f32_16x16x32_bf16 v[92:95], v[128:131], v[200:203], v[92:95]
	v_mfma_f32_16x16x32_bf16 v[88:91], v[136:139], v[200:203], v[88:91]
	v_mfma_f32_16x16x32_bf16 v[76:79], v[128:131], v[208:211], v[76:79]
	v_mfma_f32_16x16x32_bf16 v[72:75], v[136:139], v[208:211], v[72:75]
	v_mfma_f32_16x16x32_bf16 v[120:123], v[132:135], v[180:183], v[120:123]
	v_mfma_f32_16x16x32_bf16 v[124:127], v[140:143], v[180:183], v[124:127]
	v_mfma_f32_16x16x32_bf16 v[108:111], v[132:135], v[196:199], v[108:111]
	v_mfma_f32_16x16x32_bf16 v[104:107], v[140:143], v[196:199], v[104:107]
	v_mfma_f32_16x16x32_bf16 v[92:95], v[132:135], v[204:207], v[92:95]
	v_mfma_f32_16x16x32_bf16 v[88:91], v[140:143], v[204:207], v[88:91]
	v_mfma_f32_16x16x32_bf16 v[76:79], v[132:135], v[212:215], v[76:79]
	v_mfma_f32_16x16x32_bf16 v[72:75], v[140:143], v[212:215], v[72:75]
	v_mfma_f32_16x16x32_bf16 v[116:119], v[144:147], v[176:179], v[116:119]
	v_mfma_f32_16x16x32_bf16 v[112:115], v[168:171], v[176:179], v[112:115]
	v_mfma_f32_16x16x32_bf16 v[100:103], v[144:147], v[192:195], v[100:103]
	v_mfma_f32_16x16x32_bf16 v[96:99], v[168:171], v[192:195], v[96:99]
	v_mfma_f32_16x16x32_bf16 v[84:87], v[144:147], v[200:203], v[84:87]
	v_mfma_f32_16x16x32_bf16 v[80:83], v[168:171], v[200:203], v[80:83]
	v_mfma_f32_16x16x32_bf16 v[68:71], v[144:147], v[208:211], v[68:71]
	v_mfma_f32_16x16x32_bf16 v[64:67], v[168:171], v[208:211], v[64:67]
	v_mfma_f32_16x16x32_bf16 v[116:119], v[148:151], v[180:183], v[116:119]
	v_mfma_f32_16x16x32_bf16 v[112:115], v[172:175], v[180:183], v[112:115]
	v_mfma_f32_16x16x32_bf16 v[100:103], v[148:151], v[196:199], v[100:103]
	v_mfma_f32_16x16x32_bf16 v[96:99], v[172:175], v[196:199], v[96:99]
	v_mfma_f32_16x16x32_bf16 v[84:87], v[148:151], v[204:207], v[84:87]
	v_mfma_f32_16x16x32_bf16 v[80:83], v[172:175], v[204:207], v[80:83]
	v_mfma_f32_16x16x32_bf16 v[68:71], v[148:151], v[212:215], v[68:71]
	v_mfma_f32_16x16x32_bf16 v[64:67], v[172:175], v[212:215], v[64:67]
	s_setprio 0
	s_barrier
	s_add_i32 s63, s56, s44
	v_lshl_add_u64 v[184:185], s[38:39], 0, v[154:155]
	s_mov_b32 m0, s63
	ds_read_b128 v[176:179], v191 offset:16384
	ds_read_b128 v[180:183], v191 offset:17408
	ds_read_b128 v[192:195], v191 offset:18432
	ds_read_b128 v[196:199], v191 offset:19456
	ds_read_b128 v[200:203], v191 offset:20480
	ds_read_b128 v[204:207], v191 offset:21504
	ds_read_b128 v[208:211], v191 offset:22528
	ds_read_b128 v[212:215], v191 offset:23552
	global_load_lds_dwordx4 v[184:185], off
	s_add_i32 m0, s63, 0x2000
	s_add_u32 s64, s38, 0x40000
	v_lshl_add_u64 v[216:217], s[38:39], 0, v[158:159]
	s_addc_u32 s65, s39, 0
	s_add_i32 s63, s57, s44
	global_load_lds_dwordx4 v[216:217], off
	v_lshl_add_u64 v[218:219], s[64:65], 0, v[154:155]
	s_mov_b32 m0, s63
	v_lshl_add_u64 v[220:221], s[40:41], 0, v[156:157]
	global_load_lds_dwordx4 v[218:219], off
	v_lshl_add_u64 v[218:219], s[64:65], 0, v[158:159]
	s_add_i32 m0, s63, 0x2000
	s_nop 0
	global_load_lds_dwordx4 v[218:219], off
	v_lshl_add_u64 v[218:219], s[40:41], 0, v[152:153]
	s_mov_b32 m0, s45
	s_nop 0
	global_load_lds_dwordx4 v[218:219], off
	s_mov_b32 m0, s46
	s_nop 0
	global_load_lds_dwordx4 v[220:221], off
	s_waitcnt vmcnt(8)
	s_waitcnt lgkmcnt(0)
	s_barrier
; #define PG8_STAGE(bufoff, gbase, voff) do { _Pragma("unroll") for (int _i = 0; _i < 2; ++_i) \
;         __builtin_amdgcn_global_load_lds((const unsigned*)((const char*)(gbase) + (voff)[_i]), (LAS unsigned*)(lds + (bufoff) + ldsw + _i * 8192), 16, 0, 0); } while (0)
; #define PG8_LDA(dst, b, h) do { _Pragma("unroll") for (int m = 0; m < 4; ++m) _Pragma("unroll") for (int k = 0; k < 2; ++k) dst[m][k] = *(const LAS bf16x8*)(lds + PG8_SA(b, h) + aoff + m * 2048 + k * 1024); } while (0)
; #define PG8_LDB(dst, b, h) do { _Pragma("unroll") for (int n = 0; n < 2; ++n) _Pragma("unroll") for (int k = 0; k < 2; ++k) dst[n][k] = *(const LAS bf16x8*)(lds + PG8_SB(b, h) + boff + n * 2048 + k * 1024); } while (0)
; #define PG8_MMA(ai, bj, At, Bt) do { __builtin_amdgcn_s_setprio(1); _Pragma("unroll") for (int m = 0; m < 4; ++m) _Pragma("unroll") for (int n = 0; n < 2; ++n) _Pragma("unroll") for (int k = 0; k < 2; ++k) \
;         acc[ai][bj][m][n] = __builtin_amdgcn_mfma_f32_16x16x32_bf16(Bt[n][k], At[m][k], acc[ai][bj][m][n], 0, 0, 0); __builtin_amdgcn_s_setprio(0); } while (0)
; #define PG8_WAIT_V(n) asm volatile("s_waitcnt vmcnt(" #n ")" ::: "memory")
; #define PG8_WAIT_L(n) asm volatile("s_waitcnt lgkmcnt(" #n ")" ::: "memory")
; #define PG8_BAR __builtin_amdgcn_s_barrier()
; #define PG8_SCHED __builtin_amdgcn_sched_barrier(0)
; template <class Epi>
; __device__ __forceinline__ void gemm_phase(LAS unsigned char* lds, const int tid, const Gemm g, const StaticOrder& S, const Epi& E) {
;     ...
;             PG8_WAIT_V(8); PG8_WAIT_L(0); PG8_BAR; PG8_MMA(1, 0, At, B0); PG8_MMA(1, 1, At, B1); PG8_BAR; PG8_SCHED;
;             PG8_LDB(B0, 1, 0); PG8_LDB(B1, 1, 1); PG8_SCHED; PG8_LDA(At, 1, 0); PG8_STAGE(PG8_SA(0, 1), a2 + hstepA, voffA);
;             PG8_WAIT_V(8); PG8_WAIT_L(0); PG8_BAR; PG8_MMA(0, 0, At, B0); PG8_MMA(0, 1, At, B1); PG8_BAR; PG8_SCHED;
	s_setprio 1
	v_mfma_f32_16x16x32_bf16 v[60:63], v[128:131], v[176:179], v[60:63]
	v_mfma_f32_16x16x32_bf16 v[56:59], v[136:139], v[176:179], v[56:59]
	v_mfma_f32_16x16x32_bf16 v[44:47], v[128:131], v[192:195], v[44:47]
	v_mfma_f32_16x16x32_bf16 v[40:43], v[136:139], v[192:195], v[40:43]
	v_mfma_f32_16x16x32_bf16 v[28:31], v[128:131], v[200:203], v[28:31]
	v_mfma_f32_16x16x32_bf16 v[24:27], v[136:139], v[200:203], v[24:27]
	v_mfma_f32_16x16x32_bf16 v[12:15], v[128:131], v[208:211], v[12:15]
	v_mfma_f32_16x16x32_bf16 v[8:11], v[136:139], v[208:211], v[8:11]
	v_mfma_f32_16x16x32_bf16 v[60:63], v[132:135], v[180:183], v[60:63]
	v_mfma_f32_16x16x32_bf16 v[56:59], v[140:143], v[180:183], v[56:59]
	v_mfma_f32_16x16x32_bf16 v[44:47], v[132:135], v[196:199], v[44:47]
	v_mfma_f32_16x16x32_bf16 v[40:43], v[140:143], v[196:199], v[40:43]
	v_mfma_f32_16x16x32_bf16 v[28:31], v[132:135], v[204:207], v[28:31]
	v_mfma_f32_16x16x32_bf16 v[24:27], v[140:143], v[204:207], v[24:27]
	v_mfma_f32_16x16x32_bf16 v[12:15], v[132:135], v[212:215], v[12:15]
	v_mfma_f32_16x16x32_bf16 v[8:11], v[140:143], v[212:215], v[8:11]
	v_mfma_f32_16x16x32_bf16 v[52:55], v[144:147], v[176:179], v[52:55]
	v_mfma_f32_16x16x32_bf16 v[48:51], v[168:171], v[176:179], v[48:51]
	v_mfma_f32_16x16x32_bf16 v[36:39], v[144:147], v[192:195], v[36:39]
	v_mfma_f32_16x16x32_bf16 v[32:35], v[168:171], v[192:195], v[32:35]
	v_mfma_f32_16x16x32_bf16 v[20:23], v[144:147], v[200:203], v[20:23]
	v_mfma_f32_16x16x32_bf16 v[16:19], v[168:171], v[200:203], v[16:19]
	v_mfma_f32_16x16x32_bf16 v[4:7], v[144:147], v[208:211], v[4:7]
	v_mfma_f32_16x16x32_bf16 v[0:3], v[168:171], v[208:211], v[0:3]
	v_mfma_f32_16x16x32_bf16 v[52:55], v[148:151], v[180:183], v[52:55]
	v_mfma_f32_16x16x32_bf16 v[48:51], v[172:175], v[180:183], v[48:51]
	v_mfma_f32_16x16x32_bf16 v[36:39], v[148:151], v[196:199], v[36:39]
	v_mfma_f32_16x16x32_bf16 v[32:35], v[172:175], v[196:199], v[32:35]
	v_mfma_f32_16x16x32_bf16 v[20:23], v[148:151], v[204:207], v[20:23]
	v_mfma_f32_16x16x32_bf16 v[16:19], v[172:175], v[204:207], v[16:19]
	v_mfma_f32_16x16x32_bf16 v[4:7], v[148:151], v[212:215], v[4:7]
	v_mfma_f32_16x16x32_bf16 v[0:3], v[172:175], v[212:215], v[0:3]
	s_setprio 0
	s_barrier
	s_add_i32 s63, 0, 0x18000
	s_add_i32 s64, 0, 0x1c000
	v_add_u32_e32 v140, s63, v187
	v_add_u32_e32 v172, s64, v187
	ds_read_b128 v[128:131], v140
	ds_read_b128 v[132:135], v140 offset:1024
	ds_read_b128 v[136:139], v140 offset:2048
	ds_read_b128 v[140:143], v140 offset:3072
	ds_read_b128 v[144:147], v172
	ds_read_b128 v[148:151], v172 offset:1024
	ds_read_b128 v[168:171], v172 offset:2048
	ds_read_b128 v[172:175], v172 offset:3072
	s_add_u32 s40, s40, 0x40000
	s_addc_u32 s41, s41, 0
	s_mov_b32 m0, s47
	v_lshl_add_u64 v[222:223], s[40:41], 0, v[152:153]
	ds_read_b128 v[176:179], v191 offset:32768
	ds_read_b128 v[180:183], v191 offset:33792
	ds_read_b128 v[192:195], v191 offset:34816
	ds_read_b128 v[196:199], v191 offset:35840
	ds_read_b128 v[200:203], v191 offset:36864
	ds_read_b128 v[204:207], v191 offset:37888
	ds_read_b128 v[208:211], v191 offset:38912
	ds_read_b128 v[212:215], v191 offset:39936
	global_load_lds_dwordx4 v[222:223], off
	v_lshl_add_u64 v[222:223], s[40:41], 0, v[156:157]
	s_mov_b32 m0, s48
	s_nop 0
	global_load_lds_dwordx4 v[222:223], off
	s_waitcnt vmcnt(8)
	s_waitcnt lgkmcnt(0)
	s_barrier
	s_setprio 1
	v_mfma_f32_16x16x32_bf16 v[120:123], v[128:131], v[176:179], v[120:123]
	v_mfma_f32_16x16x32_bf16 v[124:127], v[136:139], v[176:179], v[124:127]
	v_mfma_f32_16x16x32_bf16 v[108:111], v[128:131], v[192:195], v[108:111]
	v_mfma_f32_16x16x32_bf16 v[104:107], v[136:139], v[192:195], v[104:107]
	v_mfma_f32_16x16x32_bf16 v[92:95], v[128:131], v[200:203], v[92:95]
	v_mfma_f32_16x16x32_bf16 v[88:91], v[136:139], v[200:203], v[88:91]
	v_mfma_f32_16x16x32_bf16 v[76:79], v[128:131], v[208:211], v[76:79]
	v_mfma_f32_16x16x32_bf16 v[72:75], v[136:139], v[208:211], v[72:75]
	v_mfma_f32_16x16x32_bf16 v[120:123], v[132:135], v[180:183], v[120:123]
	v_mfma_f32_16x16x32_bf16 v[124:127], v[140:143], v[180:183], v[124:127]
	v_mfma_f32_16x16x32_bf16 v[108:111], v[132:135], v[196:199], v[108:111]
	v_mfma_f32_16x16x32_bf16 v[104:107], v[140:143], v[196:199], v[104:107]
	v_mfma_f32_16x16x32_bf16 v[92:95], v[132:135], v[204:207], v[92:95]
	v_mfma_f32_16x16x32_bf16 v[88:91], v[140:143], v[204:207], v[88:91]
	v_mfma_f32_16x16x32_bf16 v[76:79], v[132:135], v[212:215], v[76:79]
	v_mfma_f32_16x16x32_bf16 v[72:75], v[140:143], v[212:215], v[72:75]
	v_mfma_f32_16x16x32_bf16 v[116:119], v[144:147], v[176:179], v[116:119]
	v_mfma_f32_16x16x32_bf16 v[112:115], v[168:171], v[176:179], v[112:115]
	v_mfma_f32_16x16x32_bf16 v[100:103], v[144:147], v[192:195], v[100:103]
	v_mfma_f32_16x16x32_bf16 v[96:99], v[168:171], v[192:195], v[96:99]
	v_mfma_f32_16x16x32_bf16 v[84:87], v[144:147], v[200:203], v[84:87]
	v_mfma_f32_16x16x32_bf16 v[80:83], v[168:171], v[200:203], v[80:83]
	v_mfma_f32_16x16x32_bf16 v[68:71], v[144:147], v[208:211], v[68:71]
	v_mfma_f32_16x16x32_bf16 v[64:67], v[168:171], v[208:211], v[64:67]
	v_mfma_f32_16x16x32_bf16 v[116:119], v[148:151], v[180:183], v[116:119]
	v_mfma_f32_16x16x32_bf16 v[112:115], v[172:175], v[180:183], v[112:115]
	v_mfma_f32_16x16x32_bf16 v[100:103], v[148:151], v[196:199], v[100:103]
	v_mfma_f32_16x16x32_bf16 v[96:99], v[172:175], v[196:199], v[96:99]
	v_mfma_f32_16x16x32_bf16 v[84:87], v[148:151], v[204:207], v[84:87]
	v_mfma_f32_16x16x32_bf16 v[80:83], v[172:175], v[204:207], v[80:83]
	v_mfma_f32_16x16x32_bf16 v[68:71], v[148:151], v[212:215], v[68:71]
	v_mfma_f32_16x16x32_bf16 v[64:67], v[172:175], v[212:215], v[64:67]
	s_setprio 0
	s_barrier
; #define PG8_STAGE(bufoff, gbase, voff) do { _Pragma("unroll") for (int _i = 0; _i < 2; ++_i) \
;         __builtin_amdgcn_global_load_lds((const unsigned*)((const char*)(gbase) + (voff)[_i]), (LAS unsigned*)(lds + (bufoff) + ldsw + _i * 8192), 16, 0, 0); } while (0)
; #define PG8_LDA(dst, b, h) do { _Pragma("unroll") for (int m = 0; m < 4; ++m) _Pragma("unroll") for (int k = 0; k < 2; ++k) dst[m][k] = *(const LAS bf16x8*)(lds + PG8_SA(b, h) + aoff + m * 2048 + k * 1024); } while (0)
; #define PG8_MMA(ai, bj, At, Bt) do { __builtin_amdgcn_s_setprio(1); _Pragma("unroll") for (int m = 0; m < 4; ++m) _Pragma("unroll") for (int n = 0; n < 2; ++n) _Pragma("unroll") for (int k = 0; k < 2; ++k) \
;         acc[ai][bj][m][n] = __builtin_amdgcn_mfma_f32_16x16x32_bf16(Bt[n][k], At[m][k], acc[ai][bj][m][n], 0, 0, 0); __builtin_amdgcn_s_setprio(0); } while (0)
; #define PG8_WAIT_V(n) asm volatile("s_waitcnt vmcnt(" #n ")" ::: "memory")
; #define PG8_WAIT_L(n) asm volatile("s_waitcnt lgkmcnt(" #n ")" ::: "memory")
; #define PG8_BAR __builtin_amdgcn_s_barrier()
; #define PG8_SCHED __builtin_amdgcn_sched_barrier(0)
; template <class Epi>
; __device__ __forceinline__ void gemm_phase(LAS unsigned char* lds, const int tid, const Gemm g, const StaticOrder& S, const Epi& E) {
;     ...
;         for (int t = 0; t < nt; t += 2) {
;     ...
;             PG8_LDA(At, 1, 1); PG8_STAGE(PG8_SB(1, 0), b3, voffB); PG8_STAGE(PG8_SB(1, 1), b3 + hstepB, voffB); PG8_STAGE(PG8_SA(1, 0), a3, voffA);
;             PG8_WAIT_V(8); PG8_WAIT_L(0); PG8_BAR; PG8_MMA(1, 0, At, B0); PG8_MMA(1, 1, At, B1); PG8_BAR; PG8_SCHED;
	s_add_i32 s40, s63, s44
	v_lshl_add_u64 v[184:185], v[184:185], 0, s[18:19]
	s_mov_b32 m0, s40
	ds_read_b128 v[176:179], v191 offset:49152
	ds_read_b128 v[180:183], v191 offset:50176
	ds_read_b128 v[192:195], v191 offset:51200
	ds_read_b128 v[196:199], v191 offset:52224
	ds_read_b128 v[200:203], v191 offset:53248
	ds_read_b128 v[204:207], v191 offset:54272
	ds_read_b128 v[208:211], v191 offset:55296
	ds_read_b128 v[212:215], v191 offset:56320
	global_load_lds_dwordx4 v[184:185], off
	s_add_i32 m0, s40, 0x2000
	s_add_u32 s38, s38, 0x40080
	v_lshl_add_u64 v[184:185], v[216:217], 0, s[18:19]
	s_addc_u32 s39, s39, 0
	s_add_i32 s40, s64, s44
	global_load_lds_dwordx4 v[184:185], off
	v_lshl_add_u64 v[184:185], s[38:39], 0, v[154:155]
	s_mov_b32 m0, s40
	s_nop 0
	global_load_lds_dwordx4 v[184:185], off
	v_lshl_add_u64 v[184:185], s[38:39], 0, v[158:159]
	s_add_i32 m0, s40, 0x2000
	s_nop 0
	global_load_lds_dwordx4 v[184:185], off
	v_lshl_add_u64 v[184:185], v[218:219], 0, s[18:19]
	s_mov_b32 m0, s51
	s_nop 0
	global_load_lds_dwordx4 v[184:185], off
	v_lshl_add_u64 v[184:185], v[220:221], 0, s[18:19]
	s_mov_b32 m0, s52
	s_nop 0
	global_load_lds_dwordx4 v[184:185], off
	s_waitcnt vmcnt(8)
	s_waitcnt lgkmcnt(0)
	s_barrier
	s_setprio 1
	v_mfma_f32_16x16x32_bf16 v[60:63], v[128:131], v[176:179], v[60:63]
	v_mfma_f32_16x16x32_bf16 v[56:59], v[136:139], v[176:179], v[56:59]
	v_mfma_f32_16x16x32_bf16 v[44:47], v[128:131], v[192:195], v[44:47]
	v_mfma_f32_16x16x32_bf16 v[40:43], v[136:139], v[192:195], v[40:43]
	v_mfma_f32_16x16x32_bf16 v[28:31], v[128:131], v[200:203], v[28:31]
	v_mfma_f32_16x16x32_bf16 v[24:27], v[136:139], v[200:203], v[24:27]
	v_mfma_f32_16x16x32_bf16 v[12:15], v[128:131], v[208:211], v[12:15]
	v_mfma_f32_16x16x32_bf16 v[8:11], v[136:139], v[208:211], v[8:11]
	v_mfma_f32_16x16x32_bf16 v[60:63], v[132:135], v[180:183], v[60:63]
	v_mfma_f32_16x16x32_bf16 v[56:59], v[140:143], v[180:183], v[56:59]
	v_mfma_f32_16x16x32_bf16 v[44:47], v[132:135], v[196:199], v[44:47]
	v_mfma_f32_16x16x32_bf16 v[40:43], v[140:143], v[196:199], v[40:43]
	v_mfma_f32_16x16x32_bf16 v[28:31], v[132:135], v[204:207], v[28:31]
	v_mfma_f32_16x16x32_bf16 v[24:27], v[140:143], v[204:207], v[24:27]
	v_mfma_f32_16x16x32_bf16 v[12:15], v[132:135], v[212:215], v[12:15]
	v_mfma_f32_16x16x32_bf16 v[8:11], v[140:143], v[212:215], v[8:11]
	v_mfma_f32_16x16x32_bf16 v[52:55], v[144:147], v[176:179], v[52:55]
	v_mfma_f32_16x16x32_bf16 v[48:51], v[168:171], v[176:179], v[48:51]
	v_mfma_f32_16x16x32_bf16 v[36:39], v[144:147], v[192:195], v[36:39]
	v_mfma_f32_16x16x32_bf16 v[32:35], v[168:171], v[192:195], v[32:35]
	v_mfma_f32_16x16x32_bf16 v[20:23], v[144:147], v[200:203], v[20:23]
	v_mfma_f32_16x16x32_bf16 v[16:19], v[168:171], v[200:203], v[16:19]
	v_mfma_f32_16x16x32_bf16 v[4:7], v[144:147], v[208:211], v[4:7]
	v_mfma_f32_16x16x32_bf16 v[0:3], v[168:171], v[208:211], v[0:3]
	v_mfma_f32_16x16x32_bf16 v[52:55], v[148:151], v[180:183], v[52:55]
	v_mfma_f32_16x16x32_bf16 v[48:51], v[172:175], v[180:183], v[48:51]
	v_mfma_f32_16x16x32_bf16 v[36:39], v[148:151], v[196:199], v[36:39]
	v_mfma_f32_16x16x32_bf16 v[32:35], v[172:175], v[196:199], v[32:35]
	v_mfma_f32_16x16x32_bf16 v[20:23], v[148:151], v[204:207], v[20:23]
	v_mfma_f32_16x16x32_bf16 v[16:19], v[172:175], v[204:207], v[16:19]
	v_mfma_f32_16x16x32_bf16 v[4:7], v[148:151], v[212:215], v[4:7]
	v_mfma_f32_16x16x32_bf16 v[0:3], v[172:175], v[212:215], v[0:3]
	s_setprio 0
	s_barrier
	s_add_u32 s60, s60, 0x100
	s_addc_u32 s61, s61, 0
	s_add_u32 s36, s36, 0x100
	s_addc_u32 s37, s37, 0
	s_cmp_ge_i32 s62, s50
	s_mov_b32 s38, s62
	s_cbranch_scc0 .LBB0_1734

; #define LAS __attribute__((address_space(3)))
; #define PG8_STAGE(bufoff, gbase, voff) do { _Pragma("unroll") for (int _i = 0; _i < 2; ++_i) \
;         __builtin_amdgcn_global_load_lds((const unsigned*)((const char*)(gbase) + (voff)[_i]), (LAS unsigned*)(lds + (bufoff) + ldsw + _i * 8192), 16, 0, 0); } while (0)
; #define PG8_LDA(dst, b, h) do { _Pragma("unroll") for (int m = 0; m < 4; ++m) _Pragma("unroll") for (int k = 0; k < 2; ++k) dst[m][k] = *(const LAS bf16x8*)(lds + PG8_SA(b, h) + aoff + m * 2048 + k * 1024); } while (0)
; #define PG8_LDB(dst, b, h) do { _Pragma("unroll") for (int n = 0; n < 2; ++n) _Pragma("unroll") for (int k = 0; k < 2; ++k) dst[n][k] = *(const LAS bf16x8*)(lds + PG8_SB(b, h) + boff + n * 2048 + k * 1024); } while (0)
; #define PG8_WAIT_V(n) asm volatile("s_waitcnt vmcnt(" #n ")" ::: "memory")
; #define PG8_WAIT_L(n) asm volatile("s_waitcnt lgkmcnt(" #n ")" ::: "memory")
; #define PG8_BAR __builtin_amdgcn_s_barrier()
; template <class Epi>
; __device__ __forceinline__ void gemm_phase(LAS unsigned char* lds, const int tid, const Gemm g, const StaticOrder& S, const Epi& E) {
;     ...
;             const bool last = (t == nt - 2);
;             const char* a1 = cA + (size_t)(t + 1) * kstep;
;             const char* a2 = last ? nA : cA + (size_t)(t + 2) * kstep; const char* b2 = last ? nB : cB + (size_t)(t + 2) * kstep;
;             const char* a3 = a2 + kstep; const char* b3 = b2 + kstep;
;             if constexpr (Epi::SS_LDS) { if (last) {
;                 const char* sp = (const char*)E.ss + (size_t)cur.pm * (256 * 64) + (size_t)tid * 16;
;                 __builtin_amdgcn_global_load_lds((const unsigned*)sp, (LAS unsigned*)(lds + RS_OFF + ldsw), 16, 0, 0);
;                 __builtin_amdgcn_global_load_lds((const unsigned*)(sp + 8192), (LAS unsigned*)(lds + RS_OFF + 8192 + ldsw), 16, 0, 0); } }
;     ...
;             PG8_LDB(B0, 0, 0); PG8_LDB(B1, 0, 1); PG8_SCHED; PG8_LDA(At, 0, 0); PG8_STAGE(PG8_SA(1, 1), a1 + hstepA, voffA);
;             PG8_WAIT_V(8); PG8_WAIT_L(0); PG8_BAR; PG8_MMA(0, 0, At, B0); PG8_MMA(0, 1, At, B1); PG8_BAR; PG8_SCHED;
;             PG8_LDA(At, 0, 1); PG8_STAGE(PG8_SB(0, 0), b2, voffB); PG8_STAGE(PG8_SB(0, 1), b2 + hstepB, voffB); PG8_STAGE(PG8_SA(0, 0), a2, voffA);
;             PG8_WAIT_V(8); PG8_WAIT_L(0); PG8_BAR; PG8_MMA(1, 0, At, B0); PG8_MMA(1, 1, At, B1); PG8_BAR; PG8_SCHED;
.LBB0_2036:
	v_add_u32_e32 v144, s50, v213
	v_add_u32_e32 v160, s51, v213
	ds_read_b128 v[132:135], v144
	ds_read_b128 v[136:139], v144 offset:1024
	ds_read_b128 v[140:143], v144 offset:2048
	ds_read_b128 v[144:147], v144 offset:3072
	ds_read_b128 v[148:151], v160
	ds_read_b128 v[152:155], v160 offset:1024
	ds_read_b128 v[156:159], v160 offset:2048
	ds_read_b128 v[160:163], v160 offset:3072
	s_add_i32 s55, s55, 2
	s_add_u32 s34, s28, 0xfffc0080
	s_addc_u32 s35, s29, -1
	s_and_b64 s[30:31], s[30:31], exec
	s_cselect_b32 s35, s19, s35
	s_cselect_b32 s34, s21, s34
	s_cselect_b32 s31, s52, s54
	s_cselect_b32 s30, s53, s27
	v_lshl_add_u64 v[210:211], s[28:29], 0, v[196:197]
	s_add_i32 m0, s40, 0xc000
	ds_read_b128 v[164:167], v215
	ds_read_b128 v[168:171], v215 offset:1024
	ds_read_b128 v[172:175], v215 offset:2048
	ds_read_b128 v[176:179], v215 offset:3072
	ds_read_b128 v[180:183], v215 offset:4096
	ds_read_b128 v[202:205], v215 offset:5120
	ds_read_b128 v[206:209], v215 offset:6144
	ds_read_b128 v[218:221], v215 offset:7168
	global_load_lds_dwordx4 v[210:211], off
	v_lshl_add_u64 v[210:211], s[28:29], 0, v[194:195]
	s_add_i32 m0, s40, 0xe000
	s_nop 0
	global_load_lds_dwordx4 v[210:211], off
	s_waitcnt vmcnt(8)
	s_waitcnt lgkmcnt(0)
	s_barrier
	s_setprio 1
	v_mfma_f32_16x16x32_bf16 v[124:127], v[132:135], v[164:167], v[124:127]
	v_mfma_f32_16x16x32_bf16 v[120:123], v[140:143], v[164:167], v[120:123]
	v_mfma_f32_16x16x32_bf16 v[108:111], v[132:135], v[172:175], v[108:111]
	v_mfma_f32_16x16x32_bf16 v[104:107], v[140:143], v[172:175], v[104:107]
	v_mfma_f32_16x16x32_bf16 v[92:95], v[132:135], v[180:183], v[92:95]
	v_mfma_f32_16x16x32_bf16 v[88:91], v[140:143], v[180:183], v[88:91]
	v_mfma_f32_16x16x32_bf16 v[76:79], v[132:135], v[206:209], v[76:79]
	v_mfma_f32_16x16x32_bf16 v[72:75], v[140:143], v[206:209], v[72:75]
	v_mfma_f32_16x16x32_bf16 v[124:127], v[136:139], v[168:171], v[124:127]
	v_mfma_f32_16x16x32_bf16 v[120:123], v[144:147], v[168:171], v[120:123]
	v_mfma_f32_16x16x32_bf16 v[108:111], v[136:139], v[176:179], v[108:111]
	v_mfma_f32_16x16x32_bf16 v[104:107], v[144:147], v[176:179], v[104:107]
	v_mfma_f32_16x16x32_bf16 v[92:95], v[136:139], v[202:205], v[92:95]
	v_mfma_f32_16x16x32_bf16 v[88:91], v[144:147], v[202:205], v[88:91]
	v_mfma_f32_16x16x32_bf16 v[76:79], v[136:139], v[218:221], v[76:79]
	v_mfma_f32_16x16x32_bf16 v[72:75], v[144:147], v[218:221], v[72:75]
	v_mfma_f32_16x16x32_bf16 v[116:119], v[148:151], v[164:167], v[116:119]
	v_mfma_f32_16x16x32_bf16 v[112:115], v[156:159], v[164:167], v[112:115]
	v_mfma_f32_16x16x32_bf16 v[100:103], v[148:151], v[172:175], v[100:103]
	v_mfma_f32_16x16x32_bf16 v[96:99], v[156:159], v[172:175], v[96:99]
	v_mfma_f32_16x16x32_bf16 v[84:87], v[148:151], v[180:183], v[84:87]
	v_mfma_f32_16x16x32_bf16 v[80:83], v[156:159], v[180:183], v[80:83]
	v_mfma_f32_16x16x32_bf16 v[68:71], v[148:151], v[206:209], v[68:71]
	v_mfma_f32_16x16x32_bf16 v[64:67], v[156:159], v[206:209], v[64:67]
	v_mfma_f32_16x16x32_bf16 v[116:119], v[152:155], v[168:171], v[116:119]
	v_mfma_f32_16x16x32_bf16 v[112:115], v[160:163], v[168:171], v[112:115]
	v_mfma_f32_16x16x32_bf16 v[100:103], v[152:155], v[176:179], v[100:103]
	v_mfma_f32_16x16x32_bf16 v[96:99], v[160:163], v[176:179], v[96:99]
	v_mfma_f32_16x16x32_bf16 v[84:87], v[152:155], v[202:205], v[84:87]
	v_mfma_f32_16x16x32_bf16 v[80:83], v[160:163], v[202:205], v[80:83]
	v_mfma_f32_16x16x32_bf16 v[68:71], v[152:155], v[218:221], v[68:71]
	v_mfma_f32_16x16x32_bf16 v[64:67], v[160:163], v[218:221], v[64:67]
	s_setprio 0
	s_barrier
	s_add_i32 s56, s50, s39
	v_lshl_add_u64 v[210:211], s[30:31], 0, v[186:187]
	s_mov_b32 m0, s56
	ds_read_b128 v[164:167], v215 offset:16384
	ds_read_b128 v[168:171], v215 offset:17408
	ds_read_b128 v[172:175], v215 offset:18432
	ds_read_b128 v[176:179], v215 offset:19456
	ds_read_b128 v[180:183], v215 offset:20480
	ds_read_b128 v[202:205], v215 offset:21504
	ds_read_b128 v[206:209], v215 offset:22528
	ds_read_b128 v[218:221], v215 offset:23552
	global_load_lds_dwordx4 v[210:211], off
	s_add_i32 m0, s56, 0x2000
	s_add_u32 s56, s30, 0x40000
	v_lshl_add_u64 v[222:223], s[30:31], 0, v[190:191]
	s_addc_u32 s57, s31, 0
	s_add_i32 s58, s51, s39
	global_load_lds_dwordx4 v[222:223], off
	v_lshl_add_u64 v[224:225], s[56:57], 0, v[186:187]
	s_mov_b32 m0, s58
	v_lshl_add_u64 v[226:227], s[34:35], 0, v[188:189]
	global_load_lds_dwordx4 v[224:225], off
	v_lshl_add_u64 v[224:225], s[56:57], 0, v[190:191]
	s_add_i32 m0, s58, 0x2000
	s_nop 0
	global_load_lds_dwordx4 v[224:225], off
	v_lshl_add_u64 v[224:225], s[34:35], 0, v[184:185]
	s_mov_b32 m0, s40
	s_nop 0
	global_load_lds_dwordx4 v[224:225], off
	s_mov_b32 m0, s41
	s_nop 0
	global_load_lds_dwordx4 v[226:227], off
	s_waitcnt vmcnt(8)
	s_waitcnt lgkmcnt(0)
	s_barrier
; #define PG8_STAGE(bufoff, gbase, voff) do { _Pragma("unroll") for (int _i = 0; _i < 2; ++_i) \
;         __builtin_amdgcn_global_load_lds((const unsigned*)((const char*)(gbase) + (voff)[_i]), (LAS unsigned*)(lds + (bufoff) + ldsw + _i * 8192), 16, 0, 0); } while (0)
; #define PG8_LDA(dst, b, h) do { _Pragma("unroll") for (int m = 0; m < 4; ++m) _Pragma("unroll") for (int k = 0; k < 2; ++k) dst[m][k] = *(const LAS bf16x8*)(lds + PG8_SA(b, h) + aoff + m * 2048 + k * 1024); } while (0)
; #define PG8_LDB(dst, b, h) do { _Pragma("unroll") for (int n = 0; n < 2; ++n) _Pragma("unroll") for (int k = 0; k < 2; ++k) dst[n][k] = *(const LAS bf16x8*)(lds + PG8_SB(b, h) + boff + n * 2048 + k * 1024); } while (0)
; #define PG8_MMA(ai, bj, At, Bt) do { __builtin_amdgcn_s_setprio(1); _Pragma("unroll") for (int m = 0; m < 4; ++m) _Pragma("unroll") for (int n = 0; n < 2; ++n) _Pragma("unroll") for (int k = 0; k < 2; ++k) \
;         acc[ai][bj][m][n] = __builtin_amdgcn_mfma_f32_16x16x32_bf16(Bt[n][k], At[m][k], acc[ai][bj][m][n], 0, 0, 0); __builtin_amdgcn_s_setprio(0); } while (0)
; #define PG8_WAIT_V(n) asm volatile("s_waitcnt vmcnt(" #n ")" ::: "memory")
; #define PG8_WAIT_L(n) asm volatile("s_waitcnt lgkmcnt(" #n ")" ::: "memory")
; #define PG8_BAR __builtin_amdgcn_s_barrier()
; #define PG8_SCHED __builtin_amdgcn_sched_barrier(0)
; template <class Epi>
; __device__ __forceinline__ void gemm_phase(LAS unsigned char* lds, const int tid, const Gemm g, const StaticOrder& S, const Epi& E) {
;     ...
;             PG8_WAIT_V(8); PG8_WAIT_L(0); PG8_BAR; PG8_MMA(1, 0, At, B0); PG8_MMA(1, 1, At, B1); PG8_BAR; PG8_SCHED;
;             PG8_LDB(B0, 1, 0); PG8_LDB(B1, 1, 1); PG8_SCHED; PG8_LDA(At, 1, 0); PG8_STAGE(PG8_SA(0, 1), a2 + hstepA, voffA);
;             PG8_WAIT_V(8); PG8_WAIT_L(0); PG8_BAR; PG8_MMA(0, 0, At, B0); PG8_MMA(0, 1, At, B1); PG8_BAR; PG8_SCHED;
	s_setprio 1
	v_mfma_f32_16x16x32_bf16 v[60:63], v[132:135], v[164:167], v[60:63]
	v_mfma_f32_16x16x32_bf16 v[56:59], v[140:143], v[164:167], v[56:59]
	v_mfma_f32_16x16x32_bf16 v[44:47], v[132:135], v[172:175], v[44:47]
	v_mfma_f32_16x16x32_bf16 v[40:43], v[140:143], v[172:175], v[40:43]
	v_mfma_f32_16x16x32_bf16 v[28:31], v[132:135], v[180:183], v[28:31]
	v_mfma_f32_16x16x32_bf16 v[24:27], v[140:143], v[180:183], v[24:27]
	v_mfma_f32_16x16x32_bf16 v[12:15], v[132:135], v[206:209], v[12:15]
	v_mfma_f32_16x16x32_bf16 v[8:11], v[140:143], v[206:209], v[8:11]
	v_mfma_f32_16x16x32_bf16 v[60:63], v[136:139], v[168:171], v[60:63]
	v_mfma_f32_16x16x32_bf16 v[56:59], v[144:147], v[168:171], v[56:59]
	v_mfma_f32_16x16x32_bf16 v[44:47], v[136:139], v[176:179], v[44:47]
	v_mfma_f32_16x16x32_bf16 v[40:43], v[144:147], v[176:179], v[40:43]
	v_mfma_f32_16x16x32_bf16 v[28:31], v[136:139], v[202:205], v[28:31]
	v_mfma_f32_16x16x32_bf16 v[24:27], v[144:147], v[202:205], v[24:27]
	v_mfma_f32_16x16x32_bf16 v[12:15], v[136:139], v[218:221], v[12:15]
	v_mfma_f32_16x16x32_bf16 v[8:11], v[144:147], v[218:221], v[8:11]
	v_mfma_f32_16x16x32_bf16 v[52:55], v[148:151], v[164:167], v[52:55]
	v_mfma_f32_16x16x32_bf16 v[48:51], v[156:159], v[164:167], v[48:51]
	v_mfma_f32_16x16x32_bf16 v[36:39], v[148:151], v[172:175], v[36:39]
	v_mfma_f32_16x16x32_bf16 v[32:35], v[156:159], v[172:175], v[32:35]
	v_mfma_f32_16x16x32_bf16 v[20:23], v[148:151], v[180:183], v[20:23]
	v_mfma_f32_16x16x32_bf16 v[16:19], v[156:159], v[180:183], v[16:19]
	v_mfma_f32_16x16x32_bf16 v[4:7], v[148:151], v[206:209], v[4:7]
	v_mfma_f32_16x16x32_bf16 v[0:3], v[156:159], v[206:209], v[0:3]
	v_mfma_f32_16x16x32_bf16 v[52:55], v[152:155], v[168:171], v[52:55]
	v_mfma_f32_16x16x32_bf16 v[48:51], v[160:163], v[168:171], v[48:51]
	v_mfma_f32_16x16x32_bf16 v[36:39], v[152:155], v[176:179], v[36:39]
	v_mfma_f32_16x16x32_bf16 v[32:35], v[160:163], v[176:179], v[32:35]
	v_mfma_f32_16x16x32_bf16 v[20:23], v[152:155], v[202:205], v[20:23]
	v_mfma_f32_16x16x32_bf16 v[16:19], v[160:163], v[202:205], v[16:19]
	v_mfma_f32_16x16x32_bf16 v[4:7], v[152:155], v[218:221], v[4:7]
	v_mfma_f32_16x16x32_bf16 v[0:3], v[160:163], v[218:221], v[0:3]
	s_setprio 0
	s_barrier
	s_add_i32 s56, 0, 0x18000
	s_add_i32 s57, 0, 0x1c000
	v_add_u32_e32 v144, s56, v213
	v_add_u32_e32 v160, s57, v213
	ds_read_b128 v[132:135], v144
	ds_read_b128 v[136:139], v144 offset:1024
	ds_read_b128 v[140:143], v144 offset:2048
	ds_read_b128 v[144:147], v144 offset:3072
	ds_read_b128 v[148:151], v160
	ds_read_b128 v[152:155], v160 offset:1024
	ds_read_b128 v[156:159], v160 offset:2048
	ds_read_b128 v[160:163], v160 offset:3072
	s_add_u32 s34, s34, 0x40000
	s_addc_u32 s35, s35, 0
	s_mov_b32 m0, s42
	v_lshl_add_u64 v[228:229], s[34:35], 0, v[184:185]
	ds_read_b128 v[164:167], v215 offset:32768
	ds_read_b128 v[168:171], v215 offset:33792
	ds_read_b128 v[172:175], v215 offset:34816
	ds_read_b128 v[176:179], v215 offset:35840
	ds_read_b128 v[180:183], v215 offset:36864
	ds_read_b128 v[202:205], v215 offset:37888
	ds_read_b128 v[206:209], v215 offset:38912
	ds_read_b128 v[218:221], v215 offset:39936
	global_load_lds_dwordx4 v[228:229], off
	v_lshl_add_u64 v[228:229], s[34:35], 0, v[188:189]
	s_mov_b32 m0, s43
	s_nop 0
	global_load_lds_dwordx4 v[228:229], off
	s_waitcnt vmcnt(8)
	s_waitcnt lgkmcnt(0)
	s_barrier
	s_setprio 1
	v_mfma_f32_16x16x32_bf16 v[124:127], v[132:135], v[164:167], v[124:127]
	v_mfma_f32_16x16x32_bf16 v[120:123], v[140:143], v[164:167], v[120:123]
	v_mfma_f32_16x16x32_bf16 v[108:111], v[132:135], v[172:175], v[108:111]
	v_mfma_f32_16x16x32_bf16 v[104:107], v[140:143], v[172:175], v[104:107]
	v_mfma_f32_16x16x32_bf16 v[92:95], v[132:135], v[180:183], v[92:95]
	v_mfma_f32_16x16x32_bf16 v[88:91], v[140:143], v[180:183], v[88:91]
	v_mfma_f32_16x16x32_bf16 v[76:79], v[132:135], v[206:209], v[76:79]
	v_mfma_f32_16x16x32_bf16 v[72:75], v[140:143], v[206:209], v[72:75]
	v_mfma_f32_16x16x32_bf16 v[124:127], v[136:139], v[168:171], v[124:127]
	v_mfma_f32_16x16x32_bf16 v[120:123], v[144:147], v[168:171], v[120:123]
	v_mfma_f32_16x16x32_bf16 v[108:111], v[136:139], v[176:179], v[108:111]
	v_mfma_f32_16x16x32_bf16 v[104:107], v[144:147], v[176:179], v[104:107]
	v_mfma_f32_16x16x32_bf16 v[92:95], v[136:139], v[202:205], v[92:95]
	v_mfma_f32_16x16x32_bf16 v[88:91], v[144:147], v[202:205], v[88:91]
	v_mfma_f32_16x16x32_bf16 v[76:79], v[136:139], v[218:221], v[76:79]
	v_mfma_f32_16x16x32_bf16 v[72:75], v[144:147], v[218:221], v[72:75]
	v_mfma_f32_16x16x32_bf16 v[116:119], v[148:151], v[164:167], v[116:119]
	v_mfma_f32_16x16x32_bf16 v[112:115], v[156:159], v[164:167], v[112:115]
	v_mfma_f32_16x16x32_bf16 v[100:103], v[148:151], v[172:175], v[100:103]
	v_mfma_f32_16x16x32_bf16 v[96:99], v[156:159], v[172:175], v[96:99]
	v_mfma_f32_16x16x32_bf16 v[84:87], v[148:151], v[180:183], v[84:87]
	v_mfma_f32_16x16x32_bf16 v[80:83], v[156:159], v[180:183], v[80:83]
	v_mfma_f32_16x16x32_bf16 v[68:71], v[148:151], v[206:209], v[68:71]
	v_mfma_f32_16x16x32_bf16 v[64:67], v[156:159], v[206:209], v[64:67]
	v_mfma_f32_16x16x32_bf16 v[116:119], v[152:155], v[168:171], v[116:119]
	v_mfma_f32_16x16x32_bf16 v[112:115], v[160:163], v[168:171], v[112:115]
	v_mfma_f32_16x16x32_bf16 v[100:103], v[152:155], v[176:179], v[100:103]
	v_mfma_f32_16x16x32_bf16 v[96:99], v[160:163], v[176:179], v[96:99]
	v_mfma_f32_16x16x32_bf16 v[84:87], v[152:155], v[202:205], v[84:87]
	v_mfma_f32_16x16x32_bf16 v[80:83], v[160:163], v[202:205], v[80:83]
	v_mfma_f32_16x16x32_bf16 v[68:71], v[152:155], v[218:221], v[68:71]
	v_mfma_f32_16x16x32_bf16 v[64:67], v[160:163], v[218:221], v[64:67]
	s_setprio 0
	s_barrier
; #define PG8_STAGE(bufoff, gbase, voff) do { _Pragma("unroll") for (int _i = 0; _i < 2; ++_i) \
;         __builtin_amdgcn_global_load_lds((const unsigned*)((const char*)(gbase) + (voff)[_i]), (LAS unsigned*)(lds + (bufoff) + ldsw + _i * 8192), 16, 0, 0); } while (0)
; #define PG8_LDA(dst, b, h) do { _Pragma("unroll") for (int m = 0; m < 4; ++m) _Pragma("unroll") for (int k = 0; k < 2; ++k) dst[m][k] = *(const LAS bf16x8*)(lds + PG8_SA(b, h) + aoff + m * 2048 + k * 1024); } while (0)
; #define PG8_MMA(ai, bj, At, Bt) do { __builtin_amdgcn_s_setprio(1); _Pragma("unroll") for (int m = 0; m < 4; ++m) _Pragma("unroll") for (int n = 0; n < 2; ++n) _Pragma("unroll") for (int k = 0; k < 2; ++k) \
;         acc[ai][bj][m][n] = __builtin_amdgcn_mfma_f32_16x16x32_bf16(Bt[n][k], At[m][k], acc[ai][bj][m][n], 0, 0, 0); __builtin_amdgcn_s_setprio(0); } while (0)
; #define PG8_WAIT_V(n) asm volatile("s_waitcnt vmcnt(" #n ")" ::: "memory")
; #define PG8_WAIT_L(n) asm volatile("s_waitcnt lgkmcnt(" #n ")" ::: "memory")
; #define PG8_BAR __builtin_amdgcn_s_barrier()
; #define PG8_SCHED __builtin_amdgcn_sched_barrier(0)
; template <class Epi>
; __device__ __forceinline__ void gemm_phase(LAS unsigned char* lds, const int tid, const Gemm g, const StaticOrder& S, const Epi& E) {
;     ...
;             PG8_LDA(At, 1, 1); PG8_STAGE(PG8_SB(1, 0), b3, voffB); PG8_STAGE(PG8_SB(1, 1), b3 + hstepB, voffB); PG8_STAGE(PG8_SA(1, 0), a3, voffA);
;             PG8_WAIT_V(8); PG8_WAIT_L(0); PG8_BAR; PG8_MMA(1, 0, At, B0); PG8_MMA(1, 1, At, B1); PG8_BAR; PG8_SCHED;
	s_add_i32 s34, s56, s39
	v_lshl_add_u64 v[210:211], v[210:211], 0, s[12:13]
	s_mov_b32 m0, s34
	ds_read_b128 v[164:167], v215 offset:49152
	ds_read_b128 v[168:171], v215 offset:50176
	ds_read_b128 v[172:175], v215 offset:51200
	ds_read_b128 v[176:179], v215 offset:52224
	ds_read_b128 v[180:183], v215 offset:53248
	ds_read_b128 v[202:205], v215 offset:54272
	ds_read_b128 v[206:209], v215 offset:55296
	ds_read_b128 v[218:221], v215 offset:56320
	global_load_lds_dwordx4 v[210:211], off
	s_add_i32 m0, s34, 0x2000
	s_add_u32 s30, s30, 0x40080
	v_lshl_add_u64 v[210:211], v[222:223], 0, s[12:13]
	s_addc_u32 s31, s31, 0
	s_add_i32 s34, s57, s39
	global_load_lds_dwordx4 v[210:211], off
	v_lshl_add_u64 v[210:211], s[30:31], 0, v[186:187]
	s_mov_b32 m0, s34
	s_nop 0
	global_load_lds_dwordx4 v[210:211], off
	v_lshl_add_u64 v[210:211], s[30:31], 0, v[190:191]
	s_add_i32 m0, s34, 0x2000
	s_nop 0
	global_load_lds_dwordx4 v[210:211], off
	v_lshl_add_u64 v[210:211], v[224:225], 0, s[12:13]
	s_mov_b32 m0, s46
	s_nop 0
	global_load_lds_dwordx4 v[210:211], off
	v_lshl_add_u64 v[210:211], v[226:227], 0, s[12:13]
	s_mov_b32 m0, s47
	s_nop 0
	global_load_lds_dwordx4 v[210:211], off
	s_waitcnt vmcnt(8)
	s_waitcnt lgkmcnt(0)
	s_barrier
	s_setprio 1
	v_mfma_f32_16x16x32_bf16 v[60:63], v[132:135], v[164:167], v[60:63]
	v_mfma_f32_16x16x32_bf16 v[56:59], v[140:143], v[164:167], v[56:59]
	v_mfma_f32_16x16x32_bf16 v[44:47], v[132:135], v[172:175], v[44:47]
	v_mfma_f32_16x16x32_bf16 v[40:43], v[140:143], v[172:175], v[40:43]
	v_mfma_f32_16x16x32_bf16 v[28:31], v[132:135], v[180:183], v[28:31]
	v_mfma_f32_16x16x32_bf16 v[24:27], v[140:143], v[180:183], v[24:27]
	v_mfma_f32_16x16x32_bf16 v[12:15], v[132:135], v[206:209], v[12:15]
	v_mfma_f32_16x16x32_bf16 v[8:11], v[140:143], v[206:209], v[8:11]
	v_mfma_f32_16x16x32_bf16 v[60:63], v[136:139], v[168:171], v[60:63]
	v_mfma_f32_16x16x32_bf16 v[56:59], v[144:147], v[168:171], v[56:59]
	v_mfma_f32_16x16x32_bf16 v[44:47], v[136:139], v[176:179], v[44:47]
	v_mfma_f32_16x16x32_bf16 v[40:43], v[144:147], v[176:179], v[40:43]
	v_mfma_f32_16x16x32_bf16 v[28:31], v[136:139], v[202:205], v[28:31]
	v_mfma_f32_16x16x32_bf16 v[24:27], v[144:147], v[202:205], v[24:27]
	v_mfma_f32_16x16x32_bf16 v[12:15], v[136:139], v[218:221], v[12:15]
	v_mfma_f32_16x16x32_bf16 v[8:11], v[144:147], v[218:221], v[8:11]
	v_mfma_f32_16x16x32_bf16 v[52:55], v[148:151], v[164:167], v[52:55]
	v_mfma_f32_16x16x32_bf16 v[48:51], v[156:159], v[164:167], v[48:51]
	v_mfma_f32_16x16x32_bf16 v[36:39], v[148:151], v[172:175], v[36:39]
	v_mfma_f32_16x16x32_bf16 v[32:35], v[156:159], v[172:175], v[32:35]
	v_mfma_f32_16x16x32_bf16 v[20:23], v[148:151], v[180:183], v[20:23]
	v_mfma_f32_16x16x32_bf16 v[16:19], v[156:159], v[180:183], v[16:19]
	v_mfma_f32_16x16x32_bf16 v[4:7], v[148:151], v[206:209], v[4:7]
	v_mfma_f32_16x16x32_bf16 v[0:3], v[156:159], v[206:209], v[0:3]
	v_mfma_f32_16x16x32_bf16 v[52:55], v[152:155], v[168:171], v[52:55]
	v_mfma_f32_16x16x32_bf16 v[48:51], v[160:163], v[168:171], v[48:51]
	v_mfma_f32_16x16x32_bf16 v[36:39], v[152:155], v[176:179], v[36:39]
	v_mfma_f32_16x16x32_bf16 v[32:35], v[160:163], v[176:179], v[32:35]
	v_mfma_f32_16x16x32_bf16 v[20:23], v[152:155], v[202:205], v[20:23]
	v_mfma_f32_16x16x32_bf16 v[16:19], v[160:163], v[202:205], v[16:19]
	v_mfma_f32_16x16x32_bf16 v[4:7], v[152:155], v[218:221], v[4:7]
	v_mfma_f32_16x16x32_bf16 v[0:3], v[160:163], v[218:221], v[0:3]
	s_setprio 0
	s_barrier
	s_add_u32 s27, s27, 0x100
	s_addc_u32 s54, s54, 0
	s_add_u32 s28, s28, 0x100
	s_addc_u32 s29, s29, 0
	s_cmp_ge_i32 s55, s45
	s_cbranch_scc1 .LBB0_2039
